# norm phase prologues: all 16 modulation-table loads and the first row's loads issued together with one counted wait (were four dependent round trips)
# baseline (speedup 1.0000x reference)
; __device__ __forceinline__ float ssq8(const f32x4& a, const f32x4& b) { return ((a[0] * a[0] + a[1] * a[1]) + (a[2] * a[2] + a[3] * a[3])) + ((b[0] * b[0] + b[1] * b[1]) + (b[2] * b[2] + b[3] * b[3])); }
; template <int XF32> __device__ __forceinline__ void norm_mod_phase(const void* x, const float* modl, int ch_shift, int ch_scale, bf16* H, int gw, int NGW, int lane) {
;     ...
;         const int r0 = blk * 8, b = r0 >> 12;
;         const f32x4* shp = (const f32x4*)(modl + (size_t)b * MODW + ch_shift * DM); const f32x4* scp = (const f32x4*)(modl + (size_t)b * MODW + ch_scale * DM);
;         f32x4 sh[4][2], sc[4][2];
; #pragma unroll
;         for (int j = 0; j < 4; ++j)
; #pragma unroll
;             for (int q = 0; q < 2; ++q) { sh[j][q] = shp[2 * (lane + 64 * j) + q]; sc[j][q] = scp[2 * (lane + 64 * j) + q] + 1.f; }
;         for (int rr = 0; rr < 8; ++rr) {
;             const unsigned char* xr = (const unsigned char*)x + (size_t)(r0 + rr) * rowb; f32x4 v[4][2]; float s = 0.f;
; #pragma unroll
;             for (int j = 0; j < 4; ++j) ld_row8<XF32>(xr, lane, j, v[j][0], v[j][1]);
; #pragma unroll
;             for (int j = 0; j < 4; ++j) s += ssq8(v[j][0], v[j][1]);
;             const float rstd = 1.f / sqrtf(wave_sum(s) * (1.f / DM) + EPS);
.LBB0_161:
	s_ashr_i32 s0, s3, 9
	s_mul_hi_i32 s1, s0, 0x12000
	s_mul_i32 s0, s0, 0x12000
	s_add_u32 s64, s24, s0
	s_addc_u32 s65, s26, s1
	s_add_u32 s4, s64, 0x2000
	s_addc_u32 s5, s65, 0
	v_lshl_add_u64 v[16:17], s[64:65], 0, v[38:39]
	v_lshl_add_u64 v[4:5], s[4:5], 0, v[38:39]
	global_load_dwordx4 v[8:11], v[16:17], off offset:16
	global_load_dwordx4 v[12:15], v[16:17], off
	global_load_dwordx4 v[178:181], v[4:5], off offset:16
	s_nop 0
	global_load_dwordx4 v[182:185], v[4:5], off
	v_lshl_add_u64 v[20:21], v[32:33], 4, s[4:5]
	v_lshl_add_u64 v[28:29], s[4:5], 0, v[40:41]
	v_lshl_add_u64 v[68:69], s[4:5], 0, v[42:43]
	s_add_i32 s0, s8, -7
	s_ashr_i32 s1, s0, 31
	s_ashr_i32 s9, s8, 31
	s_add_i32 s3, s3, s58
	global_load_dwordx4 v[0:3], v[16:17], off offset:2064
	global_load_dwordx4 v[4:7], v[16:17], off offset:2048
	s_nop 0
	global_load_dwordx4 v[186:189], v[20:21], off offset:16
	s_nop 0
	global_load_dwordx4 v[190:193], v[20:21], off
	v_lshl_add_u64 v[20:21], s[64:65], 0, v[40:41]
	global_load_dwordx4 v[16:19], v[20:21], off offset:16
	s_nop 0
	global_load_dwordx4 v[20:23], v[20:21], off
	s_nop 0
	global_load_dwordx4 v[194:197], v[28:29], off offset:16
	s_nop 0
	global_load_dwordx4 v[198:201], v[28:29], off
	v_lshl_add_u64 v[28:29], s[64:65], 0, v[42:43]
	global_load_dwordx4 v[24:27], v[28:29], off offset:16
	s_nop 0
	global_load_dwordx4 v[28:31], v[28:29], off
	s_nop 0
	global_load_dwordx4 v[202:205], v[68:69], off offset:16
	s_nop 0
	global_load_dwordx4 v[206:209], v[68:69], off
	s_lshl_b64 s[64:65], s[0:1], 12
	v_lshl_add_u64 v[88:89], v[34:35], 0, s[64:65]
	global_load_dwordx4 v[76:79], v[88:89], off
	global_load_dwordx4 v[80:83], v[88:89], off offset:1024
	global_load_dwordx4 v[84:87], v[88:89], off offset:2048
	s_nop 0
	global_load_dwordx4 v[88:91], v[88:89], off offset:3072
	s_waitcnt vmcnt(4)
	v_pk_add_f32 v[52:53], v[180:181], 1.0 op_sel_hi:[1,0]
	v_pk_add_f32 v[56:57], v[184:185], 1.0 op_sel_hi:[1,0]
	v_pk_add_f32 v[58:59], v[182:183], 1.0 op_sel_hi:[1,0]
	v_pk_add_f32 v[54:55], v[178:179], 1.0 op_sel_hi:[1,0]
	v_pk_add_f32 v[44:45], v[188:189], 1.0 op_sel_hi:[1,0]
	v_pk_add_f32 v[50:51], v[190:191], 1.0 op_sel_hi:[1,0]
	v_pk_add_f32 v[48:49], v[192:193], 1.0 op_sel_hi:[1,0]
	v_pk_add_f32 v[46:47], v[186:187], 1.0 op_sel_hi:[1,0]
	v_pk_add_f32 v[60:61], v[196:197], 1.0 op_sel_hi:[1,0]
	v_pk_add_f32 v[66:67], v[198:199], 1.0 op_sel_hi:[1,0]
	v_pk_add_f32 v[64:65], v[200:201], 1.0 op_sel_hi:[1,0]
	v_pk_add_f32 v[62:63], v[194:195], 1.0 op_sel_hi:[1,0]
	v_pk_add_f32 v[72:73], v[208:209], 1.0 op_sel_hi:[1,0]
	v_pk_add_f32 v[74:75], v[206:207], 1.0 op_sel_hi:[1,0]
	v_pk_add_f32 v[68:69], v[204:205], 1.0 op_sel_hi:[1,0]
	v_pk_add_f32 v[70:71], v[202:203], 1.0 op_sel_hi:[1,0]
	s_waitcnt vmcnt(3)
	v_lshlrev_b32_e32 v97, 16, v77
	v_lshlrev_b32_e32 v96, 16, v76
	v_and_b32_e32 v77, 0xffff0000, v77
	v_and_b32_e32 v76, 0xffff0000, v76
	v_lshlrev_b32_e32 v101, 16, v79
	v_lshlrev_b32_e32 v100, 16, v78
	v_and_b32_e32 v79, 0xffff0000, v79
	v_and_b32_e32 v78, 0xffff0000, v78
	v_pk_mul_f32 v[98:99], v[76:77], v[76:77]
	v_pk_mul_f32 v[102:103], v[78:79], v[78:79]
	s_waitcnt vmcnt(0)
	v_lshlrev_b32_e32 v92, 16, v88
	v_and_b32_e32 v93, 0xffff0000, v88
	v_pk_fma_f32 v[98:99], v[96:97], v[96:97], v[98:99]
	v_pk_fma_f32 v[102:103], v[100:101], v[100:101], v[102:103]
	v_lshlrev_b32_e32 v105, 16, v81
	v_lshlrev_b32_e32 v104, 16, v80
	v_and_b32_e32 v81, 0xffff0000, v81
	v_and_b32_e32 v80, 0xffff0000, v80
	v_lshlrev_b32_e32 v109, 16, v83
	v_lshlrev_b32_e32 v108, 16, v82
	v_and_b32_e32 v83, 0xffff0000, v83
	v_and_b32_e32 v82, 0xffff0000, v82
	v_pk_mul_f32 v[106:107], v[80:81], v[80:81]
	v_pk_mul_f32 v[110:111], v[82:83], v[82:83]
	v_mul_f32_e32 v116, v92, v92
	v_mul_f32_e32 v117, v93, v93
	v_pk_add_f32 v[98:99], v[98:99], v[98:99] op_sel:[0,1] op_sel_hi:[1,0]
	v_pk_add_f32 v[102:103], v[102:103], v[102:103] op_sel:[0,1] op_sel_hi:[1,0]
	v_lshlrev_b32_e32 v88, 16, v89
	v_and_b32_e32 v89, 0xffff0000, v89
	v_pk_fma_f32 v[106:107], v[104:105], v[104:105], v[106:107]
	v_pk_fma_f32 v[110:111], v[108:109], v[108:109], v[110:111]
	v_mov_b32_e32 v99, v116
	v_mov_b32_e32 v103, v117
	v_mul_f32_e32 v118, v88, v88
	v_mul_f32_e32 v119, v89, v89
	v_pk_add_f32 v[98:99], v[98:99], v[102:103]
	v_pk_add_f32 v[102:103], v[106:107], v[106:107] op_sel:[0,1] op_sel_hi:[1,0]
	v_pk_add_f32 v[106:107], v[110:111], v[110:111] op_sel:[0,1] op_sel_hi:[1,0]
	v_mov_b32_e32 v103, v118
	v_mov_b32_e32 v107, v119
	v_lshlrev_b32_e32 v112, 16, v84
	v_and_b32_e32 v113, 0xffff0000, v84
	v_lshlrev_b32_e32 v84, 16, v85
	v_and_b32_e32 v85, 0xffff0000, v85
	v_pk_add_f32 v[102:103], v[102:103], v[106:107]
	v_lshlrev_b32_e32 v94, 16, v90
	v_and_b32_e32 v95, 0xffff0000, v90
	v_pk_add_f32 v[98:99], v[98:99], v[102:103]
	v_mul_f32_e32 v102, v113, v113
	v_mul_f32_e32 v106, v85, v85
	v_mul_f32_e32 v120, v94, v94
	v_mul_f32_e32 v121, v95, v95
	v_pk_fma_f32 v[102:103], v[112:113], v[112:113], v[102:103] op_sel_hi:[1,1,0]
	v_pk_fma_f32 v[106:107], v[84:85], v[84:85], v[106:107] op_sel_hi:[1,1,0]
	v_lshlrev_b32_e32 v114, 16, v86
	v_and_b32_e32 v115, 0xffff0000, v86
	v_lshlrev_b32_e32 v86, 16, v87
	v_and_b32_e32 v87, 0xffff0000, v87
	v_mov_b32_e32 v103, v120
	v_mov_b32_e32 v107, v121
	v_lshlrev_b32_e32 v90, 16, v91
	v_and_b32_e32 v91, 0xffff0000, v91
	v_pk_add_f32 v[102:103], v[102:103], v[106:107]
	v_mul_f32_e32 v106, v115, v115
	v_mul_f32_e32 v110, v87, v87
	v_mul_f32_e32 v122, v90, v90
	v_mul_f32_e32 v123, v91, v91
	v_pk_fma_f32 v[106:107], v[114:115], v[114:115], v[106:107] op_sel_hi:[1,1,0]
	v_pk_fma_f32 v[110:111], v[86:87], v[86:87], v[110:111] op_sel_hi:[1,1,0]
	v_mov_b32_e32 v107, v122
	v_mov_b32_e32 v111, v123
	v_pk_add_f32 v[106:107], v[106:107], v[110:111]
	s_nop 0
	v_pk_add_f32 v[102:103], v[102:103], v[106:107]
	s_nop 0
	v_pk_add_f32 v[98:99], v[98:99], v[102:103]
	s_nop 0
	v_add_f32_e32 v98, v98, v99
	v_mbcnt_lo_u32_b32 v99, -1, 0
	v_mbcnt_hi_u32_b32 v99, -1, v99
	s_nop 0
	v_lshlrev_b32_e32 v99, 2, v99
	v_xor_b32_e32 v99, 4, v99
	ds_bpermute_b32 v99, v99, v98
	s_waitcnt lgkmcnt(0)
; __device__ __forceinline__ v4u pk8(f32x4 a, f32x4 b) { v4u w; w.x = pk2(a[0], a[1]); w.y = pk2(a[2], a[3]); w.z = pk2(b[0], b[1]); w.w = pk2(b[2], b[3]); return w; }
; __device__ __forceinline__ float ssq8(const f32x4& a, const f32x4& b) { return ((a[0] * a[0] + a[1] * a[1]) + (a[2] * a[2] + a[3] * a[3])) + ((b[0] * b[0] + b[1] * b[1]) + (b[2] * b[2] + b[3] * b[3])); }
; __device__ __forceinline__ float shfl_xor_f(float v, int o) {
;     int l; asm volatile("v_mbcnt_lo_u32_b32 %0, -1, 0\n\tv_mbcnt_hi_u32_b32 %0, -1, %0" : "=v"(l));
;     return __builtin_bit_cast(float, __builtin_amdgcn_ds_bpermute((l ^ o) << 2, __builtin_bit_cast(int, v)));
; }
; __device__ __forceinline__ float wave_sum(float v) {
; #pragma unroll
;     for (int o = 1; o < 64; o <<= 1) v += shfl_xor_f(v, o);
;     return v;
; template <int XF32> __device__ __forceinline__ void norm_mod_phase(const void* x, const float* modl, int ch_shift, int ch_scale, bf16* H, int gw, int NGW, int lane) {
;     ...
;         for (int rr = 0; rr < 8; ++rr) {
;             const unsigned char* xr = (const unsigned char*)x + (size_t)(r0 + rr) * rowb; f32x4 v[4][2]; float s = 0.f;
; #pragma unroll
;             for (int j = 0; j < 4; ++j) ld_row8<XF32>(xr, lane, j, v[j][0], v[j][1]);
; #pragma unroll
;             for (int j = 0; j < 4; ++j) s += ssq8(v[j][0], v[j][1]);
;             const float rstd = 1.f / sqrtf(wave_sum(s) * (1.f / DM) + EPS);
;             v4u* o = (v4u*)(H + (size_t)(r0 + rr) * DM);
; #pragma unroll
;             for (int j = 0; j < 4; ++j) o[lane + 64 * j] = pk8(v[j][0] * rstd * sc[j][0] + sh[j][0], v[j][1] * rstd * sc[j][1] + sh[j][1]);
	v_add_f32_e32 v98, v98, v99
	v_mbcnt_lo_u32_b32 v99, -1, 0
	v_mbcnt_hi_u32_b32 v99, -1, v99
	s_nop 0
	v_lshlrev_b32_e32 v99, 2, v99
	v_xor_b32_e32 v99, 8, v99
	ds_bpermute_b32 v99, v99, v98
	s_waitcnt lgkmcnt(0)
	v_add_f32_e32 v98, v98, v99
	v_mbcnt_lo_u32_b32 v99, -1, 0
	v_mbcnt_hi_u32_b32 v99, -1, v99
	s_nop 0
	v_lshlrev_b32_e32 v99, 2, v99
	v_xor_b32_e32 v99, 16, v99
	ds_bpermute_b32 v99, v99, v98
	s_waitcnt lgkmcnt(0)
	v_add_f32_e32 v98, v98, v99
	v_mbcnt_lo_u32_b32 v99, -1, 0
	v_mbcnt_hi_u32_b32 v99, -1, v99
	s_nop 0
	v_lshlrev_b32_e32 v99, 2, v99
	v_xor_b32_e32 v99, 32, v99
	ds_bpermute_b32 v99, v99, v98
	s_waitcnt lgkmcnt(0)
	v_add_f32_e32 v98, v98, v99
	v_mbcnt_lo_u32_b32 v99, -1, 0
	v_mbcnt_hi_u32_b32 v99, -1, v99
	s_nop 0
	v_lshlrev_b32_e32 v99, 2, v99
	v_xor_b32_e32 v99, 64, v99
	ds_bpermute_b32 v99, v99, v98
	s_waitcnt lgkmcnt(0)
	v_add_f32_e32 v98, v98, v99
	v_mbcnt_lo_u32_b32 v99, -1, 0
	v_mbcnt_hi_u32_b32 v99, -1, v99
	s_nop 0
	v_lshlrev_b32_e32 v99, 2, v99
	v_xor_b32_e32 v99, 0x80, v99
	ds_bpermute_b32 v99, v99, v98
	s_waitcnt lgkmcnt(0)
	v_add_f32_e32 v98, v98, v99
	v_fmamk_f32 v98, v98, 0x3a000000, v224
	v_cmp_gt_f32_e32 vcc, s41, v98
	v_mul_f32_e32 v99, 0x4f800000, v98
	s_nop 0
	v_cndmask_b32_e32 v98, v98, v99, vcc
	v_sqrt_f32_e32 v99, v98
	s_nop 0
	v_add_u32_e32 v102, -1, v99
	v_fma_f32 v103, -v102, v99, v98
	v_cmp_ge_f32_e64 s[4:5], 0, v103
	v_add_u32_e32 v103, 1, v99
	s_nop 0
	v_cndmask_b32_e64 v102, v99, v102, s[4:5]
	v_fma_f32 v99, -v103, v99, v98
	v_cmp_lt_f32_e64 s[4:5], 0, v99
	s_nop 1
	v_cndmask_b32_e64 v99, v102, v103, s[4:5]
	v_mul_f32_e32 v102, 0x37800000, v99
	v_cndmask_b32_e32 v99, v99, v102, vcc
	v_cmp_class_f32_e32 vcc, v98, v225
	s_nop 1
	v_cndmask_b32_e32 v98, v99, v98, vcc
	v_div_scale_f32 v99, s[0:1], v98, v98, 1.0
	v_rcp_f32_e32 v102, v99
	s_add_i32 s0, s8, -6
	s_ashr_i32 s1, s0, 31
	v_fma_f32 v103, -v99, v102, 1.0
	v_fmac_f32_e32 v102, v103, v102
	v_div_scale_f32 v103, vcc, 1.0, v98, 1.0
	v_mul_f32_e32 v106, v103, v102
	v_fma_f32 v107, -v99, v106, v103
	v_fmac_f32_e32 v106, v107, v102
	v_fma_f32 v99, -v99, v106, v103
	v_div_fmas_f32 v99, v99, v102, v106
	v_div_fixup_f32 v98, v99, v98, 1.0
	v_mov_b32_e32 v102, v96
	v_mov_b32_e32 v103, v76
	v_mov_b32_e32 v76, v97
	v_pk_mul_f32 v[102:103], v[98:99], v[102:103] op_sel_hi:[0,1]
	v_pk_mul_f32 v[76:77], v[98:99], v[76:77] op_sel_hi:[0,1]
	v_pk_fma_f32 v[96:97], v[56:57], v[76:77], v[14:15]
	v_pk_fma_f32 v[76:77], v[58:59], v[102:103], v[12:13]
	v_mov_b32_e32 v102, v100
	v_mov_b32_e32 v103, v78
	v_mov_b32_e32 v78, v101
	v_pk_mul_f32 v[102:103], v[98:99], v[102:103] op_sel_hi:[0,1]
	v_pk_mul_f32 v[78:79], v[98:99], v[78:79] op_sel_hi:[0,1]
	v_pk_fma_f32 v[100:101], v[52:53], v[78:79], v[10:11]
	v_pk_fma_f32 v[78:79], v[54:55], v[102:103], v[8:9]
	v_cvt_pk_bf16_f32 v76, v76, v77
	v_cvt_pk_bf16_f32 v77, v96, v97
	v_cvt_pk_bf16_f32 v78, v78, v79
	v_cvt_pk_bf16_f32 v79, v100, v101
	v_lshl_add_u64 v[96:97], v[36:37], 0, s[64:65]
	global_store_dwordx4 v[96:97], v[76:79], off
	s_lshl_b64 s[64:65], s[0:1], 12
	s_nop 0
	v_mov_b32_e32 v77, v80
	v_mov_b32_e32 v80, v105
	v_mov_b32_e32 v76, v104
	v_pk_mul_f32 v[78:79], v[98:99], v[80:81] op_sel_hi:[0,1]
	v_mov_b32_e32 v80, v108
	v_mov_b32_e32 v81, v82
	v_mov_b32_e32 v82, v109
	v_pk_mul_f32 v[76:77], v[98:99], v[76:77] op_sel_hi:[0,1]
	v_pk_mul_f32 v[80:81], v[98:99], v[80:81] op_sel_hi:[0,1]
	v_pk_mul_f32 v[82:83], v[98:99], v[82:83] op_sel_hi:[0,1]
	v_pk_fma_f32 v[78:79], v[48:49], v[78:79], v[6:7]
	v_pk_fma_f32 v[76:77], v[50:51], v[76:77], v[4:5]
	v_pk_fma_f32 v[82:83], v[44:45], v[82:83], v[2:3]
	v_pk_fma_f32 v[80:81], v[46:47], v[80:81], v[0:1]
	v_cvt_pk_bf16_f32 v76, v76, v77
	v_cvt_pk_bf16_f32 v77, v78, v79
	v_cvt_pk_bf16_f32 v78, v80, v81
	v_cvt_pk_bf16_f32 v79, v82, v83
	global_store_dwordx4 v[96:97], v[76:79], off offset:1024
	v_pk_mul_f32 v[80:81], v[98:99], v[114:115] op_sel_hi:[0,1]
	v_pk_mul_f32 v[82:83], v[98:99], v[86:87] op_sel_hi:[0,1]
	v_pk_mul_f32 v[76:77], v[98:99], v[112:113] op_sel_hi:[0,1]
	v_pk_mul_f32 v[78:79], v[98:99], v[84:85] op_sel_hi:[0,1]
	v_pk_fma_f32 v[78:79], v[64:65], v[78:79], v[22:23]
	v_pk_fma_f32 v[76:77], v[66:67], v[76:77], v[20:21]
	v_pk_fma_f32 v[82:83], v[60:61], v[82:83], v[18:19]
	v_pk_fma_f32 v[80:81], v[62:63], v[80:81], v[16:17]
	v_cvt_pk_bf16_f32 v76, v76, v77
	v_cvt_pk_bf16_f32 v77, v78, v79
	v_cvt_pk_bf16_f32 v78, v80, v81
	v_cvt_pk_bf16_f32 v79, v82, v83
	global_store_dwordx4 v[96:97], v[76:79], off offset:2048
	v_pk_mul_f32 v[80:81], v[94:95], v[98:99] op_sel_hi:[1,0]
	v_pk_mul_f32 v[82:83], v[90:91], v[98:99] op_sel_hi:[1,0]
	v_pk_mul_f32 v[76:77], v[92:93], v[98:99] op_sel_hi:[1,0]
	v_pk_mul_f32 v[78:79], v[88:89], v[98:99] op_sel_hi:[1,0]
	v_pk_fma_f32 v[76:77], v[74:75], v[76:77], v[28:29]
	v_pk_fma_f32 v[78:79], v[72:73], v[78:79], v[30:31]
	v_pk_fma_f32 v[82:83], v[68:69], v[82:83], v[26:27]
	v_pk_fma_f32 v[80:81], v[70:71], v[80:81], v[24:25]
	v_cvt_pk_bf16_f32 v76, v76, v77
	v_cvt_pk_bf16_f32 v77, v78, v79
	v_cvt_pk_bf16_f32 v78, v80, v81
	v_cvt_pk_bf16_f32 v79, v82, v83
	global_store_dwordx4 v[96:97], v[76:79], off offset:3072
	v_lshl_add_u64 v[88:89], v[34:35], 0, s[64:65]
	global_load_dwordx4 v[76:79], v[88:89], off
	global_load_dwordx4 v[80:83], v[88:89], off offset:1024
	global_load_dwordx4 v[84:87], v[88:89], off offset:2048
	s_nop 0
	global_load_dwordx4 v[88:91], v[88:89], off offset:3072
	s_waitcnt vmcnt(3)
	v_lshlrev_b32_e32 v97, 16, v77
	v_lshlrev_b32_e32 v96, 16, v76
	v_and_b32_e32 v77, 0xffff0000, v77
	v_and_b32_e32 v76, 0xffff0000, v76
	v_lshlrev_b32_e32 v101, 16, v79
	v_lshlrev_b32_e32 v100, 16, v78
	v_and_b32_e32 v79, 0xffff0000, v79
	v_and_b32_e32 v78, 0xffff0000, v78
	v_pk_mul_f32 v[98:99], v[76:77], v[76:77]
	v_pk_mul_f32 v[102:103], v[78:79], v[78:79]
	s_waitcnt vmcnt(0)
; __device__ __forceinline__ v4u pk8(f32x4 a, f32x4 b) { v4u w; w.x = pk2(a[0], a[1]); w.y = pk2(a[2], a[3]); w.z = pk2(b[0], b[1]); w.w = pk2(b[2], b[3]); return w; }
; __device__ __forceinline__ float ssq8(const f32x4& a, const f32x4& b) { return ((a[0] * a[0] + a[1] * a[1]) + (a[2] * a[2] + a[3] * a[3])) + ((b[0] * b[0] + b[1] * b[1]) + (b[2] * b[2] + b[3] * b[3])); }
; __device__ __forceinline__ float shfl_xor_f(float v, int o) {
;     int l; asm volatile("v_mbcnt_lo_u32_b32 %0, -1, 0\n\tv_mbcnt_hi_u32_b32 %0, -1, %0" : "=v"(l));
;     return __builtin_bit_cast(float, __builtin_amdgcn_ds_bpermute((l ^ o) << 2, __builtin_bit_cast(int, v)));
; }
; __device__ __forceinline__ float wave_sum(float v) {
; #pragma unroll
;     for (int o = 1; o < 64; o <<= 1) v += shfl_xor_f(v, o);
;     return v;
; template <int XF32> __device__ __forceinline__ void norm_mod_phase(const void* x, const float* modl, int ch_shift, int ch_scale, bf16* H, int gw, int NGW, int lane) {
;     ...
;         for (int rr = 0; rr < 8; ++rr) {
;             const unsigned char* xr = (const unsigned char*)x + (size_t)(r0 + rr) * rowb; f32x4 v[4][2]; float s = 0.f;
; #pragma unroll
;             for (int j = 0; j < 4; ++j) ld_row8<XF32>(xr, lane, j, v[j][0], v[j][1]);
; #pragma unroll
;             for (int j = 0; j < 4; ++j) s += ssq8(v[j][0], v[j][1]);
;             const float rstd = 1.f / sqrtf(wave_sum(s) * (1.f / DM) + EPS);
;             v4u* o = (v4u*)(H + (size_t)(r0 + rr) * DM);
; #pragma unroll
;             for (int j = 0; j < 4; ++j) o[lane + 64 * j] = pk8(v[j][0] * rstd * sc[j][0] + sh[j][0], v[j][1] * rstd * sc[j][1] + sh[j][1]);
	v_lshlrev_b32_e32 v92, 16, v88
	v_and_b32_e32 v93, 0xffff0000, v88
	v_pk_fma_f32 v[98:99], v[96:97], v[96:97], v[98:99]
	v_pk_fma_f32 v[102:103], v[100:101], v[100:101], v[102:103]
	v_lshlrev_b32_e32 v105, 16, v81
	v_lshlrev_b32_e32 v104, 16, v80
	v_and_b32_e32 v81, 0xffff0000, v81
	v_and_b32_e32 v80, 0xffff0000, v80
	v_lshlrev_b32_e32 v109, 16, v83
	v_lshlrev_b32_e32 v108, 16, v82
	v_and_b32_e32 v83, 0xffff0000, v83
	v_and_b32_e32 v82, 0xffff0000, v82
	v_pk_mul_f32 v[106:107], v[80:81], v[80:81]
	v_pk_mul_f32 v[110:111], v[82:83], v[82:83]
	v_mul_f32_e32 v116, v92, v92
	v_mul_f32_e32 v117, v93, v93
	v_pk_add_f32 v[98:99], v[98:99], v[98:99] op_sel:[0,1] op_sel_hi:[1,0]
	v_pk_add_f32 v[102:103], v[102:103], v[102:103] op_sel:[0,1] op_sel_hi:[1,0]
	v_lshlrev_b32_e32 v88, 16, v89
	v_and_b32_e32 v89, 0xffff0000, v89
	v_pk_fma_f32 v[106:107], v[104:105], v[104:105], v[106:107]
	v_pk_fma_f32 v[110:111], v[108:109], v[108:109], v[110:111]
	v_mov_b32_e32 v99, v116
	v_mov_b32_e32 v103, v117
	v_mul_f32_e32 v118, v88, v88
	v_mul_f32_e32 v119, v89, v89
	v_pk_add_f32 v[98:99], v[98:99], v[102:103]
	v_pk_add_f32 v[102:103], v[106:107], v[106:107] op_sel:[0,1] op_sel_hi:[1,0]
	v_pk_add_f32 v[106:107], v[110:111], v[110:111] op_sel:[0,1] op_sel_hi:[1,0]
	v_mov_b32_e32 v103, v118
	v_mov_b32_e32 v107, v119
	v_lshlrev_b32_e32 v112, 16, v84
	v_and_b32_e32 v113, 0xffff0000, v84
	v_lshlrev_b32_e32 v84, 16, v85
	v_and_b32_e32 v85, 0xffff0000, v85
	v_pk_add_f32 v[102:103], v[102:103], v[106:107]
	v_lshlrev_b32_e32 v94, 16, v90
	v_and_b32_e32 v95, 0xffff0000, v90
	v_pk_add_f32 v[98:99], v[98:99], v[102:103]
	v_mul_f32_e32 v102, v113, v113
	v_mul_f32_e32 v106, v85, v85
	v_mul_f32_e32 v120, v94, v94
	v_mul_f32_e32 v121, v95, v95
	v_pk_fma_f32 v[102:103], v[112:113], v[112:113], v[102:103] op_sel_hi:[1,1,0]
	v_pk_fma_f32 v[106:107], v[84:85], v[84:85], v[106:107] op_sel_hi:[1,1,0]
	v_lshlrev_b32_e32 v114, 16, v86
	v_and_b32_e32 v115, 0xffff0000, v86
	v_lshlrev_b32_e32 v86, 16, v87
	v_and_b32_e32 v87, 0xffff0000, v87
	v_mov_b32_e32 v103, v120
	v_mov_b32_e32 v107, v121
	v_lshlrev_b32_e32 v90, 16, v91
	v_and_b32_e32 v91, 0xffff0000, v91
	v_pk_add_f32 v[102:103], v[102:103], v[106:107]
	v_mul_f32_e32 v106, v115, v115
	v_mul_f32_e32 v110, v87, v87
	v_mul_f32_e32 v122, v90, v90
	v_mul_f32_e32 v123, v91, v91
	v_pk_fma_f32 v[106:107], v[114:115], v[114:115], v[106:107] op_sel_hi:[1,1,0]
	v_pk_fma_f32 v[110:111], v[86:87], v[86:87], v[110:111] op_sel_hi:[1,1,0]
	v_mov_b32_e32 v107, v122
	v_mov_b32_e32 v111, v123
	v_pk_add_f32 v[106:107], v[106:107], v[110:111]
	s_nop 0
	v_pk_add_f32 v[102:103], v[102:103], v[106:107]
	s_nop 0
	v_pk_add_f32 v[98:99], v[98:99], v[102:103]
	s_nop 0
	v_add_f32_e32 v98, v98, v99
	v_mbcnt_lo_u32_b32 v99, -1, 0
	v_mbcnt_hi_u32_b32 v99, -1, v99
	s_nop 0
	v_lshlrev_b32_e32 v99, 2, v99
	v_xor_b32_e32 v99, 4, v99
	ds_bpermute_b32 v99, v99, v98
	s_waitcnt lgkmcnt(0)
	v_add_f32_e32 v98, v98, v99
	v_mbcnt_lo_u32_b32 v99, -1, 0
	v_mbcnt_hi_u32_b32 v99, -1, v99
	s_nop 0
	v_lshlrev_b32_e32 v99, 2, v99
	v_xor_b32_e32 v99, 8, v99
	ds_bpermute_b32 v99, v99, v98
	s_waitcnt lgkmcnt(0)
	v_add_f32_e32 v98, v98, v99
	v_mbcnt_lo_u32_b32 v99, -1, 0
	v_mbcnt_hi_u32_b32 v99, -1, v99
	s_nop 0
	v_lshlrev_b32_e32 v99, 2, v99
	v_xor_b32_e32 v99, 16, v99
	ds_bpermute_b32 v99, v99, v98
	s_waitcnt lgkmcnt(0)
	v_add_f32_e32 v98, v98, v99
	v_mbcnt_lo_u32_b32 v99, -1, 0
	v_mbcnt_hi_u32_b32 v99, -1, v99
	s_nop 0
	v_lshlrev_b32_e32 v99, 2, v99
	v_xor_b32_e32 v99, 32, v99
	ds_bpermute_b32 v99, v99, v98
	s_waitcnt lgkmcnt(0)
	v_add_f32_e32 v98, v98, v99
	v_mbcnt_lo_u32_b32 v99, -1, 0
	v_mbcnt_hi_u32_b32 v99, -1, v99
	s_nop 0
	v_lshlrev_b32_e32 v99, 2, v99
	v_xor_b32_e32 v99, 64, v99
	ds_bpermute_b32 v99, v99, v98
	s_waitcnt lgkmcnt(0)
	v_add_f32_e32 v98, v98, v99
	v_mbcnt_lo_u32_b32 v99, -1, 0
	v_mbcnt_hi_u32_b32 v99, -1, v99
	s_nop 0
	v_lshlrev_b32_e32 v99, 2, v99
	v_xor_b32_e32 v99, 0x80, v99
	ds_bpermute_b32 v99, v99, v98
	s_waitcnt lgkmcnt(0)
	v_add_f32_e32 v98, v98, v99
	v_fmamk_f32 v98, v98, 0x3a000000, v224
	v_cmp_gt_f32_e32 vcc, s41, v98
	v_mul_f32_e32 v99, 0x4f800000, v98
	s_nop 0
	v_cndmask_b32_e32 v98, v98, v99, vcc
	v_sqrt_f32_e32 v99, v98
	s_nop 0
	v_add_u32_e32 v102, -1, v99
	v_fma_f32 v103, -v102, v99, v98
	v_cmp_ge_f32_e64 s[4:5], 0, v103
	v_add_u32_e32 v103, 1, v99
	s_nop 0
	v_cndmask_b32_e64 v102, v99, v102, s[4:5]
	v_fma_f32 v99, -v103, v99, v98
	v_cmp_lt_f32_e64 s[4:5], 0, v99
	s_nop 1
	v_cndmask_b32_e64 v99, v102, v103, s[4:5]
	v_mul_f32_e32 v102, 0x37800000, v99
	v_cndmask_b32_e32 v99, v99, v102, vcc
	v_cmp_class_f32_e32 vcc, v98, v225
	s_nop 1
	v_cndmask_b32_e32 v98, v99, v98, vcc
	v_div_scale_f32 v99, s[0:1], v98, v98, 1.0
	v_rcp_f32_e32 v102, v99
	s_add_i32 s0, s8, -5
	s_ashr_i32 s1, s0, 31
	v_fma_f32 v103, -v99, v102, 1.0
	v_fmac_f32_e32 v102, v103, v102
	v_div_scale_f32 v103, vcc, 1.0, v98, 1.0
	v_mul_f32_e32 v106, v103, v102
	v_fma_f32 v107, -v99, v106, v103
	v_fmac_f32_e32 v106, v107, v102
	v_fma_f32 v99, -v99, v106, v103
	v_div_fmas_f32 v99, v99, v102, v106
	v_div_fixup_f32 v98, v99, v98, 1.0
	v_mov_b32_e32 v102, v96
	v_mov_b32_e32 v103, v76
	v_mov_b32_e32 v76, v97
	v_pk_mul_f32 v[102:103], v[98:99], v[102:103] op_sel_hi:[0,1]
	v_pk_mul_f32 v[76:77], v[98:99], v[76:77] op_sel_hi:[0,1]
	v_pk_fma_f32 v[96:97], v[56:57], v[76:77], v[14:15]
	v_pk_fma_f32 v[76:77], v[58:59], v[102:103], v[12:13]
	v_mov_b32_e32 v102, v100
	v_mov_b32_e32 v103, v78
	v_mov_b32_e32 v78, v101
	v_pk_mul_f32 v[102:103], v[98:99], v[102:103] op_sel_hi:[0,1]
	v_pk_mul_f32 v[78:79], v[98:99], v[78:79] op_sel_hi:[0,1]
	v_pk_fma_f32 v[100:101], v[52:53], v[78:79], v[10:11]
; __device__ __forceinline__ v4u pk8(f32x4 a, f32x4 b) { v4u w; w.x = pk2(a[0], a[1]); w.y = pk2(a[2], a[3]); w.z = pk2(b[0], b[1]); w.w = pk2(b[2], b[3]); return w; }
; __device__ __forceinline__ float ssq8(const f32x4& a, const f32x4& b) { return ((a[0] * a[0] + a[1] * a[1]) + (a[2] * a[2] + a[3] * a[3])) + ((b[0] * b[0] + b[1] * b[1]) + (b[2] * b[2] + b[3] * b[3])); }
; template <int XF32> __device__ __forceinline__ void norm_mod_phase(const void* x, const float* modl, int ch_shift, int ch_scale, bf16* H, int gw, int NGW, int lane) {
;     ...
;         for (int rr = 0; rr < 8; ++rr) {
;             const unsigned char* xr = (const unsigned char*)x + (size_t)(r0 + rr) * rowb; f32x4 v[4][2]; float s = 0.f;
; #pragma unroll
;             for (int j = 0; j < 4; ++j) ld_row8<XF32>(xr, lane, j, v[j][0], v[j][1]);
; #pragma unroll
;             for (int j = 0; j < 4; ++j) s += ssq8(v[j][0], v[j][1]);
;             const float rstd = 1.f / sqrtf(wave_sum(s) * (1.f / DM) + EPS);
;             v4u* o = (v4u*)(H + (size_t)(r0 + rr) * DM);
; #pragma unroll
;             for (int j = 0; j < 4; ++j) o[lane + 64 * j] = pk8(v[j][0] * rstd * sc[j][0] + sh[j][0], v[j][1] * rstd * sc[j][1] + sh[j][1]);
	v_pk_fma_f32 v[78:79], v[54:55], v[102:103], v[8:9]
	v_cvt_pk_bf16_f32 v76, v76, v77
	v_cvt_pk_bf16_f32 v77, v96, v97
	v_cvt_pk_bf16_f32 v78, v78, v79
	v_cvt_pk_bf16_f32 v79, v100, v101
	v_lshl_add_u64 v[96:97], v[36:37], 0, s[64:65]
	global_store_dwordx4 v[96:97], v[76:79], off
	s_lshl_b64 s[64:65], s[0:1], 12
	s_nop 0
	v_mov_b32_e32 v77, v80
	v_mov_b32_e32 v80, v105
	v_mov_b32_e32 v76, v104
	v_pk_mul_f32 v[78:79], v[98:99], v[80:81] op_sel_hi:[0,1]
	v_mov_b32_e32 v80, v108
	v_mov_b32_e32 v81, v82
	v_mov_b32_e32 v82, v109
	v_pk_mul_f32 v[76:77], v[98:99], v[76:77] op_sel_hi:[0,1]
	v_pk_mul_f32 v[80:81], v[98:99], v[80:81] op_sel_hi:[0,1]
	v_pk_mul_f32 v[82:83], v[98:99], v[82:83] op_sel_hi:[0,1]
	v_pk_fma_f32 v[78:79], v[48:49], v[78:79], v[6:7]
	v_pk_fma_f32 v[76:77], v[50:51], v[76:77], v[4:5]
	v_pk_fma_f32 v[82:83], v[44:45], v[82:83], v[2:3]
	v_pk_fma_f32 v[80:81], v[46:47], v[80:81], v[0:1]
	v_cvt_pk_bf16_f32 v76, v76, v77
	v_cvt_pk_bf16_f32 v77, v78, v79
	v_cvt_pk_bf16_f32 v78, v80, v81
	v_cvt_pk_bf16_f32 v79, v82, v83
	global_store_dwordx4 v[96:97], v[76:79], off offset:1024
	v_pk_mul_f32 v[80:81], v[98:99], v[114:115] op_sel_hi:[0,1]
	v_pk_mul_f32 v[82:83], v[98:99], v[86:87] op_sel_hi:[0,1]
	v_pk_mul_f32 v[76:77], v[98:99], v[112:113] op_sel_hi:[0,1]
	v_pk_mul_f32 v[78:79], v[98:99], v[84:85] op_sel_hi:[0,1]
	v_pk_fma_f32 v[78:79], v[64:65], v[78:79], v[22:23]
	v_pk_fma_f32 v[76:77], v[66:67], v[76:77], v[20:21]
	v_pk_fma_f32 v[82:83], v[60:61], v[82:83], v[18:19]
	v_pk_fma_f32 v[80:81], v[62:63], v[80:81], v[16:17]
	v_cvt_pk_bf16_f32 v76, v76, v77
	v_cvt_pk_bf16_f32 v77, v78, v79
	v_cvt_pk_bf16_f32 v78, v80, v81
	v_cvt_pk_bf16_f32 v79, v82, v83
	global_store_dwordx4 v[96:97], v[76:79], off offset:2048
	v_pk_mul_f32 v[80:81], v[94:95], v[98:99] op_sel_hi:[1,0]
	v_pk_mul_f32 v[82:83], v[90:91], v[98:99] op_sel_hi:[1,0]
	v_pk_mul_f32 v[76:77], v[92:93], v[98:99] op_sel_hi:[1,0]
	v_pk_mul_f32 v[78:79], v[88:89], v[98:99] op_sel_hi:[1,0]
	v_pk_fma_f32 v[76:77], v[74:75], v[76:77], v[28:29]
	v_pk_fma_f32 v[78:79], v[72:73], v[78:79], v[30:31]
	v_pk_fma_f32 v[82:83], v[68:69], v[82:83], v[26:27]
	v_pk_fma_f32 v[80:81], v[70:71], v[80:81], v[24:25]
	v_cvt_pk_bf16_f32 v76, v76, v77
	v_cvt_pk_bf16_f32 v77, v78, v79
	v_cvt_pk_bf16_f32 v78, v80, v81
	v_cvt_pk_bf16_f32 v79, v82, v83
	global_store_dwordx4 v[96:97], v[76:79], off offset:3072
	v_lshl_add_u64 v[88:89], v[34:35], 0, s[64:65]
	global_load_dwordx4 v[76:79], v[88:89], off
	global_load_dwordx4 v[80:83], v[88:89], off offset:1024
	global_load_dwordx4 v[84:87], v[88:89], off offset:2048
	s_nop 0
	global_load_dwordx4 v[88:91], v[88:89], off offset:3072
	s_waitcnt vmcnt(3)
	v_lshlrev_b32_e32 v97, 16, v77
	v_lshlrev_b32_e32 v96, 16, v76
	v_and_b32_e32 v77, 0xffff0000, v77
	v_and_b32_e32 v76, 0xffff0000, v76
	v_lshlrev_b32_e32 v101, 16, v79
	v_lshlrev_b32_e32 v100, 16, v78
	v_and_b32_e32 v79, 0xffff0000, v79
	v_and_b32_e32 v78, 0xffff0000, v78
	v_pk_mul_f32 v[98:99], v[76:77], v[76:77]
	v_pk_mul_f32 v[102:103], v[78:79], v[78:79]
	s_waitcnt vmcnt(0)
	v_lshlrev_b32_e32 v92, 16, v88
	v_and_b32_e32 v93, 0xffff0000, v88
	v_pk_fma_f32 v[98:99], v[96:97], v[96:97], v[98:99]
	v_pk_fma_f32 v[102:103], v[100:101], v[100:101], v[102:103]
	v_lshlrev_b32_e32 v105, 16, v81
	v_lshlrev_b32_e32 v104, 16, v80
	v_and_b32_e32 v81, 0xffff0000, v81
	v_and_b32_e32 v80, 0xffff0000, v80
	v_lshlrev_b32_e32 v109, 16, v83
	v_lshlrev_b32_e32 v108, 16, v82
	v_and_b32_e32 v83, 0xffff0000, v83
	v_and_b32_e32 v82, 0xffff0000, v82
	v_pk_mul_f32 v[106:107], v[80:81], v[80:81]
	v_pk_mul_f32 v[110:111], v[82:83], v[82:83]
	v_mul_f32_e32 v116, v92, v92
	v_mul_f32_e32 v117, v93, v93
	v_pk_add_f32 v[98:99], v[98:99], v[98:99] op_sel:[0,1] op_sel_hi:[1,0]
	v_pk_add_f32 v[102:103], v[102:103], v[102:103] op_sel:[0,1] op_sel_hi:[1,0]
	v_lshlrev_b32_e32 v88, 16, v89
	v_and_b32_e32 v89, 0xffff0000, v89
	v_pk_fma_f32 v[106:107], v[104:105], v[104:105], v[106:107]
	v_pk_fma_f32 v[110:111], v[108:109], v[108:109], v[110:111]
	v_mov_b32_e32 v99, v116
	v_mov_b32_e32 v103, v117
	v_mul_f32_e32 v118, v88, v88
	v_mul_f32_e32 v119, v89, v89
	v_pk_add_f32 v[98:99], v[98:99], v[102:103]
	v_pk_add_f32 v[102:103], v[106:107], v[106:107] op_sel:[0,1] op_sel_hi:[1,0]
	v_pk_add_f32 v[106:107], v[110:111], v[110:111] op_sel:[0,1] op_sel_hi:[1,0]
	v_mov_b32_e32 v103, v118
	v_mov_b32_e32 v107, v119
	v_lshlrev_b32_e32 v112, 16, v84
	v_and_b32_e32 v113, 0xffff0000, v84
	v_lshlrev_b32_e32 v84, 16, v85
	v_and_b32_e32 v85, 0xffff0000, v85
	v_pk_add_f32 v[102:103], v[102:103], v[106:107]
	v_lshlrev_b32_e32 v94, 16, v90
	v_and_b32_e32 v95, 0xffff0000, v90
	v_pk_add_f32 v[98:99], v[98:99], v[102:103]
	v_mul_f32_e32 v102, v113, v113
	v_mul_f32_e32 v106, v85, v85
	v_mul_f32_e32 v120, v94, v94
	v_mul_f32_e32 v121, v95, v95
	v_pk_fma_f32 v[102:103], v[112:113], v[112:113], v[102:103] op_sel_hi:[1,1,0]
	v_pk_fma_f32 v[106:107], v[84:85], v[84:85], v[106:107] op_sel_hi:[1,1,0]
	v_lshlrev_b32_e32 v114, 16, v86
	v_and_b32_e32 v115, 0xffff0000, v86
	v_lshlrev_b32_e32 v86, 16, v87
	v_and_b32_e32 v87, 0xffff0000, v87
	v_mov_b32_e32 v103, v120
	v_mov_b32_e32 v107, v121
	v_lshlrev_b32_e32 v90, 16, v91
	v_and_b32_e32 v91, 0xffff0000, v91
	v_pk_add_f32 v[102:103], v[102:103], v[106:107]
	v_mul_f32_e32 v106, v115, v115
	v_mul_f32_e32 v110, v87, v87
	v_mul_f32_e32 v122, v90, v90
	v_mul_f32_e32 v123, v91, v91
	v_pk_fma_f32 v[106:107], v[114:115], v[114:115], v[106:107] op_sel_hi:[1,1,0]
	v_pk_fma_f32 v[110:111], v[86:87], v[86:87], v[110:111] op_sel_hi:[1,1,0]
	v_mov_b32_e32 v107, v122
	v_mov_b32_e32 v111, v123
	v_pk_add_f32 v[106:107], v[106:107], v[110:111]
	s_nop 0
	v_pk_add_f32 v[102:103], v[102:103], v[106:107]
	s_nop 0
	v_pk_add_f32 v[98:99], v[98:99], v[102:103]
	s_nop 0
	v_add_f32_e32 v98, v98, v99
	v_mbcnt_lo_u32_b32 v99, -1, 0
	v_mbcnt_hi_u32_b32 v99, -1, v99
	s_nop 0
	v_lshlrev_b32_e32 v99, 2, v99
	v_xor_b32_e32 v99, 4, v99
	ds_bpermute_b32 v99, v99, v98
	s_waitcnt lgkmcnt(0)
; __device__ __forceinline__ v4u pk8(f32x4 a, f32x4 b) { v4u w; w.x = pk2(a[0], a[1]); w.y = pk2(a[2], a[3]); w.z = pk2(b[0], b[1]); w.w = pk2(b[2], b[3]); return w; }
; __device__ __forceinline__ float shfl_xor_f(float v, int o) {
;     int l; asm volatile("v_mbcnt_lo_u32_b32 %0, -1, 0\n\tv_mbcnt_hi_u32_b32 %0, -1, %0" : "=v"(l));
;     return __builtin_bit_cast(float, __builtin_amdgcn_ds_bpermute((l ^ o) << 2, __builtin_bit_cast(int, v)));
; }
; __device__ __forceinline__ float wave_sum(float v) {
; #pragma unroll
;     for (int o = 1; o < 64; o <<= 1) v += shfl_xor_f(v, o);
;     return v;
; template <int XF32> __device__ __forceinline__ void norm_mod_phase(const void* x, const float* modl, int ch_shift, int ch_scale, bf16* H, int gw, int NGW, int lane) {
;     ...
;             const float rstd = 1.f / sqrtf(wave_sum(s) * (1.f / DM) + EPS);
;             v4u* o = (v4u*)(H + (size_t)(r0 + rr) * DM);
; #pragma unroll
;             for (int j = 0; j < 4; ++j) o[lane + 64 * j] = pk8(v[j][0] * rstd * sc[j][0] + sh[j][0], v[j][1] * rstd * sc[j][1] + sh[j][1]);
	v_add_f32_e32 v98, v98, v99
	v_mbcnt_lo_u32_b32 v99, -1, 0
	v_mbcnt_hi_u32_b32 v99, -1, v99
	s_nop 0
	v_lshlrev_b32_e32 v99, 2, v99
	v_xor_b32_e32 v99, 8, v99
	ds_bpermute_b32 v99, v99, v98
	s_waitcnt lgkmcnt(0)
	v_add_f32_e32 v98, v98, v99
	v_mbcnt_lo_u32_b32 v99, -1, 0
	v_mbcnt_hi_u32_b32 v99, -1, v99
	s_nop 0
	v_lshlrev_b32_e32 v99, 2, v99
	v_xor_b32_e32 v99, 16, v99
	ds_bpermute_b32 v99, v99, v98
	s_waitcnt lgkmcnt(0)
	v_add_f32_e32 v98, v98, v99
	v_mbcnt_lo_u32_b32 v99, -1, 0
	v_mbcnt_hi_u32_b32 v99, -1, v99
	s_nop 0
	v_lshlrev_b32_e32 v99, 2, v99
	v_xor_b32_e32 v99, 32, v99
	ds_bpermute_b32 v99, v99, v98
	s_waitcnt lgkmcnt(0)
	v_add_f32_e32 v98, v98, v99
	v_mbcnt_lo_u32_b32 v99, -1, 0
	v_mbcnt_hi_u32_b32 v99, -1, v99
	s_nop 0
	v_lshlrev_b32_e32 v99, 2, v99
	v_xor_b32_e32 v99, 64, v99
	ds_bpermute_b32 v99, v99, v98
	s_waitcnt lgkmcnt(0)
	v_add_f32_e32 v98, v98, v99
	v_mbcnt_lo_u32_b32 v99, -1, 0
	v_mbcnt_hi_u32_b32 v99, -1, v99
	s_nop 0
	v_lshlrev_b32_e32 v99, 2, v99
	v_xor_b32_e32 v99, 0x80, v99
	ds_bpermute_b32 v99, v99, v98
	s_waitcnt lgkmcnt(0)
	v_add_f32_e32 v98, v98, v99
	v_fmamk_f32 v98, v98, 0x3a000000, v224
	v_cmp_gt_f32_e32 vcc, s41, v98
	v_mul_f32_e32 v99, 0x4f800000, v98
	s_nop 0
	v_cndmask_b32_e32 v98, v98, v99, vcc
	v_sqrt_f32_e32 v99, v98
	s_nop 0
	v_add_u32_e32 v102, -1, v99
	v_fma_f32 v103, -v102, v99, v98
	v_cmp_ge_f32_e64 s[4:5], 0, v103
	v_add_u32_e32 v103, 1, v99
	s_nop 0
	v_cndmask_b32_e64 v102, v99, v102, s[4:5]
	v_fma_f32 v99, -v103, v99, v98
	v_cmp_lt_f32_e64 s[4:5], 0, v99
	s_nop 1
	v_cndmask_b32_e64 v99, v102, v103, s[4:5]
	v_mul_f32_e32 v102, 0x37800000, v99
	v_cndmask_b32_e32 v99, v99, v102, vcc
	v_cmp_class_f32_e32 vcc, v98, v225
	s_nop 1
	v_cndmask_b32_e32 v98, v99, v98, vcc
	v_div_scale_f32 v99, s[0:1], v98, v98, 1.0
	v_rcp_f32_e32 v102, v99
	s_add_i32 s0, s8, -4
	s_ashr_i32 s1, s0, 31
	v_fma_f32 v103, -v99, v102, 1.0
	v_fmac_f32_e32 v102, v103, v102
	v_div_scale_f32 v103, vcc, 1.0, v98, 1.0
	v_mul_f32_e32 v106, v103, v102
	v_fma_f32 v107, -v99, v106, v103
	v_fmac_f32_e32 v106, v107, v102
	v_fma_f32 v99, -v99, v106, v103
	v_div_fmas_f32 v99, v99, v102, v106
	v_div_fixup_f32 v98, v99, v98, 1.0
	v_mov_b32_e32 v102, v96
	v_mov_b32_e32 v103, v76
	v_mov_b32_e32 v76, v97
	v_pk_mul_f32 v[102:103], v[98:99], v[102:103] op_sel_hi:[0,1]
	v_pk_mul_f32 v[76:77], v[98:99], v[76:77] op_sel_hi:[0,1]
	v_pk_fma_f32 v[96:97], v[56:57], v[76:77], v[14:15]
	v_pk_fma_f32 v[76:77], v[58:59], v[102:103], v[12:13]
	v_mov_b32_e32 v102, v100
	v_mov_b32_e32 v103, v78
	v_mov_b32_e32 v78, v101
	v_pk_mul_f32 v[102:103], v[98:99], v[102:103] op_sel_hi:[0,1]
	v_pk_mul_f32 v[78:79], v[98:99], v[78:79] op_sel_hi:[0,1]
	v_pk_fma_f32 v[100:101], v[52:53], v[78:79], v[10:11]
	v_pk_fma_f32 v[78:79], v[54:55], v[102:103], v[8:9]
	v_cvt_pk_bf16_f32 v76, v76, v77
	v_cvt_pk_bf16_f32 v77, v96, v97
	v_cvt_pk_bf16_f32 v78, v78, v79
	v_cvt_pk_bf16_f32 v79, v100, v101
	v_lshl_add_u64 v[96:97], v[36:37], 0, s[64:65]
	global_store_dwordx4 v[96:97], v[76:79], off
	s_lshl_b64 s[64:65], s[0:1], 12
	s_nop 0
	v_mov_b32_e32 v77, v80
	v_mov_b32_e32 v80, v105
	v_mov_b32_e32 v76, v104
	v_pk_mul_f32 v[78:79], v[98:99], v[80:81] op_sel_hi:[0,1]
	v_mov_b32_e32 v80, v108
	v_mov_b32_e32 v81, v82
	v_mov_b32_e32 v82, v109
	v_pk_mul_f32 v[76:77], v[98:99], v[76:77] op_sel_hi:[0,1]
	v_pk_mul_f32 v[80:81], v[98:99], v[80:81] op_sel_hi:[0,1]
	v_pk_mul_f32 v[82:83], v[98:99], v[82:83] op_sel_hi:[0,1]
	v_pk_fma_f32 v[78:79], v[48:49], v[78:79], v[6:7]
	v_pk_fma_f32 v[76:77], v[50:51], v[76:77], v[4:5]
	v_pk_fma_f32 v[82:83], v[44:45], v[82:83], v[2:3]
	v_pk_fma_f32 v[80:81], v[46:47], v[80:81], v[0:1]
	v_cvt_pk_bf16_f32 v76, v76, v77
	v_cvt_pk_bf16_f32 v77, v78, v79
	v_cvt_pk_bf16_f32 v78, v80, v81
	v_cvt_pk_bf16_f32 v79, v82, v83
	global_store_dwordx4 v[96:97], v[76:79], off offset:1024
	v_pk_mul_f32 v[80:81], v[98:99], v[114:115] op_sel_hi:[0,1]
	v_pk_mul_f32 v[82:83], v[98:99], v[86:87] op_sel_hi:[0,1]
	v_pk_mul_f32 v[76:77], v[98:99], v[112:113] op_sel_hi:[0,1]
	v_pk_mul_f32 v[78:79], v[98:99], v[84:85] op_sel_hi:[0,1]
	v_pk_fma_f32 v[78:79], v[64:65], v[78:79], v[22:23]
	v_pk_fma_f32 v[76:77], v[66:67], v[76:77], v[20:21]
	v_pk_fma_f32 v[82:83], v[60:61], v[82:83], v[18:19]
	v_pk_fma_f32 v[80:81], v[62:63], v[80:81], v[16:17]
	v_cvt_pk_bf16_f32 v76, v76, v77
	v_cvt_pk_bf16_f32 v77, v78, v79
	v_cvt_pk_bf16_f32 v78, v80, v81
	v_cvt_pk_bf16_f32 v79, v82, v83
	global_store_dwordx4 v[96:97], v[76:79], off offset:2048
	v_pk_mul_f32 v[80:81], v[94:95], v[98:99] op_sel_hi:[1,0]
	v_pk_mul_f32 v[82:83], v[90:91], v[98:99] op_sel_hi:[1,0]
	v_pk_mul_f32 v[76:77], v[92:93], v[98:99] op_sel_hi:[1,0]
	v_pk_mul_f32 v[78:79], v[88:89], v[98:99] op_sel_hi:[1,0]
	v_pk_fma_f32 v[76:77], v[74:75], v[76:77], v[28:29]
	v_pk_fma_f32 v[78:79], v[72:73], v[78:79], v[30:31]
	v_pk_fma_f32 v[82:83], v[68:69], v[82:83], v[26:27]
	v_pk_fma_f32 v[80:81], v[70:71], v[80:81], v[24:25]
	v_cvt_pk_bf16_f32 v76, v76, v77
	v_cvt_pk_bf16_f32 v77, v78, v79
	v_cvt_pk_bf16_f32 v78, v80, v81
	v_cvt_pk_bf16_f32 v79, v82, v83
	global_store_dwordx4 v[96:97], v[76:79], off offset:3072
	v_lshl_add_u64 v[88:89], v[34:35], 0, s[64:65]
	global_load_dwordx4 v[76:79], v[88:89], off
	global_load_dwordx4 v[80:83], v[88:89], off offset:1024
	global_load_dwordx4 v[84:87], v[88:89], off offset:2048
	s_nop 0
	global_load_dwordx4 v[88:91], v[88:89], off offset:3072
	s_waitcnt vmcnt(3)
	v_lshlrev_b32_e32 v97, 16, v77
	v_lshlrev_b32_e32 v96, 16, v76
	v_and_b32_e32 v77, 0xffff0000, v77
	v_and_b32_e32 v76, 0xffff0000, v76
	v_lshlrev_b32_e32 v101, 16, v79
	v_lshlrev_b32_e32 v100, 16, v78
	v_and_b32_e32 v79, 0xffff0000, v79
	v_and_b32_e32 v78, 0xffff0000, v78
	v_pk_mul_f32 v[98:99], v[76:77], v[76:77]
	v_pk_mul_f32 v[102:103], v[78:79], v[78:79]
	s_waitcnt vmcnt(0)
; __device__ __forceinline__ v4u pk8(f32x4 a, f32x4 b) { v4u w; w.x = pk2(a[0], a[1]); w.y = pk2(a[2], a[3]); w.z = pk2(b[0], b[1]); w.w = pk2(b[2], b[3]); return w; }
; __device__ __forceinline__ float ssq8(const f32x4& a, const f32x4& b) { return ((a[0] * a[0] + a[1] * a[1]) + (a[2] * a[2] + a[3] * a[3])) + ((b[0] * b[0] + b[1] * b[1]) + (b[2] * b[2] + b[3] * b[3])); }
; __device__ __forceinline__ float shfl_xor_f(float v, int o) {
;     int l; asm volatile("v_mbcnt_lo_u32_b32 %0, -1, 0\n\tv_mbcnt_hi_u32_b32 %0, -1, %0" : "=v"(l));
;     return __builtin_bit_cast(float, __builtin_amdgcn_ds_bpermute((l ^ o) << 2, __builtin_bit_cast(int, v)));
; }
; __device__ __forceinline__ float wave_sum(float v) {
; #pragma unroll
;     for (int o = 1; o < 64; o <<= 1) v += shfl_xor_f(v, o);
;     return v;
; template <int XF32> __device__ __forceinline__ void norm_mod_phase(const void* x, const float* modl, int ch_shift, int ch_scale, bf16* H, int gw, int NGW, int lane) {
;     ...
;         for (int rr = 0; rr < 8; ++rr) {
;             const unsigned char* xr = (const unsigned char*)x + (size_t)(r0 + rr) * rowb; f32x4 v[4][2]; float s = 0.f;
; #pragma unroll
;             for (int j = 0; j < 4; ++j) ld_row8<XF32>(xr, lane, j, v[j][0], v[j][1]);
; #pragma unroll
;             for (int j = 0; j < 4; ++j) s += ssq8(v[j][0], v[j][1]);
;             const float rstd = 1.f / sqrtf(wave_sum(s) * (1.f / DM) + EPS);
;             v4u* o = (v4u*)(H + (size_t)(r0 + rr) * DM);
; #pragma unroll
;             for (int j = 0; j < 4; ++j) o[lane + 64 * j] = pk8(v[j][0] * rstd * sc[j][0] + sh[j][0], v[j][1] * rstd * sc[j][1] + sh[j][1]);
	v_lshlrev_b32_e32 v92, 16, v88
	v_and_b32_e32 v93, 0xffff0000, v88
	v_pk_fma_f32 v[98:99], v[96:97], v[96:97], v[98:99]
	v_pk_fma_f32 v[102:103], v[100:101], v[100:101], v[102:103]
	v_lshlrev_b32_e32 v105, 16, v81
	v_lshlrev_b32_e32 v104, 16, v80
	v_and_b32_e32 v81, 0xffff0000, v81
	v_and_b32_e32 v80, 0xffff0000, v80
	v_lshlrev_b32_e32 v109, 16, v83
	v_lshlrev_b32_e32 v108, 16, v82
	v_and_b32_e32 v83, 0xffff0000, v83
	v_and_b32_e32 v82, 0xffff0000, v82
	v_pk_mul_f32 v[106:107], v[80:81], v[80:81]
	v_pk_mul_f32 v[110:111], v[82:83], v[82:83]
	v_mul_f32_e32 v116, v92, v92
	v_mul_f32_e32 v117, v93, v93
	v_pk_add_f32 v[98:99], v[98:99], v[98:99] op_sel:[0,1] op_sel_hi:[1,0]
	v_pk_add_f32 v[102:103], v[102:103], v[102:103] op_sel:[0,1] op_sel_hi:[1,0]
	v_lshlrev_b32_e32 v88, 16, v89
	v_and_b32_e32 v89, 0xffff0000, v89
	v_pk_fma_f32 v[106:107], v[104:105], v[104:105], v[106:107]
	v_pk_fma_f32 v[110:111], v[108:109], v[108:109], v[110:111]
	v_mov_b32_e32 v99, v116
	v_mov_b32_e32 v103, v117
	v_mul_f32_e32 v118, v88, v88
	v_mul_f32_e32 v119, v89, v89
	v_pk_add_f32 v[98:99], v[98:99], v[102:103]
	v_pk_add_f32 v[102:103], v[106:107], v[106:107] op_sel:[0,1] op_sel_hi:[1,0]
	v_pk_add_f32 v[106:107], v[110:111], v[110:111] op_sel:[0,1] op_sel_hi:[1,0]
	v_mov_b32_e32 v103, v118
	v_mov_b32_e32 v107, v119
	v_lshlrev_b32_e32 v112, 16, v84
	v_and_b32_e32 v113, 0xffff0000, v84
	v_lshlrev_b32_e32 v84, 16, v85
	v_and_b32_e32 v85, 0xffff0000, v85
	v_pk_add_f32 v[102:103], v[102:103], v[106:107]
	v_lshlrev_b32_e32 v94, 16, v90
	v_and_b32_e32 v95, 0xffff0000, v90
	v_pk_add_f32 v[98:99], v[98:99], v[102:103]
	v_mul_f32_e32 v102, v113, v113
	v_mul_f32_e32 v106, v85, v85
	v_mul_f32_e32 v120, v94, v94
	v_mul_f32_e32 v121, v95, v95
	v_pk_fma_f32 v[102:103], v[112:113], v[112:113], v[102:103] op_sel_hi:[1,1,0]
	v_pk_fma_f32 v[106:107], v[84:85], v[84:85], v[106:107] op_sel_hi:[1,1,0]
	v_lshlrev_b32_e32 v114, 16, v86
	v_and_b32_e32 v115, 0xffff0000, v86
	v_lshlrev_b32_e32 v86, 16, v87
	v_and_b32_e32 v87, 0xffff0000, v87
	v_mov_b32_e32 v103, v120
	v_mov_b32_e32 v107, v121
	v_lshlrev_b32_e32 v90, 16, v91
	v_and_b32_e32 v91, 0xffff0000, v91
	v_pk_add_f32 v[102:103], v[102:103], v[106:107]
	v_mul_f32_e32 v106, v115, v115
	v_mul_f32_e32 v110, v87, v87
	v_mul_f32_e32 v122, v90, v90
	v_mul_f32_e32 v123, v91, v91
	v_pk_fma_f32 v[106:107], v[114:115], v[114:115], v[106:107] op_sel_hi:[1,1,0]
	v_pk_fma_f32 v[110:111], v[86:87], v[86:87], v[110:111] op_sel_hi:[1,1,0]
	v_mov_b32_e32 v107, v122
	v_mov_b32_e32 v111, v123
	v_pk_add_f32 v[106:107], v[106:107], v[110:111]
	s_nop 0
	v_pk_add_f32 v[102:103], v[102:103], v[106:107]
	s_nop 0
	v_pk_add_f32 v[98:99], v[98:99], v[102:103]
	s_nop 0
	v_add_f32_e32 v98, v98, v99
	v_mbcnt_lo_u32_b32 v99, -1, 0
	v_mbcnt_hi_u32_b32 v99, -1, v99
	s_nop 0
	v_lshlrev_b32_e32 v99, 2, v99
	v_xor_b32_e32 v99, 4, v99
	ds_bpermute_b32 v99, v99, v98
	s_waitcnt lgkmcnt(0)
	v_add_f32_e32 v98, v98, v99
	v_mbcnt_lo_u32_b32 v99, -1, 0
	v_mbcnt_hi_u32_b32 v99, -1, v99
	s_nop 0
	v_lshlrev_b32_e32 v99, 2, v99
	v_xor_b32_e32 v99, 8, v99
	ds_bpermute_b32 v99, v99, v98
	s_waitcnt lgkmcnt(0)
	v_add_f32_e32 v98, v98, v99
	v_mbcnt_lo_u32_b32 v99, -1, 0
	v_mbcnt_hi_u32_b32 v99, -1, v99
	s_nop 0
	v_lshlrev_b32_e32 v99, 2, v99
	v_xor_b32_e32 v99, 16, v99
	ds_bpermute_b32 v99, v99, v98
	s_waitcnt lgkmcnt(0)
	v_add_f32_e32 v98, v98, v99
	v_mbcnt_lo_u32_b32 v99, -1, 0
	v_mbcnt_hi_u32_b32 v99, -1, v99
	s_nop 0
	v_lshlrev_b32_e32 v99, 2, v99
	v_xor_b32_e32 v99, 32, v99
	ds_bpermute_b32 v99, v99, v98
	s_waitcnt lgkmcnt(0)
	v_add_f32_e32 v98, v98, v99
	v_mbcnt_lo_u32_b32 v99, -1, 0
	v_mbcnt_hi_u32_b32 v99, -1, v99
	s_nop 0
	v_lshlrev_b32_e32 v99, 2, v99
	v_xor_b32_e32 v99, 64, v99
	ds_bpermute_b32 v99, v99, v98
	s_waitcnt lgkmcnt(0)
	v_add_f32_e32 v98, v98, v99
	v_mbcnt_lo_u32_b32 v99, -1, 0
	v_mbcnt_hi_u32_b32 v99, -1, v99
	s_nop 0
	v_lshlrev_b32_e32 v99, 2, v99
	v_xor_b32_e32 v99, 0x80, v99
	ds_bpermute_b32 v99, v99, v98
	s_waitcnt lgkmcnt(0)
	v_add_f32_e32 v98, v98, v99
	v_fmamk_f32 v98, v98, 0x3a000000, v224
	v_cmp_gt_f32_e32 vcc, s41, v98
	v_mul_f32_e32 v99, 0x4f800000, v98
	s_nop 0
	v_cndmask_b32_e32 v98, v98, v99, vcc
	v_sqrt_f32_e32 v99, v98
	s_nop 0
	v_add_u32_e32 v102, -1, v99
	v_fma_f32 v103, -v102, v99, v98
	v_cmp_ge_f32_e64 s[4:5], 0, v103
	v_add_u32_e32 v103, 1, v99
	s_nop 0
	v_cndmask_b32_e64 v102, v99, v102, s[4:5]
	v_fma_f32 v99, -v103, v99, v98
	v_cmp_lt_f32_e64 s[4:5], 0, v99
	s_nop 1
	v_cndmask_b32_e64 v99, v102, v103, s[4:5]
	v_mul_f32_e32 v102, 0x37800000, v99
	v_cndmask_b32_e32 v99, v99, v102, vcc
	v_cmp_class_f32_e32 vcc, v98, v225
	s_nop 1
	v_cndmask_b32_e32 v98, v99, v98, vcc
	v_div_scale_f32 v99, s[0:1], v98, v98, 1.0
	v_rcp_f32_e32 v102, v99
	s_add_i32 s0, s8, -3
	s_ashr_i32 s1, s0, 31
	v_fma_f32 v103, -v99, v102, 1.0
	v_fmac_f32_e32 v102, v103, v102
	v_div_scale_f32 v103, vcc, 1.0, v98, 1.0
	v_mul_f32_e32 v106, v103, v102
	v_fma_f32 v107, -v99, v106, v103
	v_fmac_f32_e32 v106, v107, v102
	v_fma_f32 v99, -v99, v106, v103
	v_div_fmas_f32 v99, v99, v102, v106
	v_div_fixup_f32 v98, v99, v98, 1.0
	v_mov_b32_e32 v102, v96
	v_mov_b32_e32 v103, v76
	v_mov_b32_e32 v76, v97
	v_pk_mul_f32 v[102:103], v[98:99], v[102:103] op_sel_hi:[0,1]
	v_pk_mul_f32 v[76:77], v[98:99], v[76:77] op_sel_hi:[0,1]
	v_pk_fma_f32 v[96:97], v[56:57], v[76:77], v[14:15]
	v_pk_fma_f32 v[76:77], v[58:59], v[102:103], v[12:13]
	v_mov_b32_e32 v102, v100
	v_mov_b32_e32 v103, v78
	v_mov_b32_e32 v78, v101
	v_pk_mul_f32 v[102:103], v[98:99], v[102:103] op_sel_hi:[0,1]
	v_pk_mul_f32 v[78:79], v[98:99], v[78:79] op_sel_hi:[0,1]
	v_pk_fma_f32 v[100:101], v[52:53], v[78:79], v[10:11]
; __device__ __forceinline__ v4u pk8(f32x4 a, f32x4 b) { v4u w; w.x = pk2(a[0], a[1]); w.y = pk2(a[2], a[3]); w.z = pk2(b[0], b[1]); w.w = pk2(b[2], b[3]); return w; }
; __device__ __forceinline__ float ssq8(const f32x4& a, const f32x4& b) { return ((a[0] * a[0] + a[1] * a[1]) + (a[2] * a[2] + a[3] * a[3])) + ((b[0] * b[0] + b[1] * b[1]) + (b[2] * b[2] + b[3] * b[3])); }
; template <int XF32> __device__ __forceinline__ void norm_mod_phase(const void* x, const float* modl, int ch_shift, int ch_scale, bf16* H, int gw, int NGW, int lane) {
;     ...
;         for (int rr = 0; rr < 8; ++rr) {
;             const unsigned char* xr = (const unsigned char*)x + (size_t)(r0 + rr) * rowb; f32x4 v[4][2]; float s = 0.f;
; #pragma unroll
;             for (int j = 0; j < 4; ++j) ld_row8<XF32>(xr, lane, j, v[j][0], v[j][1]);
; #pragma unroll
;             for (int j = 0; j < 4; ++j) s += ssq8(v[j][0], v[j][1]);
;             const float rstd = 1.f / sqrtf(wave_sum(s) * (1.f / DM) + EPS);
;             v4u* o = (v4u*)(H + (size_t)(r0 + rr) * DM);
; #pragma unroll
;             for (int j = 0; j < 4; ++j) o[lane + 64 * j] = pk8(v[j][0] * rstd * sc[j][0] + sh[j][0], v[j][1] * rstd * sc[j][1] + sh[j][1]);
	v_pk_fma_f32 v[78:79], v[54:55], v[102:103], v[8:9]
	v_cvt_pk_bf16_f32 v76, v76, v77
	v_cvt_pk_bf16_f32 v77, v96, v97
	v_cvt_pk_bf16_f32 v78, v78, v79
	v_cvt_pk_bf16_f32 v79, v100, v101
	v_lshl_add_u64 v[96:97], v[36:37], 0, s[64:65]
	global_store_dwordx4 v[96:97], v[76:79], off
	s_lshl_b64 s[64:65], s[0:1], 12
	s_nop 0
	v_mov_b32_e32 v77, v80
	v_mov_b32_e32 v80, v105
	v_mov_b32_e32 v76, v104
	v_pk_mul_f32 v[78:79], v[98:99], v[80:81] op_sel_hi:[0,1]
	v_mov_b32_e32 v80, v108
	v_mov_b32_e32 v81, v82
	v_mov_b32_e32 v82, v109
	v_pk_mul_f32 v[76:77], v[98:99], v[76:77] op_sel_hi:[0,1]
	v_pk_mul_f32 v[80:81], v[98:99], v[80:81] op_sel_hi:[0,1]
	v_pk_mul_f32 v[82:83], v[98:99], v[82:83] op_sel_hi:[0,1]
	v_pk_fma_f32 v[78:79], v[48:49], v[78:79], v[6:7]
	v_pk_fma_f32 v[76:77], v[50:51], v[76:77], v[4:5]
	v_pk_fma_f32 v[82:83], v[44:45], v[82:83], v[2:3]
	v_pk_fma_f32 v[80:81], v[46:47], v[80:81], v[0:1]
	v_cvt_pk_bf16_f32 v76, v76, v77
	v_cvt_pk_bf16_f32 v77, v78, v79
	v_cvt_pk_bf16_f32 v78, v80, v81
	v_cvt_pk_bf16_f32 v79, v82, v83
	global_store_dwordx4 v[96:97], v[76:79], off offset:1024
	v_pk_mul_f32 v[80:81], v[98:99], v[114:115] op_sel_hi:[0,1]
	v_pk_mul_f32 v[82:83], v[98:99], v[86:87] op_sel_hi:[0,1]
	v_pk_mul_f32 v[76:77], v[98:99], v[112:113] op_sel_hi:[0,1]
	v_pk_mul_f32 v[78:79], v[98:99], v[84:85] op_sel_hi:[0,1]
	v_pk_fma_f32 v[78:79], v[64:65], v[78:79], v[22:23]
	v_pk_fma_f32 v[76:77], v[66:67], v[76:77], v[20:21]
	v_pk_fma_f32 v[82:83], v[60:61], v[82:83], v[18:19]
	v_pk_fma_f32 v[80:81], v[62:63], v[80:81], v[16:17]
	v_cvt_pk_bf16_f32 v76, v76, v77
	v_cvt_pk_bf16_f32 v77, v78, v79
	v_cvt_pk_bf16_f32 v78, v80, v81
	v_cvt_pk_bf16_f32 v79, v82, v83
	global_store_dwordx4 v[96:97], v[76:79], off offset:2048
	v_pk_mul_f32 v[80:81], v[94:95], v[98:99] op_sel_hi:[1,0]
	v_pk_mul_f32 v[82:83], v[90:91], v[98:99] op_sel_hi:[1,0]
	v_pk_mul_f32 v[76:77], v[92:93], v[98:99] op_sel_hi:[1,0]
	v_pk_mul_f32 v[78:79], v[88:89], v[98:99] op_sel_hi:[1,0]
	v_pk_fma_f32 v[76:77], v[74:75], v[76:77], v[28:29]
	v_pk_fma_f32 v[78:79], v[72:73], v[78:79], v[30:31]
	v_pk_fma_f32 v[82:83], v[68:69], v[82:83], v[26:27]
	v_pk_fma_f32 v[80:81], v[70:71], v[80:81], v[24:25]
	v_cvt_pk_bf16_f32 v76, v76, v77
	v_cvt_pk_bf16_f32 v77, v78, v79
	v_cvt_pk_bf16_f32 v78, v80, v81
	v_cvt_pk_bf16_f32 v79, v82, v83
	global_store_dwordx4 v[96:97], v[76:79], off offset:3072
	v_lshl_add_u64 v[88:89], v[34:35], 0, s[64:65]
	global_load_dwordx4 v[76:79], v[88:89], off
	global_load_dwordx4 v[80:83], v[88:89], off offset:1024
	global_load_dwordx4 v[84:87], v[88:89], off offset:2048
	s_nop 0
	global_load_dwordx4 v[88:91], v[88:89], off offset:3072
	s_waitcnt vmcnt(3)
	v_lshlrev_b32_e32 v97, 16, v77
	v_lshlrev_b32_e32 v96, 16, v76
	v_and_b32_e32 v77, 0xffff0000, v77
	v_and_b32_e32 v76, 0xffff0000, v76
	v_lshlrev_b32_e32 v101, 16, v79
	v_lshlrev_b32_e32 v100, 16, v78
	v_and_b32_e32 v79, 0xffff0000, v79
	v_and_b32_e32 v78, 0xffff0000, v78
	v_pk_mul_f32 v[98:99], v[76:77], v[76:77]
	v_pk_mul_f32 v[102:103], v[78:79], v[78:79]
	s_waitcnt vmcnt(0)
	v_lshlrev_b32_e32 v92, 16, v88
	v_and_b32_e32 v93, 0xffff0000, v88
	v_pk_fma_f32 v[98:99], v[96:97], v[96:97], v[98:99]
	v_pk_fma_f32 v[102:103], v[100:101], v[100:101], v[102:103]
	v_lshlrev_b32_e32 v105, 16, v81
	v_lshlrev_b32_e32 v104, 16, v80
	v_and_b32_e32 v81, 0xffff0000, v81
	v_and_b32_e32 v80, 0xffff0000, v80
	v_lshlrev_b32_e32 v109, 16, v83
	v_lshlrev_b32_e32 v108, 16, v82
	v_and_b32_e32 v83, 0xffff0000, v83
	v_and_b32_e32 v82, 0xffff0000, v82
	v_pk_mul_f32 v[106:107], v[80:81], v[80:81]
	v_pk_mul_f32 v[110:111], v[82:83], v[82:83]
	v_mul_f32_e32 v116, v92, v92
	v_mul_f32_e32 v117, v93, v93
	v_pk_add_f32 v[98:99], v[98:99], v[98:99] op_sel:[0,1] op_sel_hi:[1,0]
	v_pk_add_f32 v[102:103], v[102:103], v[102:103] op_sel:[0,1] op_sel_hi:[1,0]
	v_lshlrev_b32_e32 v88, 16, v89
	v_and_b32_e32 v89, 0xffff0000, v89
	v_pk_fma_f32 v[106:107], v[104:105], v[104:105], v[106:107]
	v_pk_fma_f32 v[110:111], v[108:109], v[108:109], v[110:111]
	v_mov_b32_e32 v99, v116
	v_mov_b32_e32 v103, v117
	v_mul_f32_e32 v118, v88, v88
	v_mul_f32_e32 v119, v89, v89
	v_pk_add_f32 v[98:99], v[98:99], v[102:103]
	v_pk_add_f32 v[102:103], v[106:107], v[106:107] op_sel:[0,1] op_sel_hi:[1,0]
	v_pk_add_f32 v[106:107], v[110:111], v[110:111] op_sel:[0,1] op_sel_hi:[1,0]
	v_mov_b32_e32 v103, v118
	v_mov_b32_e32 v107, v119
	v_lshlrev_b32_e32 v112, 16, v84
	v_and_b32_e32 v113, 0xffff0000, v84
	v_lshlrev_b32_e32 v84, 16, v85
	v_and_b32_e32 v85, 0xffff0000, v85
	v_pk_add_f32 v[102:103], v[102:103], v[106:107]
	v_lshlrev_b32_e32 v94, 16, v90
	v_and_b32_e32 v95, 0xffff0000, v90
	v_pk_add_f32 v[98:99], v[98:99], v[102:103]
	v_mul_f32_e32 v102, v113, v113
	v_mul_f32_e32 v106, v85, v85
	v_mul_f32_e32 v120, v94, v94
	v_mul_f32_e32 v121, v95, v95
	v_pk_fma_f32 v[102:103], v[112:113], v[112:113], v[102:103] op_sel_hi:[1,1,0]
	v_pk_fma_f32 v[106:107], v[84:85], v[84:85], v[106:107] op_sel_hi:[1,1,0]
	v_lshlrev_b32_e32 v114, 16, v86
	v_and_b32_e32 v115, 0xffff0000, v86
	v_lshlrev_b32_e32 v86, 16, v87
	v_and_b32_e32 v87, 0xffff0000, v87
	v_mov_b32_e32 v103, v120
	v_mov_b32_e32 v107, v121
	v_lshlrev_b32_e32 v90, 16, v91
	v_and_b32_e32 v91, 0xffff0000, v91
	v_pk_add_f32 v[102:103], v[102:103], v[106:107]
	v_mul_f32_e32 v106, v115, v115
	v_mul_f32_e32 v110, v87, v87
	v_mul_f32_e32 v122, v90, v90
	v_mul_f32_e32 v123, v91, v91
	v_pk_fma_f32 v[106:107], v[114:115], v[114:115], v[106:107] op_sel_hi:[1,1,0]
	v_pk_fma_f32 v[110:111], v[86:87], v[86:87], v[110:111] op_sel_hi:[1,1,0]
	v_mov_b32_e32 v107, v122
	v_mov_b32_e32 v111, v123
	v_pk_add_f32 v[106:107], v[106:107], v[110:111]
	s_nop 0
	v_pk_add_f32 v[102:103], v[102:103], v[106:107]
	s_nop 0
	v_pk_add_f32 v[98:99], v[98:99], v[102:103]
	s_nop 0
	v_add_f32_e32 v98, v98, v99
	v_mbcnt_lo_u32_b32 v99, -1, 0
	v_mbcnt_hi_u32_b32 v99, -1, v99
	s_nop 0
	v_lshlrev_b32_e32 v99, 2, v99
	v_xor_b32_e32 v99, 4, v99
	ds_bpermute_b32 v99, v99, v98
	s_waitcnt lgkmcnt(0)
; __device__ __forceinline__ v4u pk8(f32x4 a, f32x4 b) { v4u w; w.x = pk2(a[0], a[1]); w.y = pk2(a[2], a[3]); w.z = pk2(b[0], b[1]); w.w = pk2(b[2], b[3]); return w; }
; __device__ __forceinline__ float shfl_xor_f(float v, int o) {
;     int l; asm volatile("v_mbcnt_lo_u32_b32 %0, -1, 0\n\tv_mbcnt_hi_u32_b32 %0, -1, %0" : "=v"(l));
;     return __builtin_bit_cast(float, __builtin_amdgcn_ds_bpermute((l ^ o) << 2, __builtin_bit_cast(int, v)));
; }
; __device__ __forceinline__ float wave_sum(float v) {
; #pragma unroll
;     for (int o = 1; o < 64; o <<= 1) v += shfl_xor_f(v, o);
;     return v;
; template <int XF32> __device__ __forceinline__ void norm_mod_phase(const void* x, const float* modl, int ch_shift, int ch_scale, bf16* H, int gw, int NGW, int lane) {
;     ...
;             const float rstd = 1.f / sqrtf(wave_sum(s) * (1.f / DM) + EPS);
;             v4u* o = (v4u*)(H + (size_t)(r0 + rr) * DM);
; #pragma unroll
;             for (int j = 0; j < 4; ++j) o[lane + 64 * j] = pk8(v[j][0] * rstd * sc[j][0] + sh[j][0], v[j][1] * rstd * sc[j][1] + sh[j][1]);
	v_add_f32_e32 v98, v98, v99
	v_mbcnt_lo_u32_b32 v99, -1, 0
	v_mbcnt_hi_u32_b32 v99, -1, v99
	s_nop 0
	v_lshlrev_b32_e32 v99, 2, v99
	v_xor_b32_e32 v99, 8, v99
	ds_bpermute_b32 v99, v99, v98
	s_waitcnt lgkmcnt(0)
	v_add_f32_e32 v98, v98, v99
	v_mbcnt_lo_u32_b32 v99, -1, 0
	v_mbcnt_hi_u32_b32 v99, -1, v99
	s_nop 0
	v_lshlrev_b32_e32 v99, 2, v99
	v_xor_b32_e32 v99, 16, v99
	ds_bpermute_b32 v99, v99, v98
	s_waitcnt lgkmcnt(0)
	v_add_f32_e32 v98, v98, v99
	v_mbcnt_lo_u32_b32 v99, -1, 0
	v_mbcnt_hi_u32_b32 v99, -1, v99
	s_nop 0
	v_lshlrev_b32_e32 v99, 2, v99
	v_xor_b32_e32 v99, 32, v99
	ds_bpermute_b32 v99, v99, v98
	s_waitcnt lgkmcnt(0)
	v_add_f32_e32 v98, v98, v99
	v_mbcnt_lo_u32_b32 v99, -1, 0
	v_mbcnt_hi_u32_b32 v99, -1, v99
	s_nop 0
	v_lshlrev_b32_e32 v99, 2, v99
	v_xor_b32_e32 v99, 64, v99
	ds_bpermute_b32 v99, v99, v98
	s_waitcnt lgkmcnt(0)
	v_add_f32_e32 v98, v98, v99
	v_mbcnt_lo_u32_b32 v99, -1, 0
	v_mbcnt_hi_u32_b32 v99, -1, v99
	s_nop 0
	v_lshlrev_b32_e32 v99, 2, v99
	v_xor_b32_e32 v99, 0x80, v99
	ds_bpermute_b32 v99, v99, v98
	s_waitcnt lgkmcnt(0)
	v_add_f32_e32 v98, v98, v99
	v_fmamk_f32 v98, v98, 0x3a000000, v224
	v_cmp_gt_f32_e32 vcc, s41, v98
	v_mul_f32_e32 v99, 0x4f800000, v98
	s_nop 0
	v_cndmask_b32_e32 v98, v98, v99, vcc
	v_sqrt_f32_e32 v99, v98
	s_nop 0
	v_add_u32_e32 v102, -1, v99
	v_fma_f32 v103, -v102, v99, v98
	v_cmp_ge_f32_e64 s[4:5], 0, v103
	v_add_u32_e32 v103, 1, v99
	s_nop 0
	v_cndmask_b32_e64 v102, v99, v102, s[4:5]
	v_fma_f32 v99, -v103, v99, v98
	v_cmp_lt_f32_e64 s[4:5], 0, v99
	s_nop 1
	v_cndmask_b32_e64 v99, v102, v103, s[4:5]
	v_mul_f32_e32 v102, 0x37800000, v99
	v_cndmask_b32_e32 v99, v99, v102, vcc
	v_cmp_class_f32_e32 vcc, v98, v225
	s_nop 1
	v_cndmask_b32_e32 v98, v99, v98, vcc
	v_div_scale_f32 v99, s[0:1], v98, v98, 1.0
	v_rcp_f32_e32 v102, v99
	s_add_i32 s0, s8, -2
	s_ashr_i32 s1, s0, 31
	v_fma_f32 v103, -v99, v102, 1.0
	v_fmac_f32_e32 v102, v103, v102
	v_div_scale_f32 v103, vcc, 1.0, v98, 1.0
	v_mul_f32_e32 v106, v103, v102
	v_fma_f32 v107, -v99, v106, v103
	v_fmac_f32_e32 v106, v107, v102
	v_fma_f32 v99, -v99, v106, v103
	v_div_fmas_f32 v99, v99, v102, v106
	v_div_fixup_f32 v98, v99, v98, 1.0
	v_mov_b32_e32 v102, v96
	v_mov_b32_e32 v103, v76
	v_mov_b32_e32 v76, v97
	v_pk_mul_f32 v[102:103], v[98:99], v[102:103] op_sel_hi:[0,1]
	v_pk_mul_f32 v[76:77], v[98:99], v[76:77] op_sel_hi:[0,1]
	v_pk_fma_f32 v[96:97], v[56:57], v[76:77], v[14:15]
	v_pk_fma_f32 v[76:77], v[58:59], v[102:103], v[12:13]
	v_mov_b32_e32 v102, v100
	v_mov_b32_e32 v103, v78
	v_mov_b32_e32 v78, v101
	v_pk_mul_f32 v[102:103], v[98:99], v[102:103] op_sel_hi:[0,1]
	v_pk_mul_f32 v[78:79], v[98:99], v[78:79] op_sel_hi:[0,1]
	v_pk_fma_f32 v[100:101], v[52:53], v[78:79], v[10:11]
	v_pk_fma_f32 v[78:79], v[54:55], v[102:103], v[8:9]
	v_cvt_pk_bf16_f32 v76, v76, v77
	v_cvt_pk_bf16_f32 v77, v96, v97
	v_cvt_pk_bf16_f32 v78, v78, v79
	v_cvt_pk_bf16_f32 v79, v100, v101
	v_lshl_add_u64 v[96:97], v[36:37], 0, s[64:65]
	global_store_dwordx4 v[96:97], v[76:79], off
	s_lshl_b64 s[64:65], s[0:1], 12
	s_nop 0
	v_mov_b32_e32 v77, v80
	v_mov_b32_e32 v80, v105
	v_mov_b32_e32 v76, v104
	v_pk_mul_f32 v[78:79], v[98:99], v[80:81] op_sel_hi:[0,1]
	v_mov_b32_e32 v80, v108
	v_mov_b32_e32 v81, v82
	v_mov_b32_e32 v82, v109
	v_pk_mul_f32 v[76:77], v[98:99], v[76:77] op_sel_hi:[0,1]
	v_pk_mul_f32 v[80:81], v[98:99], v[80:81] op_sel_hi:[0,1]
	v_pk_mul_f32 v[82:83], v[98:99], v[82:83] op_sel_hi:[0,1]
	v_pk_fma_f32 v[78:79], v[48:49], v[78:79], v[6:7]
	v_pk_fma_f32 v[76:77], v[50:51], v[76:77], v[4:5]
	v_pk_fma_f32 v[82:83], v[44:45], v[82:83], v[2:3]
	v_pk_fma_f32 v[80:81], v[46:47], v[80:81], v[0:1]
	v_cvt_pk_bf16_f32 v76, v76, v77
	v_cvt_pk_bf16_f32 v77, v78, v79
	v_cvt_pk_bf16_f32 v78, v80, v81
	v_cvt_pk_bf16_f32 v79, v82, v83
	global_store_dwordx4 v[96:97], v[76:79], off offset:1024
	v_pk_mul_f32 v[80:81], v[98:99], v[114:115] op_sel_hi:[0,1]
	v_pk_mul_f32 v[82:83], v[98:99], v[86:87] op_sel_hi:[0,1]
	v_pk_mul_f32 v[76:77], v[98:99], v[112:113] op_sel_hi:[0,1]
	v_pk_mul_f32 v[78:79], v[98:99], v[84:85] op_sel_hi:[0,1]
	v_pk_fma_f32 v[78:79], v[64:65], v[78:79], v[22:23]
	v_pk_fma_f32 v[76:77], v[66:67], v[76:77], v[20:21]
	v_pk_fma_f32 v[82:83], v[60:61], v[82:83], v[18:19]
	v_pk_fma_f32 v[80:81], v[62:63], v[80:81], v[16:17]
	v_cvt_pk_bf16_f32 v76, v76, v77
	v_cvt_pk_bf16_f32 v77, v78, v79
	v_cvt_pk_bf16_f32 v78, v80, v81
	v_cvt_pk_bf16_f32 v79, v82, v83
	global_store_dwordx4 v[96:97], v[76:79], off offset:2048
	v_pk_mul_f32 v[80:81], v[94:95], v[98:99] op_sel_hi:[1,0]
	v_pk_mul_f32 v[82:83], v[90:91], v[98:99] op_sel_hi:[1,0]
	v_pk_mul_f32 v[76:77], v[92:93], v[98:99] op_sel_hi:[1,0]
	v_pk_mul_f32 v[78:79], v[88:89], v[98:99] op_sel_hi:[1,0]
	v_pk_fma_f32 v[76:77], v[74:75], v[76:77], v[28:29]
	v_pk_fma_f32 v[78:79], v[72:73], v[78:79], v[30:31]
	v_pk_fma_f32 v[82:83], v[68:69], v[82:83], v[26:27]
	v_pk_fma_f32 v[80:81], v[70:71], v[80:81], v[24:25]
	v_cvt_pk_bf16_f32 v76, v76, v77
	v_cvt_pk_bf16_f32 v77, v78, v79
	v_cvt_pk_bf16_f32 v78, v80, v81
	v_cvt_pk_bf16_f32 v79, v82, v83
	global_store_dwordx4 v[96:97], v[76:79], off offset:3072
	v_lshl_add_u64 v[88:89], v[34:35], 0, s[64:65]
	global_load_dwordx4 v[76:79], v[88:89], off
	global_load_dwordx4 v[80:83], v[88:89], off offset:1024
	global_load_dwordx4 v[84:87], v[88:89], off offset:2048
	s_nop 0
	global_load_dwordx4 v[88:91], v[88:89], off offset:3072
	s_waitcnt vmcnt(3)
	v_lshlrev_b32_e32 v97, 16, v77
	v_lshlrev_b32_e32 v96, 16, v76
	v_and_b32_e32 v77, 0xffff0000, v77
	v_and_b32_e32 v76, 0xffff0000, v76
	v_lshlrev_b32_e32 v101, 16, v79
	v_lshlrev_b32_e32 v100, 16, v78
	v_and_b32_e32 v79, 0xffff0000, v79
	v_and_b32_e32 v78, 0xffff0000, v78
	v_pk_mul_f32 v[98:99], v[76:77], v[76:77]
	v_pk_mul_f32 v[102:103], v[78:79], v[78:79]
	s_waitcnt vmcnt(0)
; __device__ __forceinline__ v4u pk8(f32x4 a, f32x4 b) { v4u w; w.x = pk2(a[0], a[1]); w.y = pk2(a[2], a[3]); w.z = pk2(b[0], b[1]); w.w = pk2(b[2], b[3]); return w; }
; __device__ __forceinline__ float ssq8(const f32x4& a, const f32x4& b) { return ((a[0] * a[0] + a[1] * a[1]) + (a[2] * a[2] + a[3] * a[3])) + ((b[0] * b[0] + b[1] * b[1]) + (b[2] * b[2] + b[3] * b[3])); }
; __device__ __forceinline__ float shfl_xor_f(float v, int o) {
;     int l; asm volatile("v_mbcnt_lo_u32_b32 %0, -1, 0\n\tv_mbcnt_hi_u32_b32 %0, -1, %0" : "=v"(l));
;     return __builtin_bit_cast(float, __builtin_amdgcn_ds_bpermute((l ^ o) << 2, __builtin_bit_cast(int, v)));
; }
; __device__ __forceinline__ float wave_sum(float v) {
; #pragma unroll
;     for (int o = 1; o < 64; o <<= 1) v += shfl_xor_f(v, o);
;     return v;
; template <int XF32> __device__ __forceinline__ void norm_mod_phase(const void* x, const float* modl, int ch_shift, int ch_scale, bf16* H, int gw, int NGW, int lane) {
;     ...
;         for (int rr = 0; rr < 8; ++rr) {
;             const unsigned char* xr = (const unsigned char*)x + (size_t)(r0 + rr) * rowb; f32x4 v[4][2]; float s = 0.f;
; #pragma unroll
;             for (int j = 0; j < 4; ++j) ld_row8<XF32>(xr, lane, j, v[j][0], v[j][1]);
; #pragma unroll
;             for (int j = 0; j < 4; ++j) s += ssq8(v[j][0], v[j][1]);
;             const float rstd = 1.f / sqrtf(wave_sum(s) * (1.f / DM) + EPS);
;             v4u* o = (v4u*)(H + (size_t)(r0 + rr) * DM);
; #pragma unroll
;             for (int j = 0; j < 4; ++j) o[lane + 64 * j] = pk8(v[j][0] * rstd * sc[j][0] + sh[j][0], v[j][1] * rstd * sc[j][1] + sh[j][1]);
	v_lshlrev_b32_e32 v92, 16, v88
	v_and_b32_e32 v93, 0xffff0000, v88
	v_pk_fma_f32 v[98:99], v[96:97], v[96:97], v[98:99]
	v_pk_fma_f32 v[102:103], v[100:101], v[100:101], v[102:103]
	v_lshlrev_b32_e32 v105, 16, v81
	v_lshlrev_b32_e32 v104, 16, v80
	v_and_b32_e32 v81, 0xffff0000, v81
	v_and_b32_e32 v80, 0xffff0000, v80
	v_lshlrev_b32_e32 v109, 16, v83
	v_lshlrev_b32_e32 v108, 16, v82
	v_and_b32_e32 v83, 0xffff0000, v83
	v_and_b32_e32 v82, 0xffff0000, v82
	v_pk_mul_f32 v[106:107], v[80:81], v[80:81]
	v_pk_mul_f32 v[110:111], v[82:83], v[82:83]
	v_mul_f32_e32 v116, v92, v92
	v_mul_f32_e32 v117, v93, v93
	v_pk_add_f32 v[98:99], v[98:99], v[98:99] op_sel:[0,1] op_sel_hi:[1,0]
	v_pk_add_f32 v[102:103], v[102:103], v[102:103] op_sel:[0,1] op_sel_hi:[1,0]
	v_lshlrev_b32_e32 v88, 16, v89
	v_and_b32_e32 v89, 0xffff0000, v89
	v_pk_fma_f32 v[106:107], v[104:105], v[104:105], v[106:107]
	v_pk_fma_f32 v[110:111], v[108:109], v[108:109], v[110:111]
	v_mov_b32_e32 v99, v116
	v_mov_b32_e32 v103, v117
	v_mul_f32_e32 v118, v88, v88
	v_mul_f32_e32 v119, v89, v89
	v_pk_add_f32 v[98:99], v[98:99], v[102:103]
	v_pk_add_f32 v[102:103], v[106:107], v[106:107] op_sel:[0,1] op_sel_hi:[1,0]
	v_pk_add_f32 v[106:107], v[110:111], v[110:111] op_sel:[0,1] op_sel_hi:[1,0]
	v_mov_b32_e32 v103, v118
	v_mov_b32_e32 v107, v119
	v_lshlrev_b32_e32 v112, 16, v84
	v_and_b32_e32 v113, 0xffff0000, v84
	v_lshlrev_b32_e32 v84, 16, v85
	v_and_b32_e32 v85, 0xffff0000, v85
	v_pk_add_f32 v[102:103], v[102:103], v[106:107]
	v_lshlrev_b32_e32 v94, 16, v90
	v_and_b32_e32 v95, 0xffff0000, v90
	v_pk_add_f32 v[98:99], v[98:99], v[102:103]
	v_mul_f32_e32 v102, v113, v113
	v_mul_f32_e32 v106, v85, v85
	v_mul_f32_e32 v120, v94, v94
	v_mul_f32_e32 v121, v95, v95
	v_pk_fma_f32 v[102:103], v[112:113], v[112:113], v[102:103] op_sel_hi:[1,1,0]
	v_pk_fma_f32 v[106:107], v[84:85], v[84:85], v[106:107] op_sel_hi:[1,1,0]
	v_lshlrev_b32_e32 v114, 16, v86
	v_and_b32_e32 v115, 0xffff0000, v86
	v_lshlrev_b32_e32 v86, 16, v87
	v_and_b32_e32 v87, 0xffff0000, v87
	v_mov_b32_e32 v103, v120
	v_mov_b32_e32 v107, v121
	v_lshlrev_b32_e32 v90, 16, v91
	v_and_b32_e32 v91, 0xffff0000, v91
	v_pk_add_f32 v[102:103], v[102:103], v[106:107]
	v_mul_f32_e32 v106, v115, v115
	v_mul_f32_e32 v110, v87, v87
	v_mul_f32_e32 v122, v90, v90
	v_mul_f32_e32 v123, v91, v91
	v_pk_fma_f32 v[106:107], v[114:115], v[114:115], v[106:107] op_sel_hi:[1,1,0]
	v_pk_fma_f32 v[110:111], v[86:87], v[86:87], v[110:111] op_sel_hi:[1,1,0]
	v_mov_b32_e32 v107, v122
	v_mov_b32_e32 v111, v123
	v_pk_add_f32 v[106:107], v[106:107], v[110:111]
	s_nop 0
	v_pk_add_f32 v[102:103], v[102:103], v[106:107]
	s_nop 0
	v_pk_add_f32 v[98:99], v[98:99], v[102:103]
	s_nop 0
	v_add_f32_e32 v98, v98, v99
	v_mbcnt_lo_u32_b32 v99, -1, 0
	v_mbcnt_hi_u32_b32 v99, -1, v99
	s_nop 0
	v_lshlrev_b32_e32 v99, 2, v99
	v_xor_b32_e32 v99, 4, v99
	ds_bpermute_b32 v99, v99, v98
	s_waitcnt lgkmcnt(0)
	v_add_f32_e32 v98, v98, v99
	v_mbcnt_lo_u32_b32 v99, -1, 0
	v_mbcnt_hi_u32_b32 v99, -1, v99
	s_nop 0
	v_lshlrev_b32_e32 v99, 2, v99
	v_xor_b32_e32 v99, 8, v99
	ds_bpermute_b32 v99, v99, v98
	s_waitcnt lgkmcnt(0)
	v_add_f32_e32 v98, v98, v99
	v_mbcnt_lo_u32_b32 v99, -1, 0
	v_mbcnt_hi_u32_b32 v99, -1, v99
	s_nop 0
	v_lshlrev_b32_e32 v99, 2, v99
	v_xor_b32_e32 v99, 16, v99
	ds_bpermute_b32 v99, v99, v98
	s_waitcnt lgkmcnt(0)
	v_add_f32_e32 v98, v98, v99
	v_mbcnt_lo_u32_b32 v99, -1, 0
	v_mbcnt_hi_u32_b32 v99, -1, v99
	s_nop 0
	v_lshlrev_b32_e32 v99, 2, v99
	v_xor_b32_e32 v99, 32, v99
	ds_bpermute_b32 v99, v99, v98
	s_waitcnt lgkmcnt(0)
	v_add_f32_e32 v98, v98, v99
	v_mbcnt_lo_u32_b32 v99, -1, 0
	v_mbcnt_hi_u32_b32 v99, -1, v99
	s_nop 0
	v_lshlrev_b32_e32 v99, 2, v99
	v_xor_b32_e32 v99, 64, v99
	ds_bpermute_b32 v99, v99, v98
	s_waitcnt lgkmcnt(0)
	v_add_f32_e32 v98, v98, v99
	v_mbcnt_lo_u32_b32 v99, -1, 0
	v_mbcnt_hi_u32_b32 v99, -1, v99
	s_nop 0
	v_lshlrev_b32_e32 v99, 2, v99
	v_xor_b32_e32 v99, 0x80, v99
	ds_bpermute_b32 v99, v99, v98
	s_waitcnt lgkmcnt(0)
	v_add_f32_e32 v98, v98, v99
	v_fmamk_f32 v98, v98, 0x3a000000, v224
	v_cmp_gt_f32_e32 vcc, s41, v98
	v_mul_f32_e32 v99, 0x4f800000, v98
	s_nop 0
	v_cndmask_b32_e32 v98, v98, v99, vcc
	v_sqrt_f32_e32 v99, v98
	s_nop 0
	v_add_u32_e32 v102, -1, v99
	v_fma_f32 v103, -v102, v99, v98
	v_cmp_ge_f32_e64 s[4:5], 0, v103
	v_add_u32_e32 v103, 1, v99
	s_nop 0
	v_cndmask_b32_e64 v102, v99, v102, s[4:5]
	v_fma_f32 v99, -v103, v99, v98
	v_cmp_lt_f32_e64 s[4:5], 0, v99
	s_nop 1
	v_cndmask_b32_e64 v99, v102, v103, s[4:5]
	v_mul_f32_e32 v102, 0x37800000, v99
	v_cndmask_b32_e32 v99, v99, v102, vcc
	v_cmp_class_f32_e32 vcc, v98, v225
	s_nop 1
	v_cndmask_b32_e32 v98, v99, v98, vcc
	v_div_scale_f32 v99, s[0:1], v98, v98, 1.0
	v_rcp_f32_e32 v102, v99
	s_add_i32 s0, s8, -1
	s_ashr_i32 s1, s0, 31
	v_fma_f32 v103, -v99, v102, 1.0
	v_fmac_f32_e32 v102, v103, v102
	v_div_scale_f32 v103, vcc, 1.0, v98, 1.0
	v_mul_f32_e32 v106, v103, v102
	v_fma_f32 v107, -v99, v106, v103
	v_fmac_f32_e32 v106, v107, v102
	v_fma_f32 v99, -v99, v106, v103
	v_div_fmas_f32 v99, v99, v102, v106
	v_div_fixup_f32 v98, v99, v98, 1.0
	v_mov_b32_e32 v102, v96
	v_mov_b32_e32 v103, v76
	v_mov_b32_e32 v76, v97
	v_pk_mul_f32 v[102:103], v[98:99], v[102:103] op_sel_hi:[0,1]
	v_pk_mul_f32 v[76:77], v[98:99], v[76:77] op_sel_hi:[0,1]
	v_pk_fma_f32 v[96:97], v[56:57], v[76:77], v[14:15]
	v_pk_fma_f32 v[76:77], v[58:59], v[102:103], v[12:13]
	v_mov_b32_e32 v102, v100
	v_mov_b32_e32 v103, v78
	v_mov_b32_e32 v78, v101
	v_pk_mul_f32 v[102:103], v[98:99], v[102:103] op_sel_hi:[0,1]
	v_pk_mul_f32 v[78:79], v[98:99], v[78:79] op_sel_hi:[0,1]
	v_pk_fma_f32 v[100:101], v[52:53], v[78:79], v[10:11]
; __device__ __forceinline__ v4u pk8(f32x4 a, f32x4 b) { v4u w; w.x = pk2(a[0], a[1]); w.y = pk2(a[2], a[3]); w.z = pk2(b[0], b[1]); w.w = pk2(b[2], b[3]); return w; }
; __device__ __forceinline__ float ssq8(const f32x4& a, const f32x4& b) { return ((a[0] * a[0] + a[1] * a[1]) + (a[2] * a[2] + a[3] * a[3])) + ((b[0] * b[0] + b[1] * b[1]) + (b[2] * b[2] + b[3] * b[3])); }
; template <int XF32> __device__ __forceinline__ void norm_mod_phase(const void* x, const float* modl, int ch_shift, int ch_scale, bf16* H, int gw, int NGW, int lane) {
;     ...
;         for (int rr = 0; rr < 8; ++rr) {
;             const unsigned char* xr = (const unsigned char*)x + (size_t)(r0 + rr) * rowb; f32x4 v[4][2]; float s = 0.f;
; #pragma unroll
;             for (int j = 0; j < 4; ++j) ld_row8<XF32>(xr, lane, j, v[j][0], v[j][1]);
; #pragma unroll
;             for (int j = 0; j < 4; ++j) s += ssq8(v[j][0], v[j][1]);
;             const float rstd = 1.f / sqrtf(wave_sum(s) * (1.f / DM) + EPS);
;             v4u* o = (v4u*)(H + (size_t)(r0 + rr) * DM);
; #pragma unroll
;             for (int j = 0; j < 4; ++j) o[lane + 64 * j] = pk8(v[j][0] * rstd * sc[j][0] + sh[j][0], v[j][1] * rstd * sc[j][1] + sh[j][1]);
	v_pk_fma_f32 v[78:79], v[54:55], v[102:103], v[8:9]
	v_cvt_pk_bf16_f32 v76, v76, v77
	v_cvt_pk_bf16_f32 v77, v96, v97
	v_cvt_pk_bf16_f32 v78, v78, v79
	v_cvt_pk_bf16_f32 v79, v100, v101
	v_lshl_add_u64 v[96:97], v[36:37], 0, s[64:65]
	global_store_dwordx4 v[96:97], v[76:79], off
	s_lshl_b64 s[64:65], s[0:1], 12
	s_nop 0
	v_mov_b32_e32 v77, v80
	v_mov_b32_e32 v80, v105
	v_mov_b32_e32 v76, v104
	v_pk_mul_f32 v[78:79], v[98:99], v[80:81] op_sel_hi:[0,1]
	v_mov_b32_e32 v80, v108
	v_mov_b32_e32 v81, v82
	v_mov_b32_e32 v82, v109
	v_pk_mul_f32 v[76:77], v[98:99], v[76:77] op_sel_hi:[0,1]
	v_pk_mul_f32 v[80:81], v[98:99], v[80:81] op_sel_hi:[0,1]
	v_pk_mul_f32 v[82:83], v[98:99], v[82:83] op_sel_hi:[0,1]
	v_pk_fma_f32 v[78:79], v[48:49], v[78:79], v[6:7]
	v_pk_fma_f32 v[76:77], v[50:51], v[76:77], v[4:5]
	v_pk_fma_f32 v[82:83], v[44:45], v[82:83], v[2:3]
	v_pk_fma_f32 v[80:81], v[46:47], v[80:81], v[0:1]
	v_cvt_pk_bf16_f32 v76, v76, v77
	v_cvt_pk_bf16_f32 v77, v78, v79
	v_cvt_pk_bf16_f32 v78, v80, v81
	v_cvt_pk_bf16_f32 v79, v82, v83
	global_store_dwordx4 v[96:97], v[76:79], off offset:1024
	v_pk_mul_f32 v[80:81], v[98:99], v[114:115] op_sel_hi:[0,1]
	v_pk_mul_f32 v[82:83], v[98:99], v[86:87] op_sel_hi:[0,1]
	v_pk_mul_f32 v[76:77], v[98:99], v[112:113] op_sel_hi:[0,1]
	v_pk_mul_f32 v[78:79], v[98:99], v[84:85] op_sel_hi:[0,1]
	v_pk_fma_f32 v[78:79], v[64:65], v[78:79], v[22:23]
	v_pk_fma_f32 v[76:77], v[66:67], v[76:77], v[20:21]
	v_pk_fma_f32 v[82:83], v[60:61], v[82:83], v[18:19]
	v_pk_fma_f32 v[80:81], v[62:63], v[80:81], v[16:17]
	v_cvt_pk_bf16_f32 v76, v76, v77
	v_cvt_pk_bf16_f32 v77, v78, v79
	v_cvt_pk_bf16_f32 v78, v80, v81
	v_cvt_pk_bf16_f32 v79, v82, v83
	global_store_dwordx4 v[96:97], v[76:79], off offset:2048
	v_pk_mul_f32 v[80:81], v[94:95], v[98:99] op_sel_hi:[1,0]
	v_pk_mul_f32 v[82:83], v[90:91], v[98:99] op_sel_hi:[1,0]
	v_pk_mul_f32 v[76:77], v[92:93], v[98:99] op_sel_hi:[1,0]
	v_pk_mul_f32 v[78:79], v[88:89], v[98:99] op_sel_hi:[1,0]
	v_pk_fma_f32 v[76:77], v[74:75], v[76:77], v[28:29]
	v_pk_fma_f32 v[78:79], v[72:73], v[78:79], v[30:31]
	v_pk_fma_f32 v[82:83], v[68:69], v[82:83], v[26:27]
	v_pk_fma_f32 v[80:81], v[70:71], v[80:81], v[24:25]
	v_cvt_pk_bf16_f32 v76, v76, v77
	v_cvt_pk_bf16_f32 v77, v78, v79
	v_cvt_pk_bf16_f32 v78, v80, v81
	v_cvt_pk_bf16_f32 v79, v82, v83
	global_store_dwordx4 v[96:97], v[76:79], off offset:3072
	v_lshl_add_u64 v[88:89], v[34:35], 0, s[64:65]
	global_load_dwordx4 v[76:79], v[88:89], off
	global_load_dwordx4 v[80:83], v[88:89], off offset:1024
	global_load_dwordx4 v[84:87], v[88:89], off offset:2048
	s_nop 0
	global_load_dwordx4 v[88:91], v[88:89], off offset:3072
	s_waitcnt vmcnt(3)
	v_lshlrev_b32_e32 v97, 16, v77
	v_lshlrev_b32_e32 v96, 16, v76
	v_and_b32_e32 v77, 0xffff0000, v77
	v_and_b32_e32 v76, 0xffff0000, v76
	v_lshlrev_b32_e32 v101, 16, v79
	v_lshlrev_b32_e32 v100, 16, v78
	v_and_b32_e32 v79, 0xffff0000, v79
	v_and_b32_e32 v78, 0xffff0000, v78
	v_pk_mul_f32 v[98:99], v[76:77], v[76:77]
	v_pk_mul_f32 v[102:103], v[78:79], v[78:79]
	s_waitcnt vmcnt(0)
	v_lshlrev_b32_e32 v92, 16, v88
	v_and_b32_e32 v93, 0xffff0000, v88
	v_pk_fma_f32 v[98:99], v[96:97], v[96:97], v[98:99]
	v_pk_fma_f32 v[102:103], v[100:101], v[100:101], v[102:103]
	v_lshlrev_b32_e32 v105, 16, v81
	v_lshlrev_b32_e32 v104, 16, v80
	v_and_b32_e32 v81, 0xffff0000, v81
	v_and_b32_e32 v80, 0xffff0000, v80
	v_lshlrev_b32_e32 v109, 16, v83
	v_lshlrev_b32_e32 v108, 16, v82
	v_and_b32_e32 v83, 0xffff0000, v83
	v_and_b32_e32 v82, 0xffff0000, v82
	v_pk_mul_f32 v[106:107], v[80:81], v[80:81]
	v_pk_mul_f32 v[110:111], v[82:83], v[82:83]
	v_mul_f32_e32 v116, v92, v92
	v_mul_f32_e32 v117, v93, v93
	v_pk_add_f32 v[98:99], v[98:99], v[98:99] op_sel:[0,1] op_sel_hi:[1,0]
	v_pk_add_f32 v[102:103], v[102:103], v[102:103] op_sel:[0,1] op_sel_hi:[1,0]
	v_lshlrev_b32_e32 v88, 16, v89
	v_and_b32_e32 v89, 0xffff0000, v89
	v_pk_fma_f32 v[106:107], v[104:105], v[104:105], v[106:107]
	v_pk_fma_f32 v[110:111], v[108:109], v[108:109], v[110:111]
	v_mov_b32_e32 v99, v116
	v_mov_b32_e32 v103, v117
	v_mul_f32_e32 v118, v88, v88
	v_mul_f32_e32 v119, v89, v89
	v_pk_add_f32 v[98:99], v[98:99], v[102:103]
	v_pk_add_f32 v[102:103], v[106:107], v[106:107] op_sel:[0,1] op_sel_hi:[1,0]
	v_pk_add_f32 v[106:107], v[110:111], v[110:111] op_sel:[0,1] op_sel_hi:[1,0]
	v_mov_b32_e32 v103, v118
	v_mov_b32_e32 v107, v119
	v_lshlrev_b32_e32 v112, 16, v84
	v_and_b32_e32 v113, 0xffff0000, v84
	v_lshlrev_b32_e32 v84, 16, v85
	v_and_b32_e32 v85, 0xffff0000, v85
	v_pk_add_f32 v[102:103], v[102:103], v[106:107]
	v_lshlrev_b32_e32 v94, 16, v90
	v_and_b32_e32 v95, 0xffff0000, v90
	v_pk_add_f32 v[98:99], v[98:99], v[102:103]
	v_mul_f32_e32 v102, v113, v113
	v_mul_f32_e32 v106, v85, v85
	v_mul_f32_e32 v120, v94, v94
	v_mul_f32_e32 v121, v95, v95
	v_pk_fma_f32 v[102:103], v[112:113], v[112:113], v[102:103] op_sel_hi:[1,1,0]
	v_pk_fma_f32 v[106:107], v[84:85], v[84:85], v[106:107] op_sel_hi:[1,1,0]
	v_lshlrev_b32_e32 v114, 16, v86
	v_and_b32_e32 v115, 0xffff0000, v86
	v_lshlrev_b32_e32 v86, 16, v87
	v_and_b32_e32 v87, 0xffff0000, v87
	v_mov_b32_e32 v103, v120
	v_mov_b32_e32 v107, v121
	v_lshlrev_b32_e32 v90, 16, v91
	v_and_b32_e32 v91, 0xffff0000, v91
	v_pk_add_f32 v[102:103], v[102:103], v[106:107]
	v_mul_f32_e32 v106, v115, v115
	v_mul_f32_e32 v110, v87, v87
	v_mul_f32_e32 v122, v90, v90
	v_mul_f32_e32 v123, v91, v91
	v_pk_fma_f32 v[106:107], v[114:115], v[114:115], v[106:107] op_sel_hi:[1,1,0]
	v_pk_fma_f32 v[110:111], v[86:87], v[86:87], v[110:111] op_sel_hi:[1,1,0]
	v_mov_b32_e32 v107, v122
	v_mov_b32_e32 v111, v123
	v_pk_add_f32 v[106:107], v[106:107], v[110:111]
	s_nop 0
	v_pk_add_f32 v[102:103], v[102:103], v[106:107]
	s_nop 0
	v_pk_add_f32 v[98:99], v[98:99], v[102:103]
	s_nop 0
	v_add_f32_e32 v98, v98, v99
	v_mbcnt_lo_u32_b32 v99, -1, 0
	v_mbcnt_hi_u32_b32 v99, -1, v99
	s_nop 0
	v_lshlrev_b32_e32 v99, 2, v99
	v_xor_b32_e32 v99, 4, v99
	ds_bpermute_b32 v99, v99, v98
	s_waitcnt lgkmcnt(0)
; __device__ __forceinline__ v4u pk8(f32x4 a, f32x4 b) { v4u w; w.x = pk2(a[0], a[1]); w.y = pk2(a[2], a[3]); w.z = pk2(b[0], b[1]); w.w = pk2(b[2], b[3]); return w; }
; __device__ __forceinline__ float shfl_xor_f(float v, int o) {
;     int l; asm volatile("v_mbcnt_lo_u32_b32 %0, -1, 0\n\tv_mbcnt_hi_u32_b32 %0, -1, %0" : "=v"(l));
;     return __builtin_bit_cast(float, __builtin_amdgcn_ds_bpermute((l ^ o) << 2, __builtin_bit_cast(int, v)));
; }
; __device__ __forceinline__ float wave_sum(float v) {
; #pragma unroll
;     for (int o = 1; o < 64; o <<= 1) v += shfl_xor_f(v, o);
;     return v;
; template <int XF32> __device__ __forceinline__ void norm_mod_phase(const void* x, const float* modl, int ch_shift, int ch_scale, bf16* H, int gw, int NGW, int lane) {
;     ...
;             const float rstd = 1.f / sqrtf(wave_sum(s) * (1.f / DM) + EPS);
;             v4u* o = (v4u*)(H + (size_t)(r0 + rr) * DM);
; #pragma unroll
;             for (int j = 0; j < 4; ++j) o[lane + 64 * j] = pk8(v[j][0] * rstd * sc[j][0] + sh[j][0], v[j][1] * rstd * sc[j][1] + sh[j][1]);
	v_add_f32_e32 v98, v98, v99
	v_mbcnt_lo_u32_b32 v99, -1, 0
	v_mbcnt_hi_u32_b32 v99, -1, v99
	s_nop 0
	v_lshlrev_b32_e32 v99, 2, v99
	v_xor_b32_e32 v99, 8, v99
	ds_bpermute_b32 v99, v99, v98
	s_waitcnt lgkmcnt(0)
	v_add_f32_e32 v98, v98, v99
	v_mbcnt_lo_u32_b32 v99, -1, 0
	v_mbcnt_hi_u32_b32 v99, -1, v99
	s_nop 0
	v_lshlrev_b32_e32 v99, 2, v99
	v_xor_b32_e32 v99, 16, v99
	ds_bpermute_b32 v99, v99, v98
	s_waitcnt lgkmcnt(0)
	v_add_f32_e32 v98, v98, v99
	v_mbcnt_lo_u32_b32 v99, -1, 0
	v_mbcnt_hi_u32_b32 v99, -1, v99
	s_nop 0
	v_lshlrev_b32_e32 v99, 2, v99
	v_xor_b32_e32 v99, 32, v99
	ds_bpermute_b32 v99, v99, v98
	s_waitcnt lgkmcnt(0)
	v_add_f32_e32 v98, v98, v99
	v_mbcnt_lo_u32_b32 v99, -1, 0
	v_mbcnt_hi_u32_b32 v99, -1, v99
	s_nop 0
	v_lshlrev_b32_e32 v99, 2, v99
	v_xor_b32_e32 v99, 64, v99
	ds_bpermute_b32 v99, v99, v98
	s_waitcnt lgkmcnt(0)
	v_add_f32_e32 v98, v98, v99
	v_mbcnt_lo_u32_b32 v99, -1, 0
	v_mbcnt_hi_u32_b32 v99, -1, v99
	s_nop 0
	v_lshlrev_b32_e32 v99, 2, v99
	v_xor_b32_e32 v99, 0x80, v99
	ds_bpermute_b32 v99, v99, v98
	s_waitcnt lgkmcnt(0)
	v_add_f32_e32 v98, v98, v99
	v_fmamk_f32 v98, v98, 0x3a000000, v224
	v_cmp_gt_f32_e32 vcc, s41, v98
	v_mul_f32_e32 v99, 0x4f800000, v98
	s_nop 0
	v_cndmask_b32_e32 v98, v98, v99, vcc
	v_sqrt_f32_e32 v99, v98
	s_nop 0
	v_add_u32_e32 v102, -1, v99
	v_fma_f32 v103, -v102, v99, v98
	v_cmp_ge_f32_e64 s[4:5], 0, v103
	v_add_u32_e32 v103, 1, v99
	s_nop 0
	v_cndmask_b32_e64 v102, v99, v102, s[4:5]
	v_fma_f32 v99, -v103, v99, v98
	v_cmp_lt_f32_e64 s[4:5], 0, v99
	s_nop 1
	v_cndmask_b32_e64 v99, v102, v103, s[4:5]
	v_mul_f32_e32 v102, 0x37800000, v99
	v_cndmask_b32_e32 v99, v99, v102, vcc
	v_cmp_class_f32_e32 vcc, v98, v225
	s_nop 1
	v_cndmask_b32_e32 v98, v99, v98, vcc
	v_div_scale_f32 v99, s[0:1], v98, v98, 1.0
	v_rcp_f32_e32 v102, v99
	s_nop 0
	v_fma_f32 v103, -v99, v102, 1.0
	v_fmac_f32_e32 v102, v103, v102
	v_div_scale_f32 v103, vcc, 1.0, v98, 1.0
	v_mul_f32_e32 v106, v103, v102
	v_fma_f32 v107, -v99, v106, v103
	v_fmac_f32_e32 v106, v107, v102
	v_fma_f32 v99, -v99, v106, v103
	v_div_fmas_f32 v99, v99, v102, v106
	v_div_fixup_f32 v98, v99, v98, 1.0
	v_mov_b32_e32 v102, v96
	v_mov_b32_e32 v103, v76
	v_mov_b32_e32 v76, v97
	v_pk_mul_f32 v[102:103], v[98:99], v[102:103] op_sel_hi:[0,1]
	v_pk_mul_f32 v[76:77], v[98:99], v[76:77] op_sel_hi:[0,1]
	v_pk_fma_f32 v[96:97], v[56:57], v[76:77], v[14:15]
	v_pk_fma_f32 v[76:77], v[58:59], v[102:103], v[12:13]
	v_mov_b32_e32 v102, v100
	v_mov_b32_e32 v103, v78
	v_mov_b32_e32 v78, v101
	v_pk_mul_f32 v[102:103], v[98:99], v[102:103] op_sel_hi:[0,1]
	v_pk_mul_f32 v[78:79], v[98:99], v[78:79] op_sel_hi:[0,1]
	v_pk_fma_f32 v[100:101], v[52:53], v[78:79], v[10:11]
	v_pk_fma_f32 v[78:79], v[54:55], v[102:103], v[8:9]
	v_cvt_pk_bf16_f32 v76, v76, v77
	v_cvt_pk_bf16_f32 v77, v96, v97
	v_cvt_pk_bf16_f32 v78, v78, v79
	v_cvt_pk_bf16_f32 v79, v100, v101
	v_lshl_add_u64 v[96:97], v[36:37], 0, s[64:65]
	global_store_dwordx4 v[96:97], v[76:79], off
	s_lshl_b64 s[64:65], s[8:9], 12
	s_add_i32 s8, s8, s2
	v_mov_b32_e32 v77, v80
	v_mov_b32_e32 v80, v105
	v_mov_b32_e32 v76, v104
	v_pk_mul_f32 v[78:79], v[98:99], v[80:81] op_sel_hi:[0,1]
	v_mov_b32_e32 v80, v108
	v_mov_b32_e32 v81, v82
	v_mov_b32_e32 v82, v109
	v_pk_mul_f32 v[76:77], v[98:99], v[76:77] op_sel_hi:[0,1]
	v_pk_mul_f32 v[80:81], v[98:99], v[80:81] op_sel_hi:[0,1]
	v_pk_mul_f32 v[82:83], v[98:99], v[82:83] op_sel_hi:[0,1]
	v_pk_fma_f32 v[78:79], v[48:49], v[78:79], v[6:7]
	v_pk_fma_f32 v[76:77], v[50:51], v[76:77], v[4:5]
	v_pk_fma_f32 v[82:83], v[44:45], v[82:83], v[2:3]
	v_pk_fma_f32 v[80:81], v[46:47], v[80:81], v[0:1]
	v_cvt_pk_bf16_f32 v76, v76, v77
	v_cvt_pk_bf16_f32 v77, v78, v79
	v_cvt_pk_bf16_f32 v78, v80, v81
	v_cvt_pk_bf16_f32 v79, v82, v83
	global_store_dwordx4 v[96:97], v[76:79], off offset:1024
	v_pk_mul_f32 v[80:81], v[98:99], v[114:115] op_sel_hi:[0,1]
	v_pk_mul_f32 v[82:83], v[98:99], v[86:87] op_sel_hi:[0,1]
	v_pk_mul_f32 v[76:77], v[98:99], v[112:113] op_sel_hi:[0,1]
	v_pk_mul_f32 v[78:79], v[98:99], v[84:85] op_sel_hi:[0,1]
	v_pk_fma_f32 v[78:79], v[64:65], v[78:79], v[22:23]
	v_pk_fma_f32 v[76:77], v[66:67], v[76:77], v[20:21]
	v_pk_fma_f32 v[82:83], v[60:61], v[82:83], v[18:19]
	v_pk_fma_f32 v[80:81], v[62:63], v[80:81], v[16:17]
	v_cvt_pk_bf16_f32 v76, v76, v77
	v_cvt_pk_bf16_f32 v77, v78, v79
	v_cvt_pk_bf16_f32 v78, v80, v81
	v_cvt_pk_bf16_f32 v79, v82, v83
	global_store_dwordx4 v[96:97], v[76:79], off offset:2048
	v_pk_mul_f32 v[80:81], v[94:95], v[98:99] op_sel_hi:[1,0]
	v_pk_mul_f32 v[82:83], v[90:91], v[98:99] op_sel_hi:[1,0]
	v_pk_mul_f32 v[76:77], v[92:93], v[98:99] op_sel_hi:[1,0]
	v_pk_mul_f32 v[78:79], v[88:89], v[98:99] op_sel_hi:[1,0]
	v_pk_fma_f32 v[76:77], v[74:75], v[76:77], v[28:29]
	v_pk_fma_f32 v[78:79], v[72:73], v[78:79], v[30:31]
	v_pk_fma_f32 v[82:83], v[68:69], v[82:83], v[26:27]
	v_pk_fma_f32 v[80:81], v[70:71], v[80:81], v[24:25]
	v_cvt_pk_bf16_f32 v76, v76, v77
	v_cvt_pk_bf16_f32 v77, v78, v79
	v_cvt_pk_bf16_f32 v78, v80, v81
	v_cvt_pk_bf16_f32 v79, v82, v83
	global_store_dwordx4 v[96:97], v[76:79], off offset:3072
	v_lshl_add_u64 v[88:89], v[34:35], 0, s[64:65]
	global_load_dwordx4 v[76:79], v[88:89], off
	global_load_dwordx4 v[80:83], v[88:89], off offset:1024
	global_load_dwordx4 v[84:87], v[88:89], off offset:2048
	s_nop 0
	global_load_dwordx4 v[88:91], v[88:89], off offset:3072
	s_cmpk_lt_i32 s3, 0x800
	s_waitcnt vmcnt(3)
	v_lshlrev_b32_e32 v97, 16, v77
	v_lshlrev_b32_e32 v96, 16, v76
	v_and_b32_e32 v77, 0xffff0000, v77
	v_and_b32_e32 v76, 0xffff0000, v76
	v_lshlrev_b32_e32 v101, 16, v79
	v_lshlrev_b32_e32 v100, 16, v78
	v_and_b32_e32 v79, 0xffff0000, v79
	v_and_b32_e32 v78, 0xffff0000, v78
	v_pk_mul_f32 v[98:99], v[76:77], v[76:77]
	v_pk_mul_f32 v[102:103], v[78:79], v[78:79]
	s_waitcnt vmcnt(0)
; __device__ __forceinline__ float ssq8(const f32x4& a, const f32x4& b) { return ((a[0] * a[0] + a[1] * a[1]) + (a[2] * a[2] + a[3] * a[3])) + ((b[0] * b[0] + b[1] * b[1]) + (b[2] * b[2] + b[3] * b[3])); }
; __device__ __forceinline__ float shfl_xor_f(float v, int o) {
;     int l; asm volatile("v_mbcnt_lo_u32_b32 %0, -1, 0\n\tv_mbcnt_hi_u32_b32 %0, -1, %0" : "=v"(l));
;     return __builtin_bit_cast(float, __builtin_amdgcn_ds_bpermute((l ^ o) << 2, __builtin_bit_cast(int, v)));
; }
; __device__ __forceinline__ float wave_sum(float v) {
; #pragma unroll
;     for (int o = 1; o < 64; o <<= 1) v += shfl_xor_f(v, o);
;     return v;
; template <int XF32> __device__ __forceinline__ void norm_mod_phase(const void* x, const float* modl, int ch_shift, int ch_scale, bf16* H, int gw, int NGW, int lane) {
;     ...
;         for (int rr = 0; rr < 8; ++rr) {
;             const unsigned char* xr = (const unsigned char*)x + (size_t)(r0 + rr) * rowb; f32x4 v[4][2]; float s = 0.f;
; #pragma unroll
;             for (int j = 0; j < 4; ++j) ld_row8<XF32>(xr, lane, j, v[j][0], v[j][1]);
; #pragma unroll
;             for (int j = 0; j < 4; ++j) s += ssq8(v[j][0], v[j][1]);
;             const float rstd = 1.f / sqrtf(wave_sum(s) * (1.f / DM) + EPS);
	v_lshlrev_b32_e32 v92, 16, v88
	v_and_b32_e32 v93, 0xffff0000, v88
	v_pk_fma_f32 v[98:99], v[96:97], v[96:97], v[98:99]
	v_pk_fma_f32 v[102:103], v[100:101], v[100:101], v[102:103]
	v_lshlrev_b32_e32 v105, 16, v81
	v_lshlrev_b32_e32 v104, 16, v80
	v_and_b32_e32 v81, 0xffff0000, v81
	v_and_b32_e32 v80, 0xffff0000, v80
	v_lshlrev_b32_e32 v109, 16, v83
	v_lshlrev_b32_e32 v108, 16, v82
	v_and_b32_e32 v83, 0xffff0000, v83
	v_and_b32_e32 v82, 0xffff0000, v82
	v_pk_mul_f32 v[106:107], v[80:81], v[80:81]
	v_pk_mul_f32 v[110:111], v[82:83], v[82:83]
	v_mul_f32_e32 v116, v92, v92
	v_mul_f32_e32 v117, v93, v93
	v_pk_add_f32 v[98:99], v[98:99], v[98:99] op_sel:[0,1] op_sel_hi:[1,0]
	v_pk_add_f32 v[102:103], v[102:103], v[102:103] op_sel:[0,1] op_sel_hi:[1,0]
	v_lshlrev_b32_e32 v88, 16, v89
	v_and_b32_e32 v89, 0xffff0000, v89
	v_pk_fma_f32 v[106:107], v[104:105], v[104:105], v[106:107]
	v_pk_fma_f32 v[110:111], v[108:109], v[108:109], v[110:111]
	v_mov_b32_e32 v99, v116
	v_mov_b32_e32 v103, v117
	v_mul_f32_e32 v118, v88, v88
	v_mul_f32_e32 v119, v89, v89
	v_pk_add_f32 v[98:99], v[98:99], v[102:103]
	v_pk_add_f32 v[102:103], v[106:107], v[106:107] op_sel:[0,1] op_sel_hi:[1,0]
	v_pk_add_f32 v[106:107], v[110:111], v[110:111] op_sel:[0,1] op_sel_hi:[1,0]
	v_mov_b32_e32 v103, v118
	v_mov_b32_e32 v107, v119
	v_lshlrev_b32_e32 v112, 16, v84
	v_and_b32_e32 v113, 0xffff0000, v84
	v_lshlrev_b32_e32 v84, 16, v85
	v_and_b32_e32 v85, 0xffff0000, v85
	v_pk_add_f32 v[102:103], v[102:103], v[106:107]
	v_lshlrev_b32_e32 v94, 16, v90
	v_and_b32_e32 v95, 0xffff0000, v90
	v_pk_add_f32 v[98:99], v[98:99], v[102:103]
	v_mul_f32_e32 v102, v113, v113
	v_mul_f32_e32 v106, v85, v85
	v_mul_f32_e32 v120, v94, v94
	v_mul_f32_e32 v121, v95, v95
	v_pk_fma_f32 v[102:103], v[112:113], v[112:113], v[102:103] op_sel_hi:[1,1,0]
	v_pk_fma_f32 v[106:107], v[84:85], v[84:85], v[106:107] op_sel_hi:[1,1,0]
	v_lshlrev_b32_e32 v114, 16, v86
	v_and_b32_e32 v115, 0xffff0000, v86
	v_lshlrev_b32_e32 v86, 16, v87
	v_and_b32_e32 v87, 0xffff0000, v87
	v_mov_b32_e32 v103, v120
	v_mov_b32_e32 v107, v121
	v_lshlrev_b32_e32 v90, 16, v91
	v_and_b32_e32 v91, 0xffff0000, v91
	v_pk_add_f32 v[102:103], v[102:103], v[106:107]
	v_mul_f32_e32 v106, v115, v115
	v_mul_f32_e32 v110, v87, v87
	v_mul_f32_e32 v122, v90, v90
	v_mul_f32_e32 v123, v91, v91
	v_pk_fma_f32 v[106:107], v[114:115], v[114:115], v[106:107] op_sel_hi:[1,1,0]
	v_pk_fma_f32 v[110:111], v[86:87], v[86:87], v[110:111] op_sel_hi:[1,1,0]
	v_mov_b32_e32 v107, v122
	v_mov_b32_e32 v111, v123
	v_pk_add_f32 v[106:107], v[106:107], v[110:111]
	s_nop 0
	v_pk_add_f32 v[102:103], v[102:103], v[106:107]
	s_nop 0
	v_pk_add_f32 v[98:99], v[98:99], v[102:103]
	s_nop 0
	v_add_f32_e32 v98, v98, v99
	v_mbcnt_lo_u32_b32 v99, -1, 0
	v_mbcnt_hi_u32_b32 v99, -1, v99
	s_nop 0
	v_lshlrev_b32_e32 v99, 2, v99
	v_xor_b32_e32 v99, 4, v99
	ds_bpermute_b32 v99, v99, v98
	s_waitcnt lgkmcnt(0)
	v_add_f32_e32 v98, v98, v99
	v_mbcnt_lo_u32_b32 v99, -1, 0
	v_mbcnt_hi_u32_b32 v99, -1, v99
	s_nop 0
	v_lshlrev_b32_e32 v99, 2, v99
	v_xor_b32_e32 v99, 8, v99
	ds_bpermute_b32 v99, v99, v98
	s_waitcnt lgkmcnt(0)
	v_add_f32_e32 v98, v98, v99
	v_mbcnt_lo_u32_b32 v99, -1, 0
	v_mbcnt_hi_u32_b32 v99, -1, v99
	s_nop 0
	v_lshlrev_b32_e32 v99, 2, v99
	v_xor_b32_e32 v99, 16, v99
	ds_bpermute_b32 v99, v99, v98
	s_waitcnt lgkmcnt(0)
	v_add_f32_e32 v98, v98, v99
	v_mbcnt_lo_u32_b32 v99, -1, 0
	v_mbcnt_hi_u32_b32 v99, -1, v99
	s_nop 0
	v_lshlrev_b32_e32 v99, 2, v99
	v_xor_b32_e32 v99, 32, v99
	ds_bpermute_b32 v99, v99, v98
	s_waitcnt lgkmcnt(0)
	v_add_f32_e32 v98, v98, v99
	v_mbcnt_lo_u32_b32 v99, -1, 0
	v_mbcnt_hi_u32_b32 v99, -1, v99
	s_nop 0
	v_lshlrev_b32_e32 v99, 2, v99
	v_xor_b32_e32 v99, 64, v99
	ds_bpermute_b32 v99, v99, v98
	s_waitcnt lgkmcnt(0)
	v_add_f32_e32 v98, v98, v99
	v_mbcnt_lo_u32_b32 v99, -1, 0
	v_mbcnt_hi_u32_b32 v99, -1, v99
	s_nop 0
	v_lshlrev_b32_e32 v99, 2, v99
	v_xor_b32_e32 v99, 0x80, v99
	ds_bpermute_b32 v99, v99, v98
	s_waitcnt lgkmcnt(0)
; __device__ __forceinline__ v4u pk8(f32x4 a, f32x4 b) { v4u w; w.x = pk2(a[0], a[1]); w.y = pk2(a[2], a[3]); w.z = pk2(b[0], b[1]); w.w = pk2(b[2], b[3]); return w; }
; template <int XF32> __device__ __forceinline__ void norm_mod_phase(const void* x, const float* modl, int ch_shift, int ch_scale, bf16* H, int gw, int NGW, int lane) {
;     ...
;             const float rstd = 1.f / sqrtf(wave_sum(s) * (1.f / DM) + EPS);
;             v4u* o = (v4u*)(H + (size_t)(r0 + rr) * DM);
; #pragma unroll
;             for (int j = 0; j < 4; ++j) o[lane + 64 * j] = pk8(v[j][0] * rstd * sc[j][0] + sh[j][0], v[j][1] * rstd * sc[j][1] + sh[j][1]);
;         }
	v_add_f32_e32 v98, v98, v99
	v_fmamk_f32 v98, v98, 0x3a000000, v224
	v_cmp_gt_f32_e32 vcc, s41, v98
	v_mul_f32_e32 v99, 0x4f800000, v98
	s_nop 0
	v_cndmask_b32_e32 v98, v98, v99, vcc
	v_sqrt_f32_e32 v99, v98
	s_nop 0
	v_add_u32_e32 v102, -1, v99
	v_fma_f32 v103, -v102, v99, v98
	v_cmp_ge_f32_e64 s[4:5], 0, v103
	v_add_u32_e32 v103, 1, v99
	s_nop 0
	v_cndmask_b32_e64 v102, v99, v102, s[4:5]
	v_fma_f32 v99, -v103, v99, v98
	v_cmp_lt_f32_e64 s[4:5], 0, v99
	s_nop 1
	v_cndmask_b32_e64 v99, v102, v103, s[4:5]
	v_mul_f32_e32 v102, 0x37800000, v99
	v_cndmask_b32_e32 v99, v99, v102, vcc
	v_cmp_class_f32_e32 vcc, v98, v225
	s_nop 1
	v_cndmask_b32_e32 v98, v99, v98, vcc
	v_div_scale_f32 v99, s[0:1], v98, v98, 1.0
	v_rcp_f32_e32 v102, v99
	s_nop 0
	v_fma_f32 v103, -v99, v102, 1.0
	v_fmac_f32_e32 v102, v103, v102
	v_div_scale_f32 v103, vcc, 1.0, v98, 1.0
	v_mul_f32_e32 v106, v103, v102
	v_fma_f32 v107, -v99, v106, v103
	v_fmac_f32_e32 v106, v107, v102
	v_fma_f32 v99, -v99, v106, v103
	v_div_fmas_f32 v99, v99, v102, v106
	v_div_fixup_f32 v98, v99, v98, 1.0
	v_mov_b32_e32 v103, v76
	v_mov_b32_e32 v76, v97
	v_mov_b32_e32 v102, v96
	v_pk_mul_f32 v[76:77], v[98:99], v[76:77] op_sel_hi:[0,1]
	v_pk_mul_f32 v[102:103], v[98:99], v[102:103] op_sel_hi:[0,1]
	v_pk_fma_f32 v[14:15], v[56:57], v[76:77], v[14:15]
	v_mov_b32_e32 v56, v100
	v_mov_b32_e32 v57, v78
	v_mov_b32_e32 v78, v101
	v_pk_fma_f32 v[12:13], v[58:59], v[102:103], v[12:13]
	v_pk_mul_f32 v[56:57], v[98:99], v[56:57] op_sel_hi:[0,1]
	v_pk_mul_f32 v[58:59], v[98:99], v[78:79] op_sel_hi:[0,1]
	v_pk_fma_f32 v[52:53], v[52:53], v[58:59], v[10:11]
	v_pk_fma_f32 v[10:11], v[54:55], v[56:57], v[8:9]
	v_cvt_pk_bf16_f32 v8, v12, v13
	v_cvt_pk_bf16_f32 v9, v14, v15
	v_cvt_pk_bf16_f32 v10, v10, v11
	v_cvt_pk_bf16_f32 v11, v52, v53
	v_lshl_add_u64 v[12:13], v[36:37], 0, s[64:65]
	global_store_dwordx4 v[12:13], v[8:11], off
	s_nop 1
	v_mov_b32_e32 v8, v104
	v_mov_b32_e32 v9, v80
	v_pk_mul_f32 v[8:9], v[98:99], v[8:9] op_sel_hi:[0,1]
	v_mov_b32_e32 v80, v105
	v_pk_mul_f32 v[10:11], v[98:99], v[80:81] op_sel_hi:[0,1]
	v_pk_fma_f32 v[4:5], v[50:51], v[8:9], v[4:5]
	v_mov_b32_e32 v8, v108
	v_mov_b32_e32 v9, v82
	v_mov_b32_e32 v82, v109
	v_pk_fma_f32 v[6:7], v[48:49], v[10:11], v[6:7]
	v_pk_mul_f32 v[8:9], v[98:99], v[8:9] op_sel_hi:[0,1]
	v_pk_mul_f32 v[10:11], v[98:99], v[82:83] op_sel_hi:[0,1]
	v_pk_fma_f32 v[10:11], v[44:45], v[10:11], v[2:3]
	v_pk_fma_f32 v[2:3], v[46:47], v[8:9], v[0:1]
	v_cvt_pk_bf16_f32 v0, v4, v5
	v_cvt_pk_bf16_f32 v1, v6, v7
	v_cvt_pk_bf16_f32 v2, v2, v3
	v_cvt_pk_bf16_f32 v3, v10, v11
	global_store_dwordx4 v[12:13], v[0:3], off offset:1024
	v_pk_mul_f32 v[4:5], v[98:99], v[114:115] op_sel_hi:[0,1]
	v_pk_mul_f32 v[6:7], v[98:99], v[86:87] op_sel_hi:[0,1]
	v_pk_mul_f32 v[0:1], v[98:99], v[112:113] op_sel_hi:[0,1]
	v_pk_mul_f32 v[2:3], v[98:99], v[84:85] op_sel_hi:[0,1]
	v_pk_fma_f32 v[2:3], v[64:65], v[2:3], v[22:23]
	v_pk_fma_f32 v[0:1], v[66:67], v[0:1], v[20:21]
	v_pk_fma_f32 v[6:7], v[60:61], v[6:7], v[18:19]
	v_pk_fma_f32 v[4:5], v[62:63], v[4:5], v[16:17]
	v_cvt_pk_bf16_f32 v0, v0, v1
	v_cvt_pk_bf16_f32 v1, v2, v3
	v_cvt_pk_bf16_f32 v2, v4, v5
	v_cvt_pk_bf16_f32 v3, v6, v7
	global_store_dwordx4 v[12:13], v[0:3], off offset:2048
	v_pk_mul_f32 v[4:5], v[94:95], v[98:99] op_sel_hi:[1,0]
	v_pk_mul_f32 v[6:7], v[90:91], v[98:99] op_sel_hi:[1,0]
	v_pk_mul_f32 v[0:1], v[92:93], v[98:99] op_sel_hi:[1,0]
	v_pk_mul_f32 v[2:3], v[88:89], v[98:99] op_sel_hi:[1,0]
	v_pk_fma_f32 v[0:1], v[74:75], v[0:1], v[28:29]
	v_pk_fma_f32 v[2:3], v[72:73], v[2:3], v[30:31]
	v_pk_fma_f32 v[6:7], v[68:69], v[6:7], v[26:27]
	v_pk_fma_f32 v[4:5], v[70:71], v[4:5], v[24:25]
	v_cvt_pk_bf16_f32 v0, v0, v1
	v_cvt_pk_bf16_f32 v1, v2, v3
	v_cvt_pk_bf16_f32 v2, v4, v5
	v_cvt_pk_bf16_f32 v3, v6, v7
	global_store_dwordx4 v[12:13], v[0:3], off offset:3072
	s_cbranch_scc1 .LBB0_161

; __device__ __forceinline__ float ssq8(const f32x4& a, const f32x4& b) { return ((a[0] * a[0] + a[1] * a[1]) + (a[2] * a[2] + a[3] * a[3])) + ((b[0] * b[0] + b[1] * b[1]) + (b[2] * b[2] + b[3] * b[3])); }
; template <int XF32> __device__ __forceinline__ void norm_mod_phase(const void* x, const float* modl, int ch_shift, int ch_scale, bf16* H, int gw, int NGW, int lane) {
;     ...
;         const int r0 = blk * 8, b = r0 >> 12;
;         const f32x4* shp = (const f32x4*)(modl + (size_t)b * MODW + ch_shift * DM); const f32x4* scp = (const f32x4*)(modl + (size_t)b * MODW + ch_scale * DM);
;         f32x4 sh[4][2], sc[4][2];
; #pragma unroll
;         for (int j = 0; j < 4; ++j)
; #pragma unroll
;             for (int q = 0; q < 2; ++q) { sh[j][q] = shp[2 * (lane + 64 * j) + q]; sc[j][q] = scp[2 * (lane + 64 * j) + q] + 1.f; }
;         for (int rr = 0; rr < 8; ++rr) {
;             const unsigned char* xr = (const unsigned char*)x + (size_t)(r0 + rr) * rowb; f32x4 v[4][2]; float s = 0.f;
; #pragma unroll
;             for (int j = 0; j < 4; ++j) ld_row8<XF32>(xr, lane, j, v[j][0], v[j][1]);
; #pragma unroll
;             for (int j = 0; j < 4; ++j) s += ssq8(v[j][0], v[j][1]);
;             const float rstd = 1.f / sqrtf(wave_sum(s) * (1.f / DM) + EPS);
.LBB0_919:
	s_ashr_i32 s0, s56, 9
	s_mul_hi_i32 s1, s0, 0x12000
	s_mul_i32 s0, s0, 0x12000
	s_add_u32 s0, s24, s0
	s_addc_u32 s1, s26, s1
	s_add_u32 s60, s0, 0xc000
	s_addc_u32 s61, s1, 0
	s_add_u32 s0, s0, 0xe000
	s_addc_u32 s1, s1, 0
	v_lshl_add_u64 v[4:5], s[60:61], 0, v[36:37]
	v_lshl_add_u64 v[12:13], s[0:1], 0, v[36:37]
	global_load_dwordx4 v[0:3], v[4:5], off offset:16
	s_nop 0
	global_load_dwordx4 v[4:7], v[4:5], off
	s_nop 0
	global_load_dwordx4 v[178:181], v[12:13], off offset:16
	s_nop 0
	global_load_dwordx4 v[182:185], v[12:13], off
	v_lshl_add_u64 v[20:21], s[0:1], 0, v[38:39]
	v_lshl_add_u64 v[28:29], s[0:1], 0, v[40:41]
	v_lshl_add_u64 v[68:69], s[0:1], 0, v[42:43]
	s_add_i32 s0, s4, -7
	s_ashr_i32 s1, s0, 31
	s_ashr_i32 s5, s4, 31
	s_add_i32 s56, s56, s58
	v_lshl_add_u64 v[12:13], s[60:61], 0, v[38:39]
	global_load_dwordx4 v[8:11], v[12:13], off offset:16
	s_nop 0
	global_load_dwordx4 v[12:15], v[12:13], off
	s_nop 0
	global_load_dwordx4 v[186:189], v[20:21], off offset:16
	s_nop 0
	global_load_dwordx4 v[190:193], v[20:21], off
	v_lshl_add_u64 v[20:21], s[60:61], 0, v[40:41]
	global_load_dwordx4 v[16:19], v[20:21], off offset:16
	s_nop 0
	global_load_dwordx4 v[20:23], v[20:21], off
	s_nop 0
	global_load_dwordx4 v[194:197], v[28:29], off offset:16
	s_nop 0
	global_load_dwordx4 v[198:201], v[28:29], off
	v_lshl_add_u64 v[28:29], s[60:61], 0, v[42:43]
	global_load_dwordx4 v[24:27], v[28:29], off offset:16
	s_nop 0
	global_load_dwordx4 v[28:31], v[28:29], off
	s_nop 0
	global_load_dwordx4 v[202:205], v[68:69], off offset:16
	s_nop 0
	global_load_dwordx4 v[206:209], v[68:69], off
	s_lshl_b64 s[60:61], s[0:1], 12
	v_lshl_add_u64 v[88:89], v[32:33], 0, s[60:61]
	global_load_dwordx4 v[76:79], v[88:89], off
	global_load_dwordx4 v[80:83], v[88:89], off offset:1024
	global_load_dwordx4 v[84:87], v[88:89], off offset:2048
	s_nop 0
	global_load_dwordx4 v[88:91], v[88:89], off offset:3072
	s_waitcnt vmcnt(4)
	v_pk_add_f32 v[44:45], v[180:181], 1.0 op_sel_hi:[1,0]
	v_pk_add_f32 v[50:51], v[182:183], 1.0 op_sel_hi:[1,0]
	v_pk_add_f32 v[48:49], v[184:185], 1.0 op_sel_hi:[1,0]
	v_pk_add_f32 v[46:47], v[178:179], 1.0 op_sel_hi:[1,0]
	v_pk_add_f32 v[52:53], v[188:189], 1.0 op_sel_hi:[1,0]
	v_pk_add_f32 v[58:59], v[190:191], 1.0 op_sel_hi:[1,0]
	v_pk_add_f32 v[56:57], v[192:193], 1.0 op_sel_hi:[1,0]
	v_pk_add_f32 v[54:55], v[186:187], 1.0 op_sel_hi:[1,0]
	v_pk_add_f32 v[60:61], v[196:197], 1.0 op_sel_hi:[1,0]
	v_pk_add_f32 v[66:67], v[198:199], 1.0 op_sel_hi:[1,0]
	v_pk_add_f32 v[64:65], v[200:201], 1.0 op_sel_hi:[1,0]
	v_pk_add_f32 v[62:63], v[194:195], 1.0 op_sel_hi:[1,0]
	v_pk_add_f32 v[72:73], v[208:209], 1.0 op_sel_hi:[1,0]
	v_pk_add_f32 v[74:75], v[206:207], 1.0 op_sel_hi:[1,0]
	v_pk_add_f32 v[68:69], v[204:205], 1.0 op_sel_hi:[1,0]
	v_pk_add_f32 v[70:71], v[202:203], 1.0 op_sel_hi:[1,0]
	s_waitcnt vmcnt(3)
	v_lshlrev_b32_e32 v97, 16, v77
	v_lshlrev_b32_e32 v96, 16, v76
	v_and_b32_e32 v77, 0xffff0000, v77
	v_and_b32_e32 v76, 0xffff0000, v76
	v_lshlrev_b32_e32 v101, 16, v79
	v_lshlrev_b32_e32 v100, 16, v78
	v_and_b32_e32 v79, 0xffff0000, v79
	v_and_b32_e32 v78, 0xffff0000, v78
	v_pk_mul_f32 v[98:99], v[76:77], v[76:77]
	v_pk_mul_f32 v[102:103], v[78:79], v[78:79]
	s_waitcnt vmcnt(0)
	v_lshlrev_b32_e32 v92, 16, v88
	v_and_b32_e32 v93, 0xffff0000, v88
	v_pk_fma_f32 v[98:99], v[96:97], v[96:97], v[98:99]
	v_pk_fma_f32 v[102:103], v[100:101], v[100:101], v[102:103]
	v_lshlrev_b32_e32 v105, 16, v81
	v_lshlrev_b32_e32 v104, 16, v80
	v_and_b32_e32 v81, 0xffff0000, v81
	v_and_b32_e32 v80, 0xffff0000, v80
	v_lshlrev_b32_e32 v109, 16, v83
	v_lshlrev_b32_e32 v108, 16, v82
	v_and_b32_e32 v83, 0xffff0000, v83
	v_and_b32_e32 v82, 0xffff0000, v82
	v_pk_mul_f32 v[106:107], v[80:81], v[80:81]
	v_pk_mul_f32 v[110:111], v[82:83], v[82:83]
	v_mul_f32_e32 v116, v92, v92
	v_mul_f32_e32 v117, v93, v93
	v_pk_add_f32 v[98:99], v[98:99], v[98:99] op_sel:[0,1] op_sel_hi:[1,0]
	v_pk_add_f32 v[102:103], v[102:103], v[102:103] op_sel:[0,1] op_sel_hi:[1,0]
	v_lshlrev_b32_e32 v88, 16, v89
	v_and_b32_e32 v89, 0xffff0000, v89
	v_pk_fma_f32 v[106:107], v[104:105], v[104:105], v[106:107]
	v_pk_fma_f32 v[110:111], v[108:109], v[108:109], v[110:111]
	v_mov_b32_e32 v99, v116
	v_mov_b32_e32 v103, v117
	v_mul_f32_e32 v118, v88, v88
	v_mul_f32_e32 v119, v89, v89
	v_pk_add_f32 v[98:99], v[98:99], v[102:103]
	v_pk_add_f32 v[102:103], v[106:107], v[106:107] op_sel:[0,1] op_sel_hi:[1,0]
	v_pk_add_f32 v[106:107], v[110:111], v[110:111] op_sel:[0,1] op_sel_hi:[1,0]
	v_mov_b32_e32 v103, v118
	v_mov_b32_e32 v107, v119
	v_lshlrev_b32_e32 v112, 16, v84
	v_and_b32_e32 v113, 0xffff0000, v84
	v_lshlrev_b32_e32 v84, 16, v85
	v_and_b32_e32 v85, 0xffff0000, v85
	v_pk_add_f32 v[102:103], v[102:103], v[106:107]
	v_lshlrev_b32_e32 v94, 16, v90
	v_and_b32_e32 v95, 0xffff0000, v90
	v_pk_add_f32 v[98:99], v[98:99], v[102:103]
	v_mul_f32_e32 v102, v113, v113
	v_mul_f32_e32 v106, v85, v85
	v_mul_f32_e32 v120, v94, v94
	v_mul_f32_e32 v121, v95, v95
	v_pk_fma_f32 v[102:103], v[112:113], v[112:113], v[102:103] op_sel_hi:[1,1,0]
	v_pk_fma_f32 v[106:107], v[84:85], v[84:85], v[106:107] op_sel_hi:[1,1,0]
	v_lshlrev_b32_e32 v114, 16, v86
	v_and_b32_e32 v115, 0xffff0000, v86
	v_lshlrev_b32_e32 v86, 16, v87
	v_and_b32_e32 v87, 0xffff0000, v87
	v_mov_b32_e32 v103, v120
	v_mov_b32_e32 v107, v121
	v_lshlrev_b32_e32 v90, 16, v91
	v_and_b32_e32 v91, 0xffff0000, v91
	v_pk_add_f32 v[102:103], v[102:103], v[106:107]
	v_mul_f32_e32 v106, v115, v115
	v_mul_f32_e32 v110, v87, v87
	v_mul_f32_e32 v122, v90, v90
	v_mul_f32_e32 v123, v91, v91
	v_pk_fma_f32 v[106:107], v[114:115], v[114:115], v[106:107] op_sel_hi:[1,1,0]
	v_pk_fma_f32 v[110:111], v[86:87], v[86:87], v[110:111] op_sel_hi:[1,1,0]
	v_mov_b32_e32 v107, v122
	v_mov_b32_e32 v111, v123
	v_pk_add_f32 v[106:107], v[106:107], v[110:111]
	s_nop 0
	v_pk_add_f32 v[102:103], v[102:103], v[106:107]
	s_nop 0
	v_pk_add_f32 v[98:99], v[98:99], v[102:103]
	s_nop 0
	v_add_f32_e32 v98, v98, v99
	v_mbcnt_lo_u32_b32 v99, -1, 0
	v_mbcnt_hi_u32_b32 v99, -1, v99
	s_nop 0
	v_lshlrev_b32_e32 v99, 2, v99
	v_xor_b32_e32 v99, 4, v99
	ds_bpermute_b32 v99, v99, v98
	s_waitcnt lgkmcnt(0)
; __device__ __forceinline__ v4u pk8(f32x4 a, f32x4 b) { v4u w; w.x = pk2(a[0], a[1]); w.y = pk2(a[2], a[3]); w.z = pk2(b[0], b[1]); w.w = pk2(b[2], b[3]); return w; }
; __device__ __forceinline__ float shfl_xor_f(float v, int o) {
;     int l; asm volatile("v_mbcnt_lo_u32_b32 %0, -1, 0\n\tv_mbcnt_hi_u32_b32 %0, -1, %0" : "=v"(l));
;     return __builtin_bit_cast(float, __builtin_amdgcn_ds_bpermute((l ^ o) << 2, __builtin_bit_cast(int, v)));
; }
; __device__ __forceinline__ float wave_sum(float v) {
; #pragma unroll
;     for (int o = 1; o < 64; o <<= 1) v += shfl_xor_f(v, o);
;     return v;
; template <int XF32> __device__ __forceinline__ void norm_mod_phase(const void* x, const float* modl, int ch_shift, int ch_scale, bf16* H, int gw, int NGW, int lane) {
;     ...
;             const float rstd = 1.f / sqrtf(wave_sum(s) * (1.f / DM) + EPS);
;             v4u* o = (v4u*)(H + (size_t)(r0 + rr) * DM);
; #pragma unroll
;             for (int j = 0; j < 4; ++j) o[lane + 64 * j] = pk8(v[j][0] * rstd * sc[j][0] + sh[j][0], v[j][1] * rstd * sc[j][1] + sh[j][1]);
	v_add_f32_e32 v98, v98, v99
	v_mbcnt_lo_u32_b32 v99, -1, 0
	v_mbcnt_hi_u32_b32 v99, -1, v99
	s_nop 0
	v_lshlrev_b32_e32 v99, 2, v99
	v_xor_b32_e32 v99, 8, v99
	ds_bpermute_b32 v99, v99, v98
	s_waitcnt lgkmcnt(0)
	v_add_f32_e32 v98, v98, v99
	v_mbcnt_lo_u32_b32 v99, -1, 0
	v_mbcnt_hi_u32_b32 v99, -1, v99
	s_nop 0
	v_lshlrev_b32_e32 v99, 2, v99
	v_xor_b32_e32 v99, 16, v99
	ds_bpermute_b32 v99, v99, v98
	s_waitcnt lgkmcnt(0)
	v_add_f32_e32 v98, v98, v99
	v_mbcnt_lo_u32_b32 v99, -1, 0
	v_mbcnt_hi_u32_b32 v99, -1, v99
	s_nop 0
	v_lshlrev_b32_e32 v99, 2, v99
	v_xor_b32_e32 v99, 32, v99
	ds_bpermute_b32 v99, v99, v98
	s_waitcnt lgkmcnt(0)
	v_add_f32_e32 v98, v98, v99
	v_mbcnt_lo_u32_b32 v99, -1, 0
	v_mbcnt_hi_u32_b32 v99, -1, v99
	s_nop 0
	v_lshlrev_b32_e32 v99, 2, v99
	v_xor_b32_e32 v99, 64, v99
	ds_bpermute_b32 v99, v99, v98
	s_waitcnt lgkmcnt(0)
	v_add_f32_e32 v98, v98, v99
	v_mbcnt_lo_u32_b32 v99, -1, 0
	v_mbcnt_hi_u32_b32 v99, -1, v99
	s_nop 0
	v_lshlrev_b32_e32 v99, 2, v99
	v_xor_b32_e32 v99, 0x80, v99
	ds_bpermute_b32 v99, v99, v98
	s_waitcnt lgkmcnt(0)
	v_add_f32_e32 v98, v98, v99
	v_fmamk_f32 v98, v98, 0x3a000000, v224
	v_cmp_gt_f32_e32 vcc, s41, v98
	v_mul_f32_e32 v99, 0x4f800000, v98
	s_nop 0
	v_cndmask_b32_e32 v98, v98, v99, vcc
	v_sqrt_f32_e32 v99, v98
	s_nop 0
	v_add_u32_e32 v102, -1, v99
	v_fma_f32 v103, -v102, v99, v98
	v_cmp_ge_f32_e64 s[0:1], 0, v103
	v_add_u32_e32 v103, 1, v99
	s_nop 0
	v_cndmask_b32_e64 v102, v99, v102, s[0:1]
	v_fma_f32 v99, -v103, v99, v98
	v_cmp_lt_f32_e64 s[0:1], 0, v99
	s_nop 1
	v_cndmask_b32_e64 v99, v102, v103, s[0:1]
	v_mul_f32_e32 v102, 0x37800000, v99
	v_cndmask_b32_e32 v99, v99, v102, vcc
	v_cmp_class_f32_e32 vcc, v98, v225
	s_nop 1
	v_cndmask_b32_e32 v98, v99, v98, vcc
	v_div_scale_f32 v99, s[0:1], v98, v98, 1.0
	v_rcp_f32_e32 v102, v99
	s_add_i32 s0, s4, -6
	s_ashr_i32 s1, s0, 31
	v_fma_f32 v103, -v99, v102, 1.0
	v_fmac_f32_e32 v102, v103, v102
	v_div_scale_f32 v103, vcc, 1.0, v98, 1.0
	v_mul_f32_e32 v106, v103, v102
	v_fma_f32 v107, -v99, v106, v103
	v_fmac_f32_e32 v106, v107, v102
	v_fma_f32 v99, -v99, v106, v103
	v_div_fmas_f32 v99, v99, v102, v106
	v_div_fixup_f32 v98, v99, v98, 1.0
	v_mov_b32_e32 v102, v96
	v_mov_b32_e32 v103, v76
	v_mov_b32_e32 v76, v97
	v_pk_mul_f32 v[102:103], v[98:99], v[102:103] op_sel_hi:[0,1]
	v_pk_mul_f32 v[76:77], v[98:99], v[76:77] op_sel_hi:[0,1]
	v_pk_fma_f32 v[96:97], v[48:49], v[76:77], v[6:7]
	v_pk_fma_f32 v[76:77], v[50:51], v[102:103], v[4:5]
	v_mov_b32_e32 v102, v100
	v_mov_b32_e32 v103, v78
	v_mov_b32_e32 v78, v101
	v_pk_mul_f32 v[102:103], v[98:99], v[102:103] op_sel_hi:[0,1]
	v_pk_mul_f32 v[78:79], v[98:99], v[78:79] op_sel_hi:[0,1]
	v_pk_fma_f32 v[100:101], v[44:45], v[78:79], v[2:3]
	v_pk_fma_f32 v[78:79], v[46:47], v[102:103], v[0:1]
	v_cvt_pk_bf16_f32 v76, v76, v77
	v_cvt_pk_bf16_f32 v77, v96, v97
	v_cvt_pk_bf16_f32 v78, v78, v79
	v_cvt_pk_bf16_f32 v79, v100, v101
	v_lshl_add_u64 v[96:97], v[34:35], 0, s[60:61]
	global_store_dwordx4 v[96:97], v[76:79], off
	s_lshl_b64 s[60:61], s[0:1], 12
	s_nop 0
	v_mov_b32_e32 v77, v80
	v_mov_b32_e32 v80, v105
	v_mov_b32_e32 v76, v104
	v_pk_mul_f32 v[78:79], v[98:99], v[80:81] op_sel_hi:[0,1]
	v_mov_b32_e32 v80, v108
	v_mov_b32_e32 v81, v82
	v_mov_b32_e32 v82, v109
	v_pk_mul_f32 v[76:77], v[98:99], v[76:77] op_sel_hi:[0,1]
	v_pk_mul_f32 v[80:81], v[98:99], v[80:81] op_sel_hi:[0,1]
	v_pk_mul_f32 v[82:83], v[98:99], v[82:83] op_sel_hi:[0,1]
	v_pk_fma_f32 v[78:79], v[56:57], v[78:79], v[14:15]
	v_pk_fma_f32 v[76:77], v[58:59], v[76:77], v[12:13]
	v_pk_fma_f32 v[82:83], v[52:53], v[82:83], v[10:11]
	v_pk_fma_f32 v[80:81], v[54:55], v[80:81], v[8:9]
	v_cvt_pk_bf16_f32 v76, v76, v77
	v_cvt_pk_bf16_f32 v77, v78, v79
	v_cvt_pk_bf16_f32 v78, v80, v81
	v_cvt_pk_bf16_f32 v79, v82, v83
	global_store_dwordx4 v[96:97], v[76:79], off offset:1024
	v_pk_mul_f32 v[80:81], v[98:99], v[114:115] op_sel_hi:[0,1]
	v_pk_mul_f32 v[82:83], v[98:99], v[86:87] op_sel_hi:[0,1]
	v_pk_mul_f32 v[76:77], v[98:99], v[112:113] op_sel_hi:[0,1]
	v_pk_mul_f32 v[78:79], v[98:99], v[84:85] op_sel_hi:[0,1]
	v_pk_fma_f32 v[78:79], v[64:65], v[78:79], v[22:23]
	v_pk_fma_f32 v[76:77], v[66:67], v[76:77], v[20:21]
	v_pk_fma_f32 v[82:83], v[60:61], v[82:83], v[18:19]
	v_pk_fma_f32 v[80:81], v[62:63], v[80:81], v[16:17]
	v_cvt_pk_bf16_f32 v76, v76, v77
	v_cvt_pk_bf16_f32 v77, v78, v79
	v_cvt_pk_bf16_f32 v78, v80, v81
	v_cvt_pk_bf16_f32 v79, v82, v83
	global_store_dwordx4 v[96:97], v[76:79], off offset:2048
	v_pk_mul_f32 v[80:81], v[94:95], v[98:99] op_sel_hi:[1,0]
	v_pk_mul_f32 v[82:83], v[90:91], v[98:99] op_sel_hi:[1,0]
	v_pk_mul_f32 v[76:77], v[92:93], v[98:99] op_sel_hi:[1,0]
	v_pk_mul_f32 v[78:79], v[88:89], v[98:99] op_sel_hi:[1,0]
	v_pk_fma_f32 v[76:77], v[74:75], v[76:77], v[28:29]
	v_pk_fma_f32 v[78:79], v[72:73], v[78:79], v[30:31]
	v_pk_fma_f32 v[82:83], v[68:69], v[82:83], v[26:27]
	v_pk_fma_f32 v[80:81], v[70:71], v[80:81], v[24:25]
	v_cvt_pk_bf16_f32 v76, v76, v77
	v_cvt_pk_bf16_f32 v77, v78, v79
	v_cvt_pk_bf16_f32 v78, v80, v81
	v_cvt_pk_bf16_f32 v79, v82, v83
	global_store_dwordx4 v[96:97], v[76:79], off offset:3072
	v_lshl_add_u64 v[88:89], v[32:33], 0, s[60:61]
	global_load_dwordx4 v[76:79], v[88:89], off
	global_load_dwordx4 v[80:83], v[88:89], off offset:1024
	global_load_dwordx4 v[84:87], v[88:89], off offset:2048
	s_nop 0
	global_load_dwordx4 v[88:91], v[88:89], off offset:3072
	s_waitcnt vmcnt(3)
	v_lshlrev_b32_e32 v97, 16, v77
	v_lshlrev_b32_e32 v96, 16, v76
	v_and_b32_e32 v77, 0xffff0000, v77
	v_and_b32_e32 v76, 0xffff0000, v76
	v_lshlrev_b32_e32 v101, 16, v79
	v_lshlrev_b32_e32 v100, 16, v78
	v_and_b32_e32 v79, 0xffff0000, v79
	v_and_b32_e32 v78, 0xffff0000, v78
	v_pk_mul_f32 v[98:99], v[76:77], v[76:77]
	v_pk_mul_f32 v[102:103], v[78:79], v[78:79]
	s_waitcnt vmcnt(0)
; __device__ __forceinline__ v4u pk8(f32x4 a, f32x4 b) { v4u w; w.x = pk2(a[0], a[1]); w.y = pk2(a[2], a[3]); w.z = pk2(b[0], b[1]); w.w = pk2(b[2], b[3]); return w; }
; __device__ __forceinline__ float ssq8(const f32x4& a, const f32x4& b) { return ((a[0] * a[0] + a[1] * a[1]) + (a[2] * a[2] + a[3] * a[3])) + ((b[0] * b[0] + b[1] * b[1]) + (b[2] * b[2] + b[3] * b[3])); }
; __device__ __forceinline__ float shfl_xor_f(float v, int o) {
;     int l; asm volatile("v_mbcnt_lo_u32_b32 %0, -1, 0\n\tv_mbcnt_hi_u32_b32 %0, -1, %0" : "=v"(l));
;     return __builtin_bit_cast(float, __builtin_amdgcn_ds_bpermute((l ^ o) << 2, __builtin_bit_cast(int, v)));
; }
; __device__ __forceinline__ float wave_sum(float v) {
; #pragma unroll
;     for (int o = 1; o < 64; o <<= 1) v += shfl_xor_f(v, o);
;     return v;
; template <int XF32> __device__ __forceinline__ void norm_mod_phase(const void* x, const float* modl, int ch_shift, int ch_scale, bf16* H, int gw, int NGW, int lane) {
;     ...
;         for (int rr = 0; rr < 8; ++rr) {
;             const unsigned char* xr = (const unsigned char*)x + (size_t)(r0 + rr) * rowb; f32x4 v[4][2]; float s = 0.f;
; #pragma unroll
;             for (int j = 0; j < 4; ++j) ld_row8<XF32>(xr, lane, j, v[j][0], v[j][1]);
; #pragma unroll
;             for (int j = 0; j < 4; ++j) s += ssq8(v[j][0], v[j][1]);
;             const float rstd = 1.f / sqrtf(wave_sum(s) * (1.f / DM) + EPS);
;             v4u* o = (v4u*)(H + (size_t)(r0 + rr) * DM);
; #pragma unroll
;             for (int j = 0; j < 4; ++j) o[lane + 64 * j] = pk8(v[j][0] * rstd * sc[j][0] + sh[j][0], v[j][1] * rstd * sc[j][1] + sh[j][1]);
	v_lshlrev_b32_e32 v92, 16, v88
	v_and_b32_e32 v93, 0xffff0000, v88
	v_pk_fma_f32 v[98:99], v[96:97], v[96:97], v[98:99]
	v_pk_fma_f32 v[102:103], v[100:101], v[100:101], v[102:103]
	v_lshlrev_b32_e32 v105, 16, v81
	v_lshlrev_b32_e32 v104, 16, v80
	v_and_b32_e32 v81, 0xffff0000, v81
	v_and_b32_e32 v80, 0xffff0000, v80
	v_lshlrev_b32_e32 v109, 16, v83
	v_lshlrev_b32_e32 v108, 16, v82
	v_and_b32_e32 v83, 0xffff0000, v83
	v_and_b32_e32 v82, 0xffff0000, v82
	v_pk_mul_f32 v[106:107], v[80:81], v[80:81]
	v_pk_mul_f32 v[110:111], v[82:83], v[82:83]
	v_mul_f32_e32 v116, v92, v92
	v_mul_f32_e32 v117, v93, v93
	v_pk_add_f32 v[98:99], v[98:99], v[98:99] op_sel:[0,1] op_sel_hi:[1,0]
	v_pk_add_f32 v[102:103], v[102:103], v[102:103] op_sel:[0,1] op_sel_hi:[1,0]
	v_lshlrev_b32_e32 v88, 16, v89
	v_and_b32_e32 v89, 0xffff0000, v89
	v_pk_fma_f32 v[106:107], v[104:105], v[104:105], v[106:107]
	v_pk_fma_f32 v[110:111], v[108:109], v[108:109], v[110:111]
	v_mov_b32_e32 v99, v116
	v_mov_b32_e32 v103, v117
	v_mul_f32_e32 v118, v88, v88
	v_mul_f32_e32 v119, v89, v89
	v_pk_add_f32 v[98:99], v[98:99], v[102:103]
	v_pk_add_f32 v[102:103], v[106:107], v[106:107] op_sel:[0,1] op_sel_hi:[1,0]
	v_pk_add_f32 v[106:107], v[110:111], v[110:111] op_sel:[0,1] op_sel_hi:[1,0]
	v_mov_b32_e32 v103, v118
	v_mov_b32_e32 v107, v119
	v_lshlrev_b32_e32 v112, 16, v84
	v_and_b32_e32 v113, 0xffff0000, v84
	v_lshlrev_b32_e32 v84, 16, v85
	v_and_b32_e32 v85, 0xffff0000, v85
	v_pk_add_f32 v[102:103], v[102:103], v[106:107]
	v_lshlrev_b32_e32 v94, 16, v90
	v_and_b32_e32 v95, 0xffff0000, v90
	v_pk_add_f32 v[98:99], v[98:99], v[102:103]
	v_mul_f32_e32 v102, v113, v113
	v_mul_f32_e32 v106, v85, v85
	v_mul_f32_e32 v120, v94, v94
	v_mul_f32_e32 v121, v95, v95
	v_pk_fma_f32 v[102:103], v[112:113], v[112:113], v[102:103] op_sel_hi:[1,1,0]
	v_pk_fma_f32 v[106:107], v[84:85], v[84:85], v[106:107] op_sel_hi:[1,1,0]
	v_lshlrev_b32_e32 v114, 16, v86
	v_and_b32_e32 v115, 0xffff0000, v86
	v_lshlrev_b32_e32 v86, 16, v87
	v_and_b32_e32 v87, 0xffff0000, v87
	v_mov_b32_e32 v103, v120
	v_mov_b32_e32 v107, v121
	v_lshlrev_b32_e32 v90, 16, v91
	v_and_b32_e32 v91, 0xffff0000, v91
	v_pk_add_f32 v[102:103], v[102:103], v[106:107]
	v_mul_f32_e32 v106, v115, v115
	v_mul_f32_e32 v110, v87, v87
	v_mul_f32_e32 v122, v90, v90
	v_mul_f32_e32 v123, v91, v91
	v_pk_fma_f32 v[106:107], v[114:115], v[114:115], v[106:107] op_sel_hi:[1,1,0]
	v_pk_fma_f32 v[110:111], v[86:87], v[86:87], v[110:111] op_sel_hi:[1,1,0]
	v_mov_b32_e32 v107, v122
	v_mov_b32_e32 v111, v123
	v_pk_add_f32 v[106:107], v[106:107], v[110:111]
	s_nop 0
	v_pk_add_f32 v[102:103], v[102:103], v[106:107]
	s_nop 0
	v_pk_add_f32 v[98:99], v[98:99], v[102:103]
	s_nop 0
	v_add_f32_e32 v98, v98, v99
	v_mbcnt_lo_u32_b32 v99, -1, 0
	v_mbcnt_hi_u32_b32 v99, -1, v99
	s_nop 0
	v_lshlrev_b32_e32 v99, 2, v99
	v_xor_b32_e32 v99, 4, v99
	ds_bpermute_b32 v99, v99, v98
	s_waitcnt lgkmcnt(0)
	v_add_f32_e32 v98, v98, v99
	v_mbcnt_lo_u32_b32 v99, -1, 0
	v_mbcnt_hi_u32_b32 v99, -1, v99
	s_nop 0
	v_lshlrev_b32_e32 v99, 2, v99
	v_xor_b32_e32 v99, 8, v99
	ds_bpermute_b32 v99, v99, v98
	s_waitcnt lgkmcnt(0)
	v_add_f32_e32 v98, v98, v99
	v_mbcnt_lo_u32_b32 v99, -1, 0
	v_mbcnt_hi_u32_b32 v99, -1, v99
	s_nop 0
	v_lshlrev_b32_e32 v99, 2, v99
	v_xor_b32_e32 v99, 16, v99
	ds_bpermute_b32 v99, v99, v98
	s_waitcnt lgkmcnt(0)
	v_add_f32_e32 v98, v98, v99
	v_mbcnt_lo_u32_b32 v99, -1, 0
	v_mbcnt_hi_u32_b32 v99, -1, v99
	s_nop 0
	v_lshlrev_b32_e32 v99, 2, v99
	v_xor_b32_e32 v99, 32, v99
	ds_bpermute_b32 v99, v99, v98
	s_waitcnt lgkmcnt(0)
	v_add_f32_e32 v98, v98, v99
	v_mbcnt_lo_u32_b32 v99, -1, 0
	v_mbcnt_hi_u32_b32 v99, -1, v99
	s_nop 0
	v_lshlrev_b32_e32 v99, 2, v99
	v_xor_b32_e32 v99, 64, v99
	ds_bpermute_b32 v99, v99, v98
	s_waitcnt lgkmcnt(0)
	v_add_f32_e32 v98, v98, v99
	v_mbcnt_lo_u32_b32 v99, -1, 0
	v_mbcnt_hi_u32_b32 v99, -1, v99
	s_nop 0
	v_lshlrev_b32_e32 v99, 2, v99
	v_xor_b32_e32 v99, 0x80, v99
	ds_bpermute_b32 v99, v99, v98
	s_waitcnt lgkmcnt(0)
	v_add_f32_e32 v98, v98, v99
	v_fmamk_f32 v98, v98, 0x3a000000, v224
	v_cmp_gt_f32_e32 vcc, s41, v98
	v_mul_f32_e32 v99, 0x4f800000, v98
	s_nop 0
	v_cndmask_b32_e32 v98, v98, v99, vcc
	v_sqrt_f32_e32 v99, v98
	s_nop 0
	v_add_u32_e32 v102, -1, v99
	v_fma_f32 v103, -v102, v99, v98
	v_cmp_ge_f32_e64 s[0:1], 0, v103
	v_add_u32_e32 v103, 1, v99
	s_nop 0
	v_cndmask_b32_e64 v102, v99, v102, s[0:1]
	v_fma_f32 v99, -v103, v99, v98
	v_cmp_lt_f32_e64 s[0:1], 0, v99
	s_nop 1
	v_cndmask_b32_e64 v99, v102, v103, s[0:1]
	v_mul_f32_e32 v102, 0x37800000, v99
	v_cndmask_b32_e32 v99, v99, v102, vcc
	v_cmp_class_f32_e32 vcc, v98, v225
	s_nop 1
	v_cndmask_b32_e32 v98, v99, v98, vcc
	v_div_scale_f32 v99, s[0:1], v98, v98, 1.0
	v_rcp_f32_e32 v102, v99
	s_add_i32 s0, s4, -5
	s_ashr_i32 s1, s0, 31
	v_fma_f32 v103, -v99, v102, 1.0
	v_fmac_f32_e32 v102, v103, v102
	v_div_scale_f32 v103, vcc, 1.0, v98, 1.0
	v_mul_f32_e32 v106, v103, v102
	v_fma_f32 v107, -v99, v106, v103
	v_fmac_f32_e32 v106, v107, v102
	v_fma_f32 v99, -v99, v106, v103
	v_div_fmas_f32 v99, v99, v102, v106
	v_div_fixup_f32 v98, v99, v98, 1.0
	v_mov_b32_e32 v102, v96
	v_mov_b32_e32 v103, v76
	v_mov_b32_e32 v76, v97
	v_pk_mul_f32 v[102:103], v[98:99], v[102:103] op_sel_hi:[0,1]
	v_pk_mul_f32 v[76:77], v[98:99], v[76:77] op_sel_hi:[0,1]
	v_pk_fma_f32 v[96:97], v[48:49], v[76:77], v[6:7]
	v_pk_fma_f32 v[76:77], v[50:51], v[102:103], v[4:5]
	v_mov_b32_e32 v102, v100
	v_mov_b32_e32 v103, v78
	v_mov_b32_e32 v78, v101
	v_pk_mul_f32 v[102:103], v[98:99], v[102:103] op_sel_hi:[0,1]
	v_pk_mul_f32 v[78:79], v[98:99], v[78:79] op_sel_hi:[0,1]
	v_pk_fma_f32 v[100:101], v[44:45], v[78:79], v[2:3]
; __device__ __forceinline__ v4u pk8(f32x4 a, f32x4 b) { v4u w; w.x = pk2(a[0], a[1]); w.y = pk2(a[2], a[3]); w.z = pk2(b[0], b[1]); w.w = pk2(b[2], b[3]); return w; }
; __device__ __forceinline__ float ssq8(const f32x4& a, const f32x4& b) { return ((a[0] * a[0] + a[1] * a[1]) + (a[2] * a[2] + a[3] * a[3])) + ((b[0] * b[0] + b[1] * b[1]) + (b[2] * b[2] + b[3] * b[3])); }
; template <int XF32> __device__ __forceinline__ void norm_mod_phase(const void* x, const float* modl, int ch_shift, int ch_scale, bf16* H, int gw, int NGW, int lane) {
;     ...
;         for (int rr = 0; rr < 8; ++rr) {
;             const unsigned char* xr = (const unsigned char*)x + (size_t)(r0 + rr) * rowb; f32x4 v[4][2]; float s = 0.f;
; #pragma unroll
;             for (int j = 0; j < 4; ++j) ld_row8<XF32>(xr, lane, j, v[j][0], v[j][1]);
; #pragma unroll
;             for (int j = 0; j < 4; ++j) s += ssq8(v[j][0], v[j][1]);
;             const float rstd = 1.f / sqrtf(wave_sum(s) * (1.f / DM) + EPS);
;             v4u* o = (v4u*)(H + (size_t)(r0 + rr) * DM);
; #pragma unroll
;             for (int j = 0; j < 4; ++j) o[lane + 64 * j] = pk8(v[j][0] * rstd * sc[j][0] + sh[j][0], v[j][1] * rstd * sc[j][1] + sh[j][1]);
	v_pk_fma_f32 v[78:79], v[46:47], v[102:103], v[0:1]
	v_cvt_pk_bf16_f32 v76, v76, v77
	v_cvt_pk_bf16_f32 v77, v96, v97
	v_cvt_pk_bf16_f32 v78, v78, v79
	v_cvt_pk_bf16_f32 v79, v100, v101
	v_lshl_add_u64 v[96:97], v[34:35], 0, s[60:61]
	global_store_dwordx4 v[96:97], v[76:79], off
	s_lshl_b64 s[60:61], s[0:1], 12
	s_nop 0
	v_mov_b32_e32 v77, v80
	v_mov_b32_e32 v80, v105
	v_mov_b32_e32 v76, v104
	v_pk_mul_f32 v[78:79], v[98:99], v[80:81] op_sel_hi:[0,1]
	v_mov_b32_e32 v80, v108
	v_mov_b32_e32 v81, v82
	v_mov_b32_e32 v82, v109
	v_pk_mul_f32 v[76:77], v[98:99], v[76:77] op_sel_hi:[0,1]
	v_pk_mul_f32 v[80:81], v[98:99], v[80:81] op_sel_hi:[0,1]
	v_pk_mul_f32 v[82:83], v[98:99], v[82:83] op_sel_hi:[0,1]
	v_pk_fma_f32 v[78:79], v[56:57], v[78:79], v[14:15]
	v_pk_fma_f32 v[76:77], v[58:59], v[76:77], v[12:13]
	v_pk_fma_f32 v[82:83], v[52:53], v[82:83], v[10:11]
	v_pk_fma_f32 v[80:81], v[54:55], v[80:81], v[8:9]
	v_cvt_pk_bf16_f32 v76, v76, v77
	v_cvt_pk_bf16_f32 v77, v78, v79
	v_cvt_pk_bf16_f32 v78, v80, v81
	v_cvt_pk_bf16_f32 v79, v82, v83
	global_store_dwordx4 v[96:97], v[76:79], off offset:1024
	v_pk_mul_f32 v[80:81], v[98:99], v[114:115] op_sel_hi:[0,1]
	v_pk_mul_f32 v[82:83], v[98:99], v[86:87] op_sel_hi:[0,1]
	v_pk_mul_f32 v[76:77], v[98:99], v[112:113] op_sel_hi:[0,1]
	v_pk_mul_f32 v[78:79], v[98:99], v[84:85] op_sel_hi:[0,1]
	v_pk_fma_f32 v[78:79], v[64:65], v[78:79], v[22:23]
	v_pk_fma_f32 v[76:77], v[66:67], v[76:77], v[20:21]
	v_pk_fma_f32 v[82:83], v[60:61], v[82:83], v[18:19]
	v_pk_fma_f32 v[80:81], v[62:63], v[80:81], v[16:17]
	v_cvt_pk_bf16_f32 v76, v76, v77
	v_cvt_pk_bf16_f32 v77, v78, v79
	v_cvt_pk_bf16_f32 v78, v80, v81
	v_cvt_pk_bf16_f32 v79, v82, v83
	global_store_dwordx4 v[96:97], v[76:79], off offset:2048
	v_pk_mul_f32 v[80:81], v[94:95], v[98:99] op_sel_hi:[1,0]
	v_pk_mul_f32 v[82:83], v[90:91], v[98:99] op_sel_hi:[1,0]
	v_pk_mul_f32 v[76:77], v[92:93], v[98:99] op_sel_hi:[1,0]
	v_pk_mul_f32 v[78:79], v[88:89], v[98:99] op_sel_hi:[1,0]
	v_pk_fma_f32 v[76:77], v[74:75], v[76:77], v[28:29]
	v_pk_fma_f32 v[78:79], v[72:73], v[78:79], v[30:31]
	v_pk_fma_f32 v[82:83], v[68:69], v[82:83], v[26:27]
	v_pk_fma_f32 v[80:81], v[70:71], v[80:81], v[24:25]
	v_cvt_pk_bf16_f32 v76, v76, v77
	v_cvt_pk_bf16_f32 v77, v78, v79
	v_cvt_pk_bf16_f32 v78, v80, v81
	v_cvt_pk_bf16_f32 v79, v82, v83
	global_store_dwordx4 v[96:97], v[76:79], off offset:3072
	v_lshl_add_u64 v[88:89], v[32:33], 0, s[60:61]
	global_load_dwordx4 v[76:79], v[88:89], off
	global_load_dwordx4 v[80:83], v[88:89], off offset:1024
	global_load_dwordx4 v[84:87], v[88:89], off offset:2048
	s_nop 0
	global_load_dwordx4 v[88:91], v[88:89], off offset:3072
	s_waitcnt vmcnt(3)
	v_lshlrev_b32_e32 v97, 16, v77
	v_lshlrev_b32_e32 v96, 16, v76
	v_and_b32_e32 v77, 0xffff0000, v77
	v_and_b32_e32 v76, 0xffff0000, v76
	v_lshlrev_b32_e32 v101, 16, v79
	v_lshlrev_b32_e32 v100, 16, v78
	v_and_b32_e32 v79, 0xffff0000, v79
	v_and_b32_e32 v78, 0xffff0000, v78
	v_pk_mul_f32 v[98:99], v[76:77], v[76:77]
	v_pk_mul_f32 v[102:103], v[78:79], v[78:79]
	s_waitcnt vmcnt(0)
	v_lshlrev_b32_e32 v92, 16, v88
	v_and_b32_e32 v93, 0xffff0000, v88
	v_pk_fma_f32 v[98:99], v[96:97], v[96:97], v[98:99]
	v_pk_fma_f32 v[102:103], v[100:101], v[100:101], v[102:103]
	v_lshlrev_b32_e32 v105, 16, v81
	v_lshlrev_b32_e32 v104, 16, v80
	v_and_b32_e32 v81, 0xffff0000, v81
	v_and_b32_e32 v80, 0xffff0000, v80
	v_lshlrev_b32_e32 v109, 16, v83
	v_lshlrev_b32_e32 v108, 16, v82
	v_and_b32_e32 v83, 0xffff0000, v83
	v_and_b32_e32 v82, 0xffff0000, v82
	v_pk_mul_f32 v[106:107], v[80:81], v[80:81]
	v_pk_mul_f32 v[110:111], v[82:83], v[82:83]
	v_mul_f32_e32 v116, v92, v92
	v_mul_f32_e32 v117, v93, v93
	v_pk_add_f32 v[98:99], v[98:99], v[98:99] op_sel:[0,1] op_sel_hi:[1,0]
	v_pk_add_f32 v[102:103], v[102:103], v[102:103] op_sel:[0,1] op_sel_hi:[1,0]
	v_lshlrev_b32_e32 v88, 16, v89
	v_and_b32_e32 v89, 0xffff0000, v89
	v_pk_fma_f32 v[106:107], v[104:105], v[104:105], v[106:107]
	v_pk_fma_f32 v[110:111], v[108:109], v[108:109], v[110:111]
	v_mov_b32_e32 v99, v116
	v_mov_b32_e32 v103, v117
	v_mul_f32_e32 v118, v88, v88
	v_mul_f32_e32 v119, v89, v89
	v_pk_add_f32 v[98:99], v[98:99], v[102:103]
	v_pk_add_f32 v[102:103], v[106:107], v[106:107] op_sel:[0,1] op_sel_hi:[1,0]
	v_pk_add_f32 v[106:107], v[110:111], v[110:111] op_sel:[0,1] op_sel_hi:[1,0]
	v_mov_b32_e32 v103, v118
	v_mov_b32_e32 v107, v119
	v_lshlrev_b32_e32 v112, 16, v84
	v_and_b32_e32 v113, 0xffff0000, v84
	v_lshlrev_b32_e32 v84, 16, v85
	v_and_b32_e32 v85, 0xffff0000, v85
	v_pk_add_f32 v[102:103], v[102:103], v[106:107]
	v_lshlrev_b32_e32 v94, 16, v90
	v_and_b32_e32 v95, 0xffff0000, v90
	v_pk_add_f32 v[98:99], v[98:99], v[102:103]
	v_mul_f32_e32 v102, v113, v113
	v_mul_f32_e32 v106, v85, v85
	v_mul_f32_e32 v120, v94, v94
	v_mul_f32_e32 v121, v95, v95
	v_pk_fma_f32 v[102:103], v[112:113], v[112:113], v[102:103] op_sel_hi:[1,1,0]
	v_pk_fma_f32 v[106:107], v[84:85], v[84:85], v[106:107] op_sel_hi:[1,1,0]
	v_lshlrev_b32_e32 v114, 16, v86
	v_and_b32_e32 v115, 0xffff0000, v86
	v_lshlrev_b32_e32 v86, 16, v87
	v_and_b32_e32 v87, 0xffff0000, v87
	v_mov_b32_e32 v103, v120
	v_mov_b32_e32 v107, v121
	v_lshlrev_b32_e32 v90, 16, v91
	v_and_b32_e32 v91, 0xffff0000, v91
	v_pk_add_f32 v[102:103], v[102:103], v[106:107]
	v_mul_f32_e32 v106, v115, v115
	v_mul_f32_e32 v110, v87, v87
	v_mul_f32_e32 v122, v90, v90
	v_mul_f32_e32 v123, v91, v91
	v_pk_fma_f32 v[106:107], v[114:115], v[114:115], v[106:107] op_sel_hi:[1,1,0]
	v_pk_fma_f32 v[110:111], v[86:87], v[86:87], v[110:111] op_sel_hi:[1,1,0]
	v_mov_b32_e32 v107, v122
	v_mov_b32_e32 v111, v123
	v_pk_add_f32 v[106:107], v[106:107], v[110:111]
	s_nop 0
	v_pk_add_f32 v[102:103], v[102:103], v[106:107]
	s_nop 0
	v_pk_add_f32 v[98:99], v[98:99], v[102:103]
	s_nop 0
	v_add_f32_e32 v98, v98, v99
	v_mbcnt_lo_u32_b32 v99, -1, 0
	v_mbcnt_hi_u32_b32 v99, -1, v99
	s_nop 0
	v_lshlrev_b32_e32 v99, 2, v99
	v_xor_b32_e32 v99, 4, v99
	ds_bpermute_b32 v99, v99, v98
	s_waitcnt lgkmcnt(0)
; __device__ __forceinline__ v4u pk8(f32x4 a, f32x4 b) { v4u w; w.x = pk2(a[0], a[1]); w.y = pk2(a[2], a[3]); w.z = pk2(b[0], b[1]); w.w = pk2(b[2], b[3]); return w; }
; __device__ __forceinline__ float shfl_xor_f(float v, int o) {
;     int l; asm volatile("v_mbcnt_lo_u32_b32 %0, -1, 0\n\tv_mbcnt_hi_u32_b32 %0, -1, %0" : "=v"(l));
;     return __builtin_bit_cast(float, __builtin_amdgcn_ds_bpermute((l ^ o) << 2, __builtin_bit_cast(int, v)));
; }
; __device__ __forceinline__ float wave_sum(float v) {
; #pragma unroll
;     for (int o = 1; o < 64; o <<= 1) v += shfl_xor_f(v, o);
;     return v;
; template <int XF32> __device__ __forceinline__ void norm_mod_phase(const void* x, const float* modl, int ch_shift, int ch_scale, bf16* H, int gw, int NGW, int lane) {
;     ...
;             const float rstd = 1.f / sqrtf(wave_sum(s) * (1.f / DM) + EPS);
;             v4u* o = (v4u*)(H + (size_t)(r0 + rr) * DM);
; #pragma unroll
;             for (int j = 0; j < 4; ++j) o[lane + 64 * j] = pk8(v[j][0] * rstd * sc[j][0] + sh[j][0], v[j][1] * rstd * sc[j][1] + sh[j][1]);
	v_add_f32_e32 v98, v98, v99
	v_mbcnt_lo_u32_b32 v99, -1, 0
	v_mbcnt_hi_u32_b32 v99, -1, v99
	s_nop 0
	v_lshlrev_b32_e32 v99, 2, v99
	v_xor_b32_e32 v99, 8, v99
	ds_bpermute_b32 v99, v99, v98
	s_waitcnt lgkmcnt(0)
	v_add_f32_e32 v98, v98, v99
	v_mbcnt_lo_u32_b32 v99, -1, 0
	v_mbcnt_hi_u32_b32 v99, -1, v99
	s_nop 0
	v_lshlrev_b32_e32 v99, 2, v99
	v_xor_b32_e32 v99, 16, v99
	ds_bpermute_b32 v99, v99, v98
	s_waitcnt lgkmcnt(0)
	v_add_f32_e32 v98, v98, v99
	v_mbcnt_lo_u32_b32 v99, -1, 0
	v_mbcnt_hi_u32_b32 v99, -1, v99
	s_nop 0
	v_lshlrev_b32_e32 v99, 2, v99
	v_xor_b32_e32 v99, 32, v99
	ds_bpermute_b32 v99, v99, v98
	s_waitcnt lgkmcnt(0)
	v_add_f32_e32 v98, v98, v99
	v_mbcnt_lo_u32_b32 v99, -1, 0
	v_mbcnt_hi_u32_b32 v99, -1, v99
	s_nop 0
	v_lshlrev_b32_e32 v99, 2, v99
	v_xor_b32_e32 v99, 64, v99
	ds_bpermute_b32 v99, v99, v98
	s_waitcnt lgkmcnt(0)
	v_add_f32_e32 v98, v98, v99
	v_mbcnt_lo_u32_b32 v99, -1, 0
	v_mbcnt_hi_u32_b32 v99, -1, v99
	s_nop 0
	v_lshlrev_b32_e32 v99, 2, v99
	v_xor_b32_e32 v99, 0x80, v99
	ds_bpermute_b32 v99, v99, v98
	s_waitcnt lgkmcnt(0)
	v_add_f32_e32 v98, v98, v99
	v_fmamk_f32 v98, v98, 0x3a000000, v224
	v_cmp_gt_f32_e32 vcc, s41, v98
	v_mul_f32_e32 v99, 0x4f800000, v98
	s_nop 0
	v_cndmask_b32_e32 v98, v98, v99, vcc
	v_sqrt_f32_e32 v99, v98
	s_nop 0
	v_add_u32_e32 v102, -1, v99
	v_fma_f32 v103, -v102, v99, v98
	v_cmp_ge_f32_e64 s[0:1], 0, v103
	v_add_u32_e32 v103, 1, v99
	s_nop 0
	v_cndmask_b32_e64 v102, v99, v102, s[0:1]
	v_fma_f32 v99, -v103, v99, v98
	v_cmp_lt_f32_e64 s[0:1], 0, v99
	s_nop 1
	v_cndmask_b32_e64 v99, v102, v103, s[0:1]
	v_mul_f32_e32 v102, 0x37800000, v99
	v_cndmask_b32_e32 v99, v99, v102, vcc
	v_cmp_class_f32_e32 vcc, v98, v225
	s_nop 1
	v_cndmask_b32_e32 v98, v99, v98, vcc
	v_div_scale_f32 v99, s[0:1], v98, v98, 1.0
	v_rcp_f32_e32 v102, v99
	s_add_i32 s0, s4, -4
	s_ashr_i32 s1, s0, 31
	v_fma_f32 v103, -v99, v102, 1.0
	v_fmac_f32_e32 v102, v103, v102
	v_div_scale_f32 v103, vcc, 1.0, v98, 1.0
	v_mul_f32_e32 v106, v103, v102
	v_fma_f32 v107, -v99, v106, v103
	v_fmac_f32_e32 v106, v107, v102
	v_fma_f32 v99, -v99, v106, v103
	v_div_fmas_f32 v99, v99, v102, v106
	v_div_fixup_f32 v98, v99, v98, 1.0
	v_mov_b32_e32 v102, v96
	v_mov_b32_e32 v103, v76
	v_mov_b32_e32 v76, v97
	v_pk_mul_f32 v[102:103], v[98:99], v[102:103] op_sel_hi:[0,1]
	v_pk_mul_f32 v[76:77], v[98:99], v[76:77] op_sel_hi:[0,1]
	v_pk_fma_f32 v[96:97], v[48:49], v[76:77], v[6:7]
	v_pk_fma_f32 v[76:77], v[50:51], v[102:103], v[4:5]
	v_mov_b32_e32 v102, v100
	v_mov_b32_e32 v103, v78
	v_mov_b32_e32 v78, v101
	v_pk_mul_f32 v[102:103], v[98:99], v[102:103] op_sel_hi:[0,1]
	v_pk_mul_f32 v[78:79], v[98:99], v[78:79] op_sel_hi:[0,1]
	v_pk_fma_f32 v[100:101], v[44:45], v[78:79], v[2:3]
	v_pk_fma_f32 v[78:79], v[46:47], v[102:103], v[0:1]
	v_cvt_pk_bf16_f32 v76, v76, v77
	v_cvt_pk_bf16_f32 v77, v96, v97
	v_cvt_pk_bf16_f32 v78, v78, v79
	v_cvt_pk_bf16_f32 v79, v100, v101
	v_lshl_add_u64 v[96:97], v[34:35], 0, s[60:61]
	global_store_dwordx4 v[96:97], v[76:79], off
	s_lshl_b64 s[60:61], s[0:1], 12
	s_nop 0
	v_mov_b32_e32 v77, v80
	v_mov_b32_e32 v80, v105
	v_mov_b32_e32 v76, v104
	v_pk_mul_f32 v[78:79], v[98:99], v[80:81] op_sel_hi:[0,1]
	v_mov_b32_e32 v80, v108
	v_mov_b32_e32 v81, v82
	v_mov_b32_e32 v82, v109
	v_pk_mul_f32 v[76:77], v[98:99], v[76:77] op_sel_hi:[0,1]
	v_pk_mul_f32 v[80:81], v[98:99], v[80:81] op_sel_hi:[0,1]
	v_pk_mul_f32 v[82:83], v[98:99], v[82:83] op_sel_hi:[0,1]
	v_pk_fma_f32 v[78:79], v[56:57], v[78:79], v[14:15]
	v_pk_fma_f32 v[76:77], v[58:59], v[76:77], v[12:13]
	v_pk_fma_f32 v[82:83], v[52:53], v[82:83], v[10:11]
	v_pk_fma_f32 v[80:81], v[54:55], v[80:81], v[8:9]
	v_cvt_pk_bf16_f32 v76, v76, v77
	v_cvt_pk_bf16_f32 v77, v78, v79
	v_cvt_pk_bf16_f32 v78, v80, v81
	v_cvt_pk_bf16_f32 v79, v82, v83
	global_store_dwordx4 v[96:97], v[76:79], off offset:1024
	v_pk_mul_f32 v[80:81], v[98:99], v[114:115] op_sel_hi:[0,1]
	v_pk_mul_f32 v[82:83], v[98:99], v[86:87] op_sel_hi:[0,1]
	v_pk_mul_f32 v[76:77], v[98:99], v[112:113] op_sel_hi:[0,1]
	v_pk_mul_f32 v[78:79], v[98:99], v[84:85] op_sel_hi:[0,1]
	v_pk_fma_f32 v[78:79], v[64:65], v[78:79], v[22:23]
	v_pk_fma_f32 v[76:77], v[66:67], v[76:77], v[20:21]
	v_pk_fma_f32 v[82:83], v[60:61], v[82:83], v[18:19]
	v_pk_fma_f32 v[80:81], v[62:63], v[80:81], v[16:17]
	v_cvt_pk_bf16_f32 v76, v76, v77
	v_cvt_pk_bf16_f32 v77, v78, v79
	v_cvt_pk_bf16_f32 v78, v80, v81
	v_cvt_pk_bf16_f32 v79, v82, v83
	global_store_dwordx4 v[96:97], v[76:79], off offset:2048
	v_pk_mul_f32 v[80:81], v[94:95], v[98:99] op_sel_hi:[1,0]
	v_pk_mul_f32 v[82:83], v[90:91], v[98:99] op_sel_hi:[1,0]
	v_pk_mul_f32 v[76:77], v[92:93], v[98:99] op_sel_hi:[1,0]
	v_pk_mul_f32 v[78:79], v[88:89], v[98:99] op_sel_hi:[1,0]
	v_pk_fma_f32 v[76:77], v[74:75], v[76:77], v[28:29]
	v_pk_fma_f32 v[78:79], v[72:73], v[78:79], v[30:31]
	v_pk_fma_f32 v[82:83], v[68:69], v[82:83], v[26:27]
	v_pk_fma_f32 v[80:81], v[70:71], v[80:81], v[24:25]
	v_cvt_pk_bf16_f32 v76, v76, v77
	v_cvt_pk_bf16_f32 v77, v78, v79
	v_cvt_pk_bf16_f32 v78, v80, v81
	v_cvt_pk_bf16_f32 v79, v82, v83
	global_store_dwordx4 v[96:97], v[76:79], off offset:3072
	v_lshl_add_u64 v[88:89], v[32:33], 0, s[60:61]
	global_load_dwordx4 v[76:79], v[88:89], off
	global_load_dwordx4 v[80:83], v[88:89], off offset:1024
	global_load_dwordx4 v[84:87], v[88:89], off offset:2048
	s_nop 0
	global_load_dwordx4 v[88:91], v[88:89], off offset:3072
	s_waitcnt vmcnt(3)
	v_lshlrev_b32_e32 v97, 16, v77
	v_lshlrev_b32_e32 v96, 16, v76
	v_and_b32_e32 v77, 0xffff0000, v77
	v_and_b32_e32 v76, 0xffff0000, v76
	v_lshlrev_b32_e32 v101, 16, v79
	v_lshlrev_b32_e32 v100, 16, v78
	v_and_b32_e32 v79, 0xffff0000, v79
	v_and_b32_e32 v78, 0xffff0000, v78
	v_pk_mul_f32 v[98:99], v[76:77], v[76:77]
	v_pk_mul_f32 v[102:103], v[78:79], v[78:79]
	s_waitcnt vmcnt(0)
; __device__ __forceinline__ v4u pk8(f32x4 a, f32x4 b) { v4u w; w.x = pk2(a[0], a[1]); w.y = pk2(a[2], a[3]); w.z = pk2(b[0], b[1]); w.w = pk2(b[2], b[3]); return w; }
; __device__ __forceinline__ float ssq8(const f32x4& a, const f32x4& b) { return ((a[0] * a[0] + a[1] * a[1]) + (a[2] * a[2] + a[3] * a[3])) + ((b[0] * b[0] + b[1] * b[1]) + (b[2] * b[2] + b[3] * b[3])); }
; __device__ __forceinline__ float shfl_xor_f(float v, int o) {
;     int l; asm volatile("v_mbcnt_lo_u32_b32 %0, -1, 0\n\tv_mbcnt_hi_u32_b32 %0, -1, %0" : "=v"(l));
;     return __builtin_bit_cast(float, __builtin_amdgcn_ds_bpermute((l ^ o) << 2, __builtin_bit_cast(int, v)));
; }
; __device__ __forceinline__ float wave_sum(float v) {
; #pragma unroll
;     for (int o = 1; o < 64; o <<= 1) v += shfl_xor_f(v, o);
;     return v;
; template <int XF32> __device__ __forceinline__ void norm_mod_phase(const void* x, const float* modl, int ch_shift, int ch_scale, bf16* H, int gw, int NGW, int lane) {
;     ...
;         for (int rr = 0; rr < 8; ++rr) {
;             const unsigned char* xr = (const unsigned char*)x + (size_t)(r0 + rr) * rowb; f32x4 v[4][2]; float s = 0.f;
; #pragma unroll
;             for (int j = 0; j < 4; ++j) ld_row8<XF32>(xr, lane, j, v[j][0], v[j][1]);
; #pragma unroll
;             for (int j = 0; j < 4; ++j) s += ssq8(v[j][0], v[j][1]);
;             const float rstd = 1.f / sqrtf(wave_sum(s) * (1.f / DM) + EPS);
;             v4u* o = (v4u*)(H + (size_t)(r0 + rr) * DM);
; #pragma unroll
;             for (int j = 0; j < 4; ++j) o[lane + 64 * j] = pk8(v[j][0] * rstd * sc[j][0] + sh[j][0], v[j][1] * rstd * sc[j][1] + sh[j][1]);
	v_lshlrev_b32_e32 v92, 16, v88
	v_and_b32_e32 v93, 0xffff0000, v88
	v_pk_fma_f32 v[98:99], v[96:97], v[96:97], v[98:99]
	v_pk_fma_f32 v[102:103], v[100:101], v[100:101], v[102:103]
	v_lshlrev_b32_e32 v105, 16, v81
	v_lshlrev_b32_e32 v104, 16, v80
	v_and_b32_e32 v81, 0xffff0000, v81
	v_and_b32_e32 v80, 0xffff0000, v80
	v_lshlrev_b32_e32 v109, 16, v83
	v_lshlrev_b32_e32 v108, 16, v82
	v_and_b32_e32 v83, 0xffff0000, v83
	v_and_b32_e32 v82, 0xffff0000, v82
	v_pk_mul_f32 v[106:107], v[80:81], v[80:81]
	v_pk_mul_f32 v[110:111], v[82:83], v[82:83]
	v_mul_f32_e32 v116, v92, v92
	v_mul_f32_e32 v117, v93, v93
	v_pk_add_f32 v[98:99], v[98:99], v[98:99] op_sel:[0,1] op_sel_hi:[1,0]
	v_pk_add_f32 v[102:103], v[102:103], v[102:103] op_sel:[0,1] op_sel_hi:[1,0]
	v_lshlrev_b32_e32 v88, 16, v89
	v_and_b32_e32 v89, 0xffff0000, v89
	v_pk_fma_f32 v[106:107], v[104:105], v[104:105], v[106:107]
	v_pk_fma_f32 v[110:111], v[108:109], v[108:109], v[110:111]
	v_mov_b32_e32 v99, v116
	v_mov_b32_e32 v103, v117
	v_mul_f32_e32 v118, v88, v88
	v_mul_f32_e32 v119, v89, v89
	v_pk_add_f32 v[98:99], v[98:99], v[102:103]
	v_pk_add_f32 v[102:103], v[106:107], v[106:107] op_sel:[0,1] op_sel_hi:[1,0]
	v_pk_add_f32 v[106:107], v[110:111], v[110:111] op_sel:[0,1] op_sel_hi:[1,0]
	v_mov_b32_e32 v103, v118
	v_mov_b32_e32 v107, v119
	v_lshlrev_b32_e32 v112, 16, v84
	v_and_b32_e32 v113, 0xffff0000, v84
	v_lshlrev_b32_e32 v84, 16, v85
	v_and_b32_e32 v85, 0xffff0000, v85
	v_pk_add_f32 v[102:103], v[102:103], v[106:107]
	v_lshlrev_b32_e32 v94, 16, v90
	v_and_b32_e32 v95, 0xffff0000, v90
	v_pk_add_f32 v[98:99], v[98:99], v[102:103]
	v_mul_f32_e32 v102, v113, v113
	v_mul_f32_e32 v106, v85, v85
	v_mul_f32_e32 v120, v94, v94
	v_mul_f32_e32 v121, v95, v95
	v_pk_fma_f32 v[102:103], v[112:113], v[112:113], v[102:103] op_sel_hi:[1,1,0]
	v_pk_fma_f32 v[106:107], v[84:85], v[84:85], v[106:107] op_sel_hi:[1,1,0]
	v_lshlrev_b32_e32 v114, 16, v86
	v_and_b32_e32 v115, 0xffff0000, v86
	v_lshlrev_b32_e32 v86, 16, v87
	v_and_b32_e32 v87, 0xffff0000, v87
	v_mov_b32_e32 v103, v120
	v_mov_b32_e32 v107, v121
	v_lshlrev_b32_e32 v90, 16, v91
	v_and_b32_e32 v91, 0xffff0000, v91
	v_pk_add_f32 v[102:103], v[102:103], v[106:107]
	v_mul_f32_e32 v106, v115, v115
	v_mul_f32_e32 v110, v87, v87
	v_mul_f32_e32 v122, v90, v90
	v_mul_f32_e32 v123, v91, v91
	v_pk_fma_f32 v[106:107], v[114:115], v[114:115], v[106:107] op_sel_hi:[1,1,0]
	v_pk_fma_f32 v[110:111], v[86:87], v[86:87], v[110:111] op_sel_hi:[1,1,0]
	v_mov_b32_e32 v107, v122
	v_mov_b32_e32 v111, v123
	v_pk_add_f32 v[106:107], v[106:107], v[110:111]
	s_nop 0
	v_pk_add_f32 v[102:103], v[102:103], v[106:107]
	s_nop 0
	v_pk_add_f32 v[98:99], v[98:99], v[102:103]
	s_nop 0
	v_add_f32_e32 v98, v98, v99
	v_mbcnt_lo_u32_b32 v99, -1, 0
	v_mbcnt_hi_u32_b32 v99, -1, v99
	s_nop 0
	v_lshlrev_b32_e32 v99, 2, v99
	v_xor_b32_e32 v99, 4, v99
	ds_bpermute_b32 v99, v99, v98
	s_waitcnt lgkmcnt(0)
	v_add_f32_e32 v98, v98, v99
	v_mbcnt_lo_u32_b32 v99, -1, 0
	v_mbcnt_hi_u32_b32 v99, -1, v99
	s_nop 0
	v_lshlrev_b32_e32 v99, 2, v99
	v_xor_b32_e32 v99, 8, v99
	ds_bpermute_b32 v99, v99, v98
	s_waitcnt lgkmcnt(0)
	v_add_f32_e32 v98, v98, v99
	v_mbcnt_lo_u32_b32 v99, -1, 0
	v_mbcnt_hi_u32_b32 v99, -1, v99
	s_nop 0
	v_lshlrev_b32_e32 v99, 2, v99
	v_xor_b32_e32 v99, 16, v99
	ds_bpermute_b32 v99, v99, v98
	s_waitcnt lgkmcnt(0)
	v_add_f32_e32 v98, v98, v99
	v_mbcnt_lo_u32_b32 v99, -1, 0
	v_mbcnt_hi_u32_b32 v99, -1, v99
	s_nop 0
	v_lshlrev_b32_e32 v99, 2, v99
	v_xor_b32_e32 v99, 32, v99
	ds_bpermute_b32 v99, v99, v98
	s_waitcnt lgkmcnt(0)
	v_add_f32_e32 v98, v98, v99
	v_mbcnt_lo_u32_b32 v99, -1, 0
	v_mbcnt_hi_u32_b32 v99, -1, v99
	s_nop 0
	v_lshlrev_b32_e32 v99, 2, v99
	v_xor_b32_e32 v99, 64, v99
	ds_bpermute_b32 v99, v99, v98
	s_waitcnt lgkmcnt(0)
	v_add_f32_e32 v98, v98, v99
	v_mbcnt_lo_u32_b32 v99, -1, 0
	v_mbcnt_hi_u32_b32 v99, -1, v99
	s_nop 0
	v_lshlrev_b32_e32 v99, 2, v99
	v_xor_b32_e32 v99, 0x80, v99
	ds_bpermute_b32 v99, v99, v98
	s_waitcnt lgkmcnt(0)
	v_add_f32_e32 v98, v98, v99
	v_fmamk_f32 v98, v98, 0x3a000000, v224
	v_cmp_gt_f32_e32 vcc, s41, v98
	v_mul_f32_e32 v99, 0x4f800000, v98
	s_nop 0
	v_cndmask_b32_e32 v98, v98, v99, vcc
	v_sqrt_f32_e32 v99, v98
	s_nop 0
	v_add_u32_e32 v102, -1, v99
	v_fma_f32 v103, -v102, v99, v98
	v_cmp_ge_f32_e64 s[0:1], 0, v103
	v_add_u32_e32 v103, 1, v99
	s_nop 0
	v_cndmask_b32_e64 v102, v99, v102, s[0:1]
	v_fma_f32 v99, -v103, v99, v98
	v_cmp_lt_f32_e64 s[0:1], 0, v99
	s_nop 1
	v_cndmask_b32_e64 v99, v102, v103, s[0:1]
	v_mul_f32_e32 v102, 0x37800000, v99
	v_cndmask_b32_e32 v99, v99, v102, vcc
	v_cmp_class_f32_e32 vcc, v98, v225
	s_nop 1
	v_cndmask_b32_e32 v98, v99, v98, vcc
	v_div_scale_f32 v99, s[0:1], v98, v98, 1.0
	v_rcp_f32_e32 v102, v99
	s_add_i32 s0, s4, -3
	s_ashr_i32 s1, s0, 31
	v_fma_f32 v103, -v99, v102, 1.0
	v_fmac_f32_e32 v102, v103, v102
	v_div_scale_f32 v103, vcc, 1.0, v98, 1.0
	v_mul_f32_e32 v106, v103, v102
	v_fma_f32 v107, -v99, v106, v103
	v_fmac_f32_e32 v106, v107, v102
	v_fma_f32 v99, -v99, v106, v103
	v_div_fmas_f32 v99, v99, v102, v106
	v_div_fixup_f32 v98, v99, v98, 1.0
	v_mov_b32_e32 v102, v96
	v_mov_b32_e32 v103, v76
	v_mov_b32_e32 v76, v97
	v_pk_mul_f32 v[102:103], v[98:99], v[102:103] op_sel_hi:[0,1]
	v_pk_mul_f32 v[76:77], v[98:99], v[76:77] op_sel_hi:[0,1]
	v_pk_fma_f32 v[96:97], v[48:49], v[76:77], v[6:7]
	v_pk_fma_f32 v[76:77], v[50:51], v[102:103], v[4:5]
	v_mov_b32_e32 v102, v100
	v_mov_b32_e32 v103, v78
	v_mov_b32_e32 v78, v101
	v_pk_mul_f32 v[102:103], v[98:99], v[102:103] op_sel_hi:[0,1]
	v_pk_mul_f32 v[78:79], v[98:99], v[78:79] op_sel_hi:[0,1]
	v_pk_fma_f32 v[100:101], v[44:45], v[78:79], v[2:3]
; __device__ __forceinline__ v4u pk8(f32x4 a, f32x4 b) { v4u w; w.x = pk2(a[0], a[1]); w.y = pk2(a[2], a[3]); w.z = pk2(b[0], b[1]); w.w = pk2(b[2], b[3]); return w; }
; __device__ __forceinline__ float ssq8(const f32x4& a, const f32x4& b) { return ((a[0] * a[0] + a[1] * a[1]) + (a[2] * a[2] + a[3] * a[3])) + ((b[0] * b[0] + b[1] * b[1]) + (b[2] * b[2] + b[3] * b[3])); }
; __device__ __forceinline__ float shfl_xor_f(float v, int o) {
;     int l; asm volatile("v_mbcnt_lo_u32_b32 %0, -1, 0\n\tv_mbcnt_hi_u32_b32 %0, -1, %0" : "=v"(l));
;     return __builtin_bit_cast(float, __builtin_amdgcn_ds_bpermute((l ^ o) << 2, __builtin_bit_cast(int, v)));
; }
; __device__ __forceinline__ float wave_sum(float v) {
; #pragma unroll
;     for (int o = 1; o < 64; o <<= 1) v += shfl_xor_f(v, o);
; template <int XF32> __device__ __forceinline__ void norm_mod_phase(const void* x, const float* modl, int ch_shift, int ch_scale, bf16* H, int gw, int NGW, int lane) {
;     ...
;         for (int rr = 0; rr < 8; ++rr) {
;             const unsigned char* xr = (const unsigned char*)x + (size_t)(r0 + rr) * rowb; f32x4 v[4][2]; float s = 0.f;
; #pragma unroll
;             for (int j = 0; j < 4; ++j) ld_row8<XF32>(xr, lane, j, v[j][0], v[j][1]);
; #pragma unroll
;             for (int j = 0; j < 4; ++j) s += ssq8(v[j][0], v[j][1]);
;             const float rstd = 1.f / sqrtf(wave_sum(s) * (1.f / DM) + EPS);
;             v4u* o = (v4u*)(H + (size_t)(r0 + rr) * DM);
; #pragma unroll
;             for (int j = 0; j < 4; ++j) o[lane + 64 * j] = pk8(v[j][0] * rstd * sc[j][0] + sh[j][0], v[j][1] * rstd * sc[j][1] + sh[j][1]);
	v_pk_fma_f32 v[78:79], v[46:47], v[102:103], v[0:1]
	v_cvt_pk_bf16_f32 v76, v76, v77
	v_cvt_pk_bf16_f32 v77, v96, v97
	v_cvt_pk_bf16_f32 v78, v78, v79
	v_cvt_pk_bf16_f32 v79, v100, v101
	v_lshl_add_u64 v[96:97], v[34:35], 0, s[60:61]
	global_store_dwordx4 v[96:97], v[76:79], off
	s_lshl_b64 s[60:61], s[0:1], 12
	s_nop 0
	v_mov_b32_e32 v77, v80
	v_mov_b32_e32 v80, v105
	v_mov_b32_e32 v76, v104
	v_pk_mul_f32 v[78:79], v[98:99], v[80:81] op_sel_hi:[0,1]
	v_mov_b32_e32 v80, v108
	v_mov_b32_e32 v81, v82
	v_mov_b32_e32 v82, v109
	v_pk_mul_f32 v[76:77], v[98:99], v[76:77] op_sel_hi:[0,1]
	v_pk_mul_f32 v[80:81], v[98:99], v[80:81] op_sel_hi:[0,1]
	v_pk_mul_f32 v[82:83], v[98:99], v[82:83] op_sel_hi:[0,1]
	v_pk_fma_f32 v[78:79], v[56:57], v[78:79], v[14:15]
	v_pk_fma_f32 v[76:77], v[58:59], v[76:77], v[12:13]
	v_pk_fma_f32 v[82:83], v[52:53], v[82:83], v[10:11]
	v_pk_fma_f32 v[80:81], v[54:55], v[80:81], v[8:9]
	v_cvt_pk_bf16_f32 v76, v76, v77
	v_cvt_pk_bf16_f32 v77, v78, v79
	v_cvt_pk_bf16_f32 v78, v80, v81
	v_cvt_pk_bf16_f32 v79, v82, v83
	global_store_dwordx4 v[96:97], v[76:79], off offset:1024
	v_pk_mul_f32 v[80:81], v[98:99], v[114:115] op_sel_hi:[0,1]
	v_pk_mul_f32 v[82:83], v[98:99], v[86:87] op_sel_hi:[0,1]
	v_pk_mul_f32 v[76:77], v[98:99], v[112:113] op_sel_hi:[0,1]
	v_pk_mul_f32 v[78:79], v[98:99], v[84:85] op_sel_hi:[0,1]
	v_pk_fma_f32 v[78:79], v[64:65], v[78:79], v[22:23]
	v_pk_fma_f32 v[76:77], v[66:67], v[76:77], v[20:21]
	v_pk_fma_f32 v[82:83], v[60:61], v[82:83], v[18:19]
	v_pk_fma_f32 v[80:81], v[62:63], v[80:81], v[16:17]
	v_cvt_pk_bf16_f32 v76, v76, v77
	v_cvt_pk_bf16_f32 v77, v78, v79
	v_cvt_pk_bf16_f32 v78, v80, v81
	v_cvt_pk_bf16_f32 v79, v82, v83
	global_store_dwordx4 v[96:97], v[76:79], off offset:2048
	v_pk_mul_f32 v[80:81], v[94:95], v[98:99] op_sel_hi:[1,0]
	v_pk_mul_f32 v[82:83], v[90:91], v[98:99] op_sel_hi:[1,0]
	v_pk_mul_f32 v[76:77], v[92:93], v[98:99] op_sel_hi:[1,0]
	v_pk_mul_f32 v[78:79], v[88:89], v[98:99] op_sel_hi:[1,0]
	v_pk_fma_f32 v[76:77], v[74:75], v[76:77], v[28:29]
	v_pk_fma_f32 v[78:79], v[72:73], v[78:79], v[30:31]
	v_pk_fma_f32 v[82:83], v[68:69], v[82:83], v[26:27]
	v_pk_fma_f32 v[80:81], v[70:71], v[80:81], v[24:25]
	v_cvt_pk_bf16_f32 v76, v76, v77
	v_cvt_pk_bf16_f32 v77, v78, v79
	v_cvt_pk_bf16_f32 v78, v80, v81
	v_cvt_pk_bf16_f32 v79, v82, v83
	global_store_dwordx4 v[96:97], v[76:79], off offset:3072
	v_lshl_add_u64 v[88:89], v[32:33], 0, s[60:61]
	global_load_dwordx4 v[76:79], v[88:89], off
	global_load_dwordx4 v[80:83], v[88:89], off offset:1024
	global_load_dwordx4 v[84:87], v[88:89], off offset:2048
	s_nop 0
	global_load_dwordx4 v[88:91], v[88:89], off offset:3072
	s_waitcnt vmcnt(3)
	v_lshlrev_b32_e32 v97, 16, v77
	v_lshlrev_b32_e32 v96, 16, v76
	v_and_b32_e32 v77, 0xffff0000, v77
	v_and_b32_e32 v76, 0xffff0000, v76
	v_lshlrev_b32_e32 v101, 16, v79
	v_lshlrev_b32_e32 v100, 16, v78
	v_and_b32_e32 v79, 0xffff0000, v79
	v_and_b32_e32 v78, 0xffff0000, v78
	v_pk_mul_f32 v[98:99], v[76:77], v[76:77]
	v_pk_mul_f32 v[102:103], v[78:79], v[78:79]
	s_waitcnt vmcnt(0)
	v_lshlrev_b32_e32 v92, 16, v88
	v_and_b32_e32 v93, 0xffff0000, v88
	v_pk_fma_f32 v[98:99], v[96:97], v[96:97], v[98:99]
	v_pk_fma_f32 v[102:103], v[100:101], v[100:101], v[102:103]
	v_lshlrev_b32_e32 v105, 16, v81
	v_lshlrev_b32_e32 v104, 16, v80
	v_and_b32_e32 v81, 0xffff0000, v81
	v_and_b32_e32 v80, 0xffff0000, v80
	v_lshlrev_b32_e32 v109, 16, v83
	v_lshlrev_b32_e32 v108, 16, v82
	v_and_b32_e32 v83, 0xffff0000, v83
	v_and_b32_e32 v82, 0xffff0000, v82
	v_pk_mul_f32 v[106:107], v[80:81], v[80:81]
	v_pk_mul_f32 v[110:111], v[82:83], v[82:83]
	v_mul_f32_e32 v116, v92, v92
	v_mul_f32_e32 v117, v93, v93
	v_pk_add_f32 v[98:99], v[98:99], v[98:99] op_sel:[0,1] op_sel_hi:[1,0]
	v_pk_add_f32 v[102:103], v[102:103], v[102:103] op_sel:[0,1] op_sel_hi:[1,0]
	v_lshlrev_b32_e32 v88, 16, v89
	v_and_b32_e32 v89, 0xffff0000, v89
	v_pk_fma_f32 v[106:107], v[104:105], v[104:105], v[106:107]
	v_pk_fma_f32 v[110:111], v[108:109], v[108:109], v[110:111]
	v_mov_b32_e32 v99, v116
	v_mov_b32_e32 v103, v117
	v_mul_f32_e32 v118, v88, v88
	v_mul_f32_e32 v119, v89, v89
	v_pk_add_f32 v[98:99], v[98:99], v[102:103]
	v_pk_add_f32 v[102:103], v[106:107], v[106:107] op_sel:[0,1] op_sel_hi:[1,0]
	v_pk_add_f32 v[106:107], v[110:111], v[110:111] op_sel:[0,1] op_sel_hi:[1,0]
	v_mov_b32_e32 v103, v118
	v_mov_b32_e32 v107, v119
	v_lshlrev_b32_e32 v112, 16, v84
	v_and_b32_e32 v113, 0xffff0000, v84
	v_lshlrev_b32_e32 v84, 16, v85
	v_and_b32_e32 v85, 0xffff0000, v85
	v_pk_add_f32 v[102:103], v[102:103], v[106:107]
	v_lshlrev_b32_e32 v94, 16, v90
	v_and_b32_e32 v95, 0xffff0000, v90
	v_pk_add_f32 v[98:99], v[98:99], v[102:103]
	v_mul_f32_e32 v102, v113, v113
	v_mul_f32_e32 v106, v85, v85
	v_mul_f32_e32 v120, v94, v94
	v_mul_f32_e32 v121, v95, v95
	v_pk_fma_f32 v[102:103], v[112:113], v[112:113], v[102:103] op_sel_hi:[1,1,0]
	v_pk_fma_f32 v[106:107], v[84:85], v[84:85], v[106:107] op_sel_hi:[1,1,0]
	v_lshlrev_b32_e32 v114, 16, v86
	v_and_b32_e32 v115, 0xffff0000, v86
	v_lshlrev_b32_e32 v86, 16, v87
	v_and_b32_e32 v87, 0xffff0000, v87
	v_mov_b32_e32 v103, v120
	v_mov_b32_e32 v107, v121
	v_lshlrev_b32_e32 v90, 16, v91
	v_and_b32_e32 v91, 0xffff0000, v91
	v_pk_add_f32 v[102:103], v[102:103], v[106:107]
	v_mul_f32_e32 v106, v115, v115
	v_mul_f32_e32 v110, v87, v87
	v_mul_f32_e32 v122, v90, v90
	v_mul_f32_e32 v123, v91, v91
	v_pk_fma_f32 v[106:107], v[114:115], v[114:115], v[106:107] op_sel_hi:[1,1,0]
	v_pk_fma_f32 v[110:111], v[86:87], v[86:87], v[110:111] op_sel_hi:[1,1,0]
	v_mov_b32_e32 v107, v122
	v_mov_b32_e32 v111, v123
	v_pk_add_f32 v[106:107], v[106:107], v[110:111]
	s_nop 0
	v_pk_add_f32 v[102:103], v[102:103], v[106:107]
	s_nop 0
	v_pk_add_f32 v[98:99], v[98:99], v[102:103]
	s_nop 0
	v_add_f32_e32 v98, v98, v99
	v_mbcnt_lo_u32_b32 v99, -1, 0
	v_mbcnt_hi_u32_b32 v99, -1, v99
	s_nop 0
	v_lshlrev_b32_e32 v99, 2, v99
	v_xor_b32_e32 v99, 4, v99
	ds_bpermute_b32 v99, v99, v98
	s_waitcnt lgkmcnt(0)
; __device__ __forceinline__ v4u pk8(f32x4 a, f32x4 b) { v4u w; w.x = pk2(a[0], a[1]); w.y = pk2(a[2], a[3]); w.z = pk2(b[0], b[1]); w.w = pk2(b[2], b[3]); return w; }
; __device__ __forceinline__ float ssq8(const f32x4& a, const f32x4& b) { return ((a[0] * a[0] + a[1] * a[1]) + (a[2] * a[2] + a[3] * a[3])) + ((b[0] * b[0] + b[1] * b[1]) + (b[2] * b[2] + b[3] * b[3])); }
; __device__ __forceinline__ float shfl_xor_f(float v, int o) {
;     int l; asm volatile("v_mbcnt_lo_u32_b32 %0, -1, 0\n\tv_mbcnt_hi_u32_b32 %0, -1, %0" : "=v"(l));
;     return __builtin_bit_cast(float, __builtin_amdgcn_ds_bpermute((l ^ o) << 2, __builtin_bit_cast(int, v)));
; }
; __device__ __forceinline__ float wave_sum(float v) {
; #pragma unroll
;     for (int o = 1; o < 64; o <<= 1) v += shfl_xor_f(v, o);
; template <int XF32> __device__ __forceinline__ void norm_mod_phase(const void* x, const float* modl, int ch_shift, int ch_scale, bf16* H, int gw, int NGW, int lane) {
;     ...
;         for (int rr = 0; rr < 8; ++rr) {
;             const unsigned char* xr = (const unsigned char*)x + (size_t)(r0 + rr) * rowb; f32x4 v[4][2]; float s = 0.f;
; #pragma unroll
;             for (int j = 0; j < 4; ++j) ld_row8<XF32>(xr, lane, j, v[j][0], v[j][1]);
; #pragma unroll
;             for (int j = 0; j < 4; ++j) s += ssq8(v[j][0], v[j][1]);
;             const float rstd = 1.f / sqrtf(wave_sum(s) * (1.f / DM) + EPS);
;             v4u* o = (v4u*)(H + (size_t)(r0 + rr) * DM);
; #pragma unroll
;             for (int j = 0; j < 4; ++j) o[lane + 64 * j] = pk8(v[j][0] * rstd * sc[j][0] + sh[j][0], v[j][1] * rstd * sc[j][1] + sh[j][1]);
	v_add_f32_e32 v98, v98, v99
	v_mbcnt_lo_u32_b32 v99, -1, 0
	v_mbcnt_hi_u32_b32 v99, -1, v99
	s_nop 0
	v_lshlrev_b32_e32 v99, 2, v99
	v_xor_b32_e32 v99, 8, v99
	ds_bpermute_b32 v99, v99, v98
	s_waitcnt lgkmcnt(0)
	v_add_f32_e32 v98, v98, v99
	v_mbcnt_lo_u32_b32 v99, -1, 0
	v_mbcnt_hi_u32_b32 v99, -1, v99
	s_nop 0
	v_lshlrev_b32_e32 v99, 2, v99
	v_xor_b32_e32 v99, 16, v99
	ds_bpermute_b32 v99, v99, v98
	s_waitcnt lgkmcnt(0)
	v_add_f32_e32 v98, v98, v99
	v_mbcnt_lo_u32_b32 v99, -1, 0
	v_mbcnt_hi_u32_b32 v99, -1, v99
	s_nop 0
	v_lshlrev_b32_e32 v99, 2, v99
	v_xor_b32_e32 v99, 32, v99
	ds_bpermute_b32 v99, v99, v98
	s_waitcnt lgkmcnt(0)
	v_add_f32_e32 v98, v98, v99
	v_mbcnt_lo_u32_b32 v99, -1, 0
	v_mbcnt_hi_u32_b32 v99, -1, v99
	s_nop 0
	v_lshlrev_b32_e32 v99, 2, v99
	v_xor_b32_e32 v99, 64, v99
	ds_bpermute_b32 v99, v99, v98
	s_waitcnt lgkmcnt(0)
	v_add_f32_e32 v98, v98, v99
	v_mbcnt_lo_u32_b32 v99, -1, 0
	v_mbcnt_hi_u32_b32 v99, -1, v99
	s_nop 0
	v_lshlrev_b32_e32 v99, 2, v99
	v_xor_b32_e32 v99, 0x80, v99
	ds_bpermute_b32 v99, v99, v98
	s_waitcnt lgkmcnt(0)
	v_add_f32_e32 v98, v98, v99
	v_fmamk_f32 v98, v98, 0x3a000000, v224
	v_cmp_gt_f32_e32 vcc, s41, v98
	v_mul_f32_e32 v99, 0x4f800000, v98
	s_nop 0
	v_cndmask_b32_e32 v98, v98, v99, vcc
	v_sqrt_f32_e32 v99, v98
	s_nop 0
	v_add_u32_e32 v102, -1, v99
	v_fma_f32 v103, -v102, v99, v98
	v_cmp_ge_f32_e64 s[0:1], 0, v103
	v_add_u32_e32 v103, 1, v99
	s_nop 0
	v_cndmask_b32_e64 v102, v99, v102, s[0:1]
	v_fma_f32 v99, -v103, v99, v98
	v_cmp_lt_f32_e64 s[0:1], 0, v99
	s_nop 1
	v_cndmask_b32_e64 v99, v102, v103, s[0:1]
	v_mul_f32_e32 v102, 0x37800000, v99
	v_cndmask_b32_e32 v99, v99, v102, vcc
	v_cmp_class_f32_e32 vcc, v98, v225
	s_nop 1
	v_cndmask_b32_e32 v98, v99, v98, vcc
	v_div_scale_f32 v99, s[0:1], v98, v98, 1.0
	v_rcp_f32_e32 v102, v99
	s_add_i32 s0, s4, -2
	s_ashr_i32 s1, s0, 31
	v_fma_f32 v103, -v99, v102, 1.0
	v_fmac_f32_e32 v102, v103, v102
	v_div_scale_f32 v103, vcc, 1.0, v98, 1.0
	v_mul_f32_e32 v106, v103, v102
	v_fma_f32 v107, -v99, v106, v103
	v_fmac_f32_e32 v106, v107, v102
	v_fma_f32 v99, -v99, v106, v103
	v_div_fmas_f32 v99, v99, v102, v106
	v_div_fixup_f32 v98, v99, v98, 1.0
	v_mov_b32_e32 v102, v96
	v_mov_b32_e32 v103, v76
	v_mov_b32_e32 v76, v97
	v_pk_mul_f32 v[102:103], v[98:99], v[102:103] op_sel_hi:[0,1]
	v_pk_mul_f32 v[76:77], v[98:99], v[76:77] op_sel_hi:[0,1]
	v_pk_fma_f32 v[96:97], v[48:49], v[76:77], v[6:7]
	v_pk_fma_f32 v[76:77], v[50:51], v[102:103], v[4:5]
	v_mov_b32_e32 v102, v100
	v_mov_b32_e32 v103, v78
	v_mov_b32_e32 v78, v101
	v_pk_mul_f32 v[102:103], v[98:99], v[102:103] op_sel_hi:[0,1]
	v_pk_mul_f32 v[78:79], v[98:99], v[78:79] op_sel_hi:[0,1]
	v_pk_fma_f32 v[100:101], v[44:45], v[78:79], v[2:3]
	v_pk_fma_f32 v[78:79], v[46:47], v[102:103], v[0:1]
	v_cvt_pk_bf16_f32 v76, v76, v77
	v_cvt_pk_bf16_f32 v77, v96, v97
	v_cvt_pk_bf16_f32 v78, v78, v79
	v_cvt_pk_bf16_f32 v79, v100, v101
	v_lshl_add_u64 v[96:97], v[34:35], 0, s[60:61]
	global_store_dwordx4 v[96:97], v[76:79], off
	s_lshl_b64 s[60:61], s[0:1], 12
	s_nop 0
	v_mov_b32_e32 v77, v80
	v_mov_b32_e32 v80, v105
	v_mov_b32_e32 v76, v104
	v_pk_mul_f32 v[78:79], v[98:99], v[80:81] op_sel_hi:[0,1]
	v_mov_b32_e32 v80, v108
	v_mov_b32_e32 v81, v82
	v_mov_b32_e32 v82, v109
	v_pk_mul_f32 v[76:77], v[98:99], v[76:77] op_sel_hi:[0,1]
	v_pk_mul_f32 v[80:81], v[98:99], v[80:81] op_sel_hi:[0,1]
	v_pk_mul_f32 v[82:83], v[98:99], v[82:83] op_sel_hi:[0,1]
	v_pk_fma_f32 v[78:79], v[56:57], v[78:79], v[14:15]
	v_pk_fma_f32 v[76:77], v[58:59], v[76:77], v[12:13]
	v_pk_fma_f32 v[82:83], v[52:53], v[82:83], v[10:11]
	v_pk_fma_f32 v[80:81], v[54:55], v[80:81], v[8:9]
	v_cvt_pk_bf16_f32 v76, v76, v77
	v_cvt_pk_bf16_f32 v77, v78, v79
	v_cvt_pk_bf16_f32 v78, v80, v81
	v_cvt_pk_bf16_f32 v79, v82, v83
	global_store_dwordx4 v[96:97], v[76:79], off offset:1024
	v_pk_mul_f32 v[80:81], v[98:99], v[114:115] op_sel_hi:[0,1]
	v_pk_mul_f32 v[82:83], v[98:99], v[86:87] op_sel_hi:[0,1]
	v_pk_mul_f32 v[76:77], v[98:99], v[112:113] op_sel_hi:[0,1]
	v_pk_mul_f32 v[78:79], v[98:99], v[84:85] op_sel_hi:[0,1]
	v_pk_fma_f32 v[78:79], v[64:65], v[78:79], v[22:23]
	v_pk_fma_f32 v[76:77], v[66:67], v[76:77], v[20:21]
	v_pk_fma_f32 v[82:83], v[60:61], v[82:83], v[18:19]
	v_pk_fma_f32 v[80:81], v[62:63], v[80:81], v[16:17]
	v_cvt_pk_bf16_f32 v76, v76, v77
	v_cvt_pk_bf16_f32 v77, v78, v79
	v_cvt_pk_bf16_f32 v78, v80, v81
	v_cvt_pk_bf16_f32 v79, v82, v83
	global_store_dwordx4 v[96:97], v[76:79], off offset:2048
	v_pk_mul_f32 v[80:81], v[94:95], v[98:99] op_sel_hi:[1,0]
	v_pk_mul_f32 v[82:83], v[90:91], v[98:99] op_sel_hi:[1,0]
	v_pk_mul_f32 v[76:77], v[92:93], v[98:99] op_sel_hi:[1,0]
	v_pk_mul_f32 v[78:79], v[88:89], v[98:99] op_sel_hi:[1,0]
	v_pk_fma_f32 v[76:77], v[74:75], v[76:77], v[28:29]
	v_pk_fma_f32 v[78:79], v[72:73], v[78:79], v[30:31]
	v_pk_fma_f32 v[82:83], v[68:69], v[82:83], v[26:27]
	v_pk_fma_f32 v[80:81], v[70:71], v[80:81], v[24:25]
	v_cvt_pk_bf16_f32 v76, v76, v77
	v_cvt_pk_bf16_f32 v77, v78, v79
	v_cvt_pk_bf16_f32 v78, v80, v81
	v_cvt_pk_bf16_f32 v79, v82, v83
	global_store_dwordx4 v[96:97], v[76:79], off offset:3072
	v_lshl_add_u64 v[88:89], v[32:33], 0, s[60:61]
	global_load_dwordx4 v[76:79], v[88:89], off
	global_load_dwordx4 v[80:83], v[88:89], off offset:1024
	global_load_dwordx4 v[84:87], v[88:89], off offset:2048
	s_nop 0
	global_load_dwordx4 v[88:91], v[88:89], off offset:3072
	s_waitcnt vmcnt(3)
	v_lshlrev_b32_e32 v97, 16, v77
	v_lshlrev_b32_e32 v96, 16, v76
	v_and_b32_e32 v77, 0xffff0000, v77
	v_and_b32_e32 v76, 0xffff0000, v76
	v_lshlrev_b32_e32 v101, 16, v79
	v_lshlrev_b32_e32 v100, 16, v78
	v_and_b32_e32 v79, 0xffff0000, v79
	v_and_b32_e32 v78, 0xffff0000, v78
	v_pk_mul_f32 v[98:99], v[76:77], v[76:77]
	v_pk_mul_f32 v[102:103], v[78:79], v[78:79]
	s_waitcnt vmcnt(0)
; __device__ __forceinline__ v4u pk8(f32x4 a, f32x4 b) { v4u w; w.x = pk2(a[0], a[1]); w.y = pk2(a[2], a[3]); w.z = pk2(b[0], b[1]); w.w = pk2(b[2], b[3]); return w; }
; __device__ __forceinline__ float ssq8(const f32x4& a, const f32x4& b) { return ((a[0] * a[0] + a[1] * a[1]) + (a[2] * a[2] + a[3] * a[3])) + ((b[0] * b[0] + b[1] * b[1]) + (b[2] * b[2] + b[3] * b[3])); }
; __device__ __forceinline__ float shfl_xor_f(float v, int o) {
;     int l; asm volatile("v_mbcnt_lo_u32_b32 %0, -1, 0\n\tv_mbcnt_hi_u32_b32 %0, -1, %0" : "=v"(l));
;     return __builtin_bit_cast(float, __builtin_amdgcn_ds_bpermute((l ^ o) << 2, __builtin_bit_cast(int, v)));
; }
; __device__ __forceinline__ float wave_sum(float v) {
; #pragma unroll
;     for (int o = 1; o < 64; o <<= 1) v += shfl_xor_f(v, o);
; template <int XF32> __device__ __forceinline__ void norm_mod_phase(const void* x, const float* modl, int ch_shift, int ch_scale, bf16* H, int gw, int NGW, int lane) {
;     ...
;         for (int rr = 0; rr < 8; ++rr) {
;             const unsigned char* xr = (const unsigned char*)x + (size_t)(r0 + rr) * rowb; f32x4 v[4][2]; float s = 0.f;
; #pragma unroll
;             for (int j = 0; j < 4; ++j) ld_row8<XF32>(xr, lane, j, v[j][0], v[j][1]);
; #pragma unroll
;             for (int j = 0; j < 4; ++j) s += ssq8(v[j][0], v[j][1]);
;             const float rstd = 1.f / sqrtf(wave_sum(s) * (1.f / DM) + EPS);
;             v4u* o = (v4u*)(H + (size_t)(r0 + rr) * DM);
; #pragma unroll
;             for (int j = 0; j < 4; ++j) o[lane + 64 * j] = pk8(v[j][0] * rstd * sc[j][0] + sh[j][0], v[j][1] * rstd * sc[j][1] + sh[j][1]);
	v_lshlrev_b32_e32 v92, 16, v88
	v_and_b32_e32 v93, 0xffff0000, v88
	v_pk_fma_f32 v[98:99], v[96:97], v[96:97], v[98:99]
	v_pk_fma_f32 v[102:103], v[100:101], v[100:101], v[102:103]
	v_lshlrev_b32_e32 v105, 16, v81
	v_lshlrev_b32_e32 v104, 16, v80
	v_and_b32_e32 v81, 0xffff0000, v81
	v_and_b32_e32 v80, 0xffff0000, v80
	v_lshlrev_b32_e32 v109, 16, v83
	v_lshlrev_b32_e32 v108, 16, v82
	v_and_b32_e32 v83, 0xffff0000, v83
	v_and_b32_e32 v82, 0xffff0000, v82
	v_pk_mul_f32 v[106:107], v[80:81], v[80:81]
	v_pk_mul_f32 v[110:111], v[82:83], v[82:83]
	v_mul_f32_e32 v116, v92, v92
	v_mul_f32_e32 v117, v93, v93
	v_pk_add_f32 v[98:99], v[98:99], v[98:99] op_sel:[0,1] op_sel_hi:[1,0]
	v_pk_add_f32 v[102:103], v[102:103], v[102:103] op_sel:[0,1] op_sel_hi:[1,0]
	v_lshlrev_b32_e32 v88, 16, v89
	v_and_b32_e32 v89, 0xffff0000, v89
	v_pk_fma_f32 v[106:107], v[104:105], v[104:105], v[106:107]
	v_pk_fma_f32 v[110:111], v[108:109], v[108:109], v[110:111]
	v_mov_b32_e32 v99, v116
	v_mov_b32_e32 v103, v117
	v_mul_f32_e32 v118, v88, v88
	v_mul_f32_e32 v119, v89, v89
	v_pk_add_f32 v[98:99], v[98:99], v[102:103]
	v_pk_add_f32 v[102:103], v[106:107], v[106:107] op_sel:[0,1] op_sel_hi:[1,0]
	v_pk_add_f32 v[106:107], v[110:111], v[110:111] op_sel:[0,1] op_sel_hi:[1,0]
	v_mov_b32_e32 v103, v118
	v_mov_b32_e32 v107, v119
	v_lshlrev_b32_e32 v112, 16, v84
	v_and_b32_e32 v113, 0xffff0000, v84
	v_lshlrev_b32_e32 v84, 16, v85
	v_and_b32_e32 v85, 0xffff0000, v85
	v_pk_add_f32 v[102:103], v[102:103], v[106:107]
	v_lshlrev_b32_e32 v94, 16, v90
	v_and_b32_e32 v95, 0xffff0000, v90
	v_pk_add_f32 v[98:99], v[98:99], v[102:103]
	v_mul_f32_e32 v102, v113, v113
	v_mul_f32_e32 v106, v85, v85
	v_mul_f32_e32 v120, v94, v94
	v_mul_f32_e32 v121, v95, v95
	v_pk_fma_f32 v[102:103], v[112:113], v[112:113], v[102:103] op_sel_hi:[1,1,0]
	v_pk_fma_f32 v[106:107], v[84:85], v[84:85], v[106:107] op_sel_hi:[1,1,0]
	v_lshlrev_b32_e32 v114, 16, v86
	v_and_b32_e32 v115, 0xffff0000, v86
	v_lshlrev_b32_e32 v86, 16, v87
	v_and_b32_e32 v87, 0xffff0000, v87
	v_mov_b32_e32 v103, v120
	v_mov_b32_e32 v107, v121
	v_lshlrev_b32_e32 v90, 16, v91
	v_and_b32_e32 v91, 0xffff0000, v91
	v_pk_add_f32 v[102:103], v[102:103], v[106:107]
	v_mul_f32_e32 v106, v115, v115
	v_mul_f32_e32 v110, v87, v87
	v_mul_f32_e32 v122, v90, v90
	v_mul_f32_e32 v123, v91, v91
	v_pk_fma_f32 v[106:107], v[114:115], v[114:115], v[106:107] op_sel_hi:[1,1,0]
	v_pk_fma_f32 v[110:111], v[86:87], v[86:87], v[110:111] op_sel_hi:[1,1,0]
	v_mov_b32_e32 v107, v122
	v_mov_b32_e32 v111, v123
	v_pk_add_f32 v[106:107], v[106:107], v[110:111]
	s_nop 0
	v_pk_add_f32 v[102:103], v[102:103], v[106:107]
	s_nop 0
	v_pk_add_f32 v[98:99], v[98:99], v[102:103]
	s_nop 0
	v_add_f32_e32 v98, v98, v99
	v_mbcnt_lo_u32_b32 v99, -1, 0
	v_mbcnt_hi_u32_b32 v99, -1, v99
	s_nop 0
	v_lshlrev_b32_e32 v99, 2, v99
	v_xor_b32_e32 v99, 4, v99
	ds_bpermute_b32 v99, v99, v98
	s_waitcnt lgkmcnt(0)
	v_add_f32_e32 v98, v98, v99
	v_mbcnt_lo_u32_b32 v99, -1, 0
	v_mbcnt_hi_u32_b32 v99, -1, v99
	s_nop 0
	v_lshlrev_b32_e32 v99, 2, v99
	v_xor_b32_e32 v99, 8, v99
	ds_bpermute_b32 v99, v99, v98
	s_waitcnt lgkmcnt(0)
	v_add_f32_e32 v98, v98, v99
	v_mbcnt_lo_u32_b32 v99, -1, 0
	v_mbcnt_hi_u32_b32 v99, -1, v99
	s_nop 0
	v_lshlrev_b32_e32 v99, 2, v99
	v_xor_b32_e32 v99, 16, v99
	ds_bpermute_b32 v99, v99, v98
	s_waitcnt lgkmcnt(0)
	v_add_f32_e32 v98, v98, v99
	v_mbcnt_lo_u32_b32 v99, -1, 0
	v_mbcnt_hi_u32_b32 v99, -1, v99
	s_nop 0
	v_lshlrev_b32_e32 v99, 2, v99
	v_xor_b32_e32 v99, 32, v99
	ds_bpermute_b32 v99, v99, v98
	s_waitcnt lgkmcnt(0)
	v_add_f32_e32 v98, v98, v99
	v_mbcnt_lo_u32_b32 v99, -1, 0
	v_mbcnt_hi_u32_b32 v99, -1, v99
	s_nop 0
	v_lshlrev_b32_e32 v99, 2, v99
	v_xor_b32_e32 v99, 64, v99
	ds_bpermute_b32 v99, v99, v98
	s_waitcnt lgkmcnt(0)
	v_add_f32_e32 v98, v98, v99
	v_mbcnt_lo_u32_b32 v99, -1, 0
	v_mbcnt_hi_u32_b32 v99, -1, v99
	s_nop 0
	v_lshlrev_b32_e32 v99, 2, v99
	v_xor_b32_e32 v99, 0x80, v99
	ds_bpermute_b32 v99, v99, v98
	s_waitcnt lgkmcnt(0)
	v_add_f32_e32 v98, v98, v99
	v_fmamk_f32 v98, v98, 0x3a000000, v224
	v_cmp_gt_f32_e32 vcc, s41, v98
	v_mul_f32_e32 v99, 0x4f800000, v98
	s_nop 0
	v_cndmask_b32_e32 v98, v98, v99, vcc
	v_sqrt_f32_e32 v99, v98
	s_nop 0
	v_add_u32_e32 v102, -1, v99
	v_fma_f32 v103, -v102, v99, v98
	v_cmp_ge_f32_e64 s[0:1], 0, v103
	v_add_u32_e32 v103, 1, v99
	s_nop 0
	v_cndmask_b32_e64 v102, v99, v102, s[0:1]
	v_fma_f32 v99, -v103, v99, v98
	v_cmp_lt_f32_e64 s[0:1], 0, v99
	s_nop 1
	v_cndmask_b32_e64 v99, v102, v103, s[0:1]
	v_mul_f32_e32 v102, 0x37800000, v99
	v_cndmask_b32_e32 v99, v99, v102, vcc
	v_cmp_class_f32_e32 vcc, v98, v225
	s_nop 1
	v_cndmask_b32_e32 v98, v99, v98, vcc
	v_div_scale_f32 v99, s[0:1], v98, v98, 1.0
	v_rcp_f32_e32 v102, v99
	s_add_i32 s0, s4, -1
	s_ashr_i32 s1, s0, 31
	v_fma_f32 v103, -v99, v102, 1.0
	v_fmac_f32_e32 v102, v103, v102
	v_div_scale_f32 v103, vcc, 1.0, v98, 1.0
	v_mul_f32_e32 v106, v103, v102
	v_fma_f32 v107, -v99, v106, v103
	v_fmac_f32_e32 v106, v107, v102
	v_fma_f32 v99, -v99, v106, v103
	v_div_fmas_f32 v99, v99, v102, v106
	v_div_fixup_f32 v98, v99, v98, 1.0
	v_mov_b32_e32 v102, v96
	v_mov_b32_e32 v103, v76
	v_mov_b32_e32 v76, v97
	v_pk_mul_f32 v[102:103], v[98:99], v[102:103] op_sel_hi:[0,1]
	v_pk_mul_f32 v[76:77], v[98:99], v[76:77] op_sel_hi:[0,1]
	v_pk_fma_f32 v[96:97], v[48:49], v[76:77], v[6:7]
	v_pk_fma_f32 v[76:77], v[50:51], v[102:103], v[4:5]
	v_mov_b32_e32 v102, v100
	v_mov_b32_e32 v103, v78
	v_mov_b32_e32 v78, v101
	v_pk_mul_f32 v[102:103], v[98:99], v[102:103] op_sel_hi:[0,1]
	v_pk_mul_f32 v[78:79], v[98:99], v[78:79] op_sel_hi:[0,1]
	v_pk_fma_f32 v[100:101], v[44:45], v[78:79], v[2:3]
; __device__ __forceinline__ v4u pk8(f32x4 a, f32x4 b) { v4u w; w.x = pk2(a[0], a[1]); w.y = pk2(a[2], a[3]); w.z = pk2(b[0], b[1]); w.w = pk2(b[2], b[3]); return w; }
; __device__ __forceinline__ float ssq8(const f32x4& a, const f32x4& b) { return ((a[0] * a[0] + a[1] * a[1]) + (a[2] * a[2] + a[3] * a[3])) + ((b[0] * b[0] + b[1] * b[1]) + (b[2] * b[2] + b[3] * b[3])); }
; __device__ __forceinline__ float shfl_xor_f(float v, int o) {
;     int l; asm volatile("v_mbcnt_lo_u32_b32 %0, -1, 0\n\tv_mbcnt_hi_u32_b32 %0, -1, %0" : "=v"(l));
;     return __builtin_bit_cast(float, __builtin_amdgcn_ds_bpermute((l ^ o) << 2, __builtin_bit_cast(int, v)));
; }
; __device__ __forceinline__ float wave_sum(float v) {
; #pragma unroll
;     for (int o = 1; o < 64; o <<= 1) v += shfl_xor_f(v, o);
; template <int XF32> __device__ __forceinline__ void norm_mod_phase(const void* x, const float* modl, int ch_shift, int ch_scale, bf16* H, int gw, int NGW, int lane) {
;     ...
;         for (int rr = 0; rr < 8; ++rr) {
;             const unsigned char* xr = (const unsigned char*)x + (size_t)(r0 + rr) * rowb; f32x4 v[4][2]; float s = 0.f;
; #pragma unroll
;             for (int j = 0; j < 4; ++j) ld_row8<XF32>(xr, lane, j, v[j][0], v[j][1]);
; #pragma unroll
;             for (int j = 0; j < 4; ++j) s += ssq8(v[j][0], v[j][1]);
;             const float rstd = 1.f / sqrtf(wave_sum(s) * (1.f / DM) + EPS);
;             v4u* o = (v4u*)(H + (size_t)(r0 + rr) * DM);
; #pragma unroll
;             for (int j = 0; j < 4; ++j) o[lane + 64 * j] = pk8(v[j][0] * rstd * sc[j][0] + sh[j][0], v[j][1] * rstd * sc[j][1] + sh[j][1]);
	v_pk_fma_f32 v[78:79], v[46:47], v[102:103], v[0:1]
	v_cvt_pk_bf16_f32 v76, v76, v77
	v_cvt_pk_bf16_f32 v77, v96, v97
	v_cvt_pk_bf16_f32 v78, v78, v79
	v_cvt_pk_bf16_f32 v79, v100, v101
	v_lshl_add_u64 v[96:97], v[34:35], 0, s[60:61]
	global_store_dwordx4 v[96:97], v[76:79], off
	s_lshl_b64 s[60:61], s[0:1], 12
	s_nop 0
	v_mov_b32_e32 v77, v80
	v_mov_b32_e32 v80, v105
	v_mov_b32_e32 v76, v104
	v_pk_mul_f32 v[78:79], v[98:99], v[80:81] op_sel_hi:[0,1]
	v_mov_b32_e32 v80, v108
	v_mov_b32_e32 v81, v82
	v_mov_b32_e32 v82, v109
	v_pk_mul_f32 v[76:77], v[98:99], v[76:77] op_sel_hi:[0,1]
	v_pk_mul_f32 v[80:81], v[98:99], v[80:81] op_sel_hi:[0,1]
	v_pk_mul_f32 v[82:83], v[98:99], v[82:83] op_sel_hi:[0,1]
	v_pk_fma_f32 v[78:79], v[56:57], v[78:79], v[14:15]
	v_pk_fma_f32 v[76:77], v[58:59], v[76:77], v[12:13]
	v_pk_fma_f32 v[82:83], v[52:53], v[82:83], v[10:11]
	v_pk_fma_f32 v[80:81], v[54:55], v[80:81], v[8:9]
	v_cvt_pk_bf16_f32 v76, v76, v77
	v_cvt_pk_bf16_f32 v77, v78, v79
	v_cvt_pk_bf16_f32 v78, v80, v81
	v_cvt_pk_bf16_f32 v79, v82, v83
	global_store_dwordx4 v[96:97], v[76:79], off offset:1024
	v_pk_mul_f32 v[80:81], v[98:99], v[114:115] op_sel_hi:[0,1]
	v_pk_mul_f32 v[82:83], v[98:99], v[86:87] op_sel_hi:[0,1]
	v_pk_mul_f32 v[76:77], v[98:99], v[112:113] op_sel_hi:[0,1]
	v_pk_mul_f32 v[78:79], v[98:99], v[84:85] op_sel_hi:[0,1]
	v_pk_fma_f32 v[78:79], v[64:65], v[78:79], v[22:23]
	v_pk_fma_f32 v[76:77], v[66:67], v[76:77], v[20:21]
	v_pk_fma_f32 v[82:83], v[60:61], v[82:83], v[18:19]
	v_pk_fma_f32 v[80:81], v[62:63], v[80:81], v[16:17]
	v_cvt_pk_bf16_f32 v76, v76, v77
	v_cvt_pk_bf16_f32 v77, v78, v79
	v_cvt_pk_bf16_f32 v78, v80, v81
	v_cvt_pk_bf16_f32 v79, v82, v83
	global_store_dwordx4 v[96:97], v[76:79], off offset:2048
	v_pk_mul_f32 v[80:81], v[94:95], v[98:99] op_sel_hi:[1,0]
	v_pk_mul_f32 v[82:83], v[90:91], v[98:99] op_sel_hi:[1,0]
	v_pk_mul_f32 v[76:77], v[92:93], v[98:99] op_sel_hi:[1,0]
	v_pk_mul_f32 v[78:79], v[88:89], v[98:99] op_sel_hi:[1,0]
	v_pk_fma_f32 v[76:77], v[74:75], v[76:77], v[28:29]
	v_pk_fma_f32 v[78:79], v[72:73], v[78:79], v[30:31]
	v_pk_fma_f32 v[82:83], v[68:69], v[82:83], v[26:27]
	v_pk_fma_f32 v[80:81], v[70:71], v[80:81], v[24:25]
	v_cvt_pk_bf16_f32 v76, v76, v77
	v_cvt_pk_bf16_f32 v77, v78, v79
	v_cvt_pk_bf16_f32 v78, v80, v81
	v_cvt_pk_bf16_f32 v79, v82, v83
	global_store_dwordx4 v[96:97], v[76:79], off offset:3072
	v_lshl_add_u64 v[88:89], v[32:33], 0, s[60:61]
	global_load_dwordx4 v[76:79], v[88:89], off
	global_load_dwordx4 v[80:83], v[88:89], off offset:1024
	global_load_dwordx4 v[84:87], v[88:89], off offset:2048
	s_nop 0
	global_load_dwordx4 v[88:91], v[88:89], off offset:3072
	s_waitcnt vmcnt(3)
	v_lshlrev_b32_e32 v97, 16, v77
	v_lshlrev_b32_e32 v96, 16, v76
	v_and_b32_e32 v77, 0xffff0000, v77
	v_and_b32_e32 v76, 0xffff0000, v76
	v_lshlrev_b32_e32 v101, 16, v79
	v_lshlrev_b32_e32 v100, 16, v78
	v_and_b32_e32 v79, 0xffff0000, v79
	v_and_b32_e32 v78, 0xffff0000, v78
	v_pk_mul_f32 v[98:99], v[76:77], v[76:77]
	v_pk_mul_f32 v[102:103], v[78:79], v[78:79]
	s_waitcnt vmcnt(0)
	v_lshlrev_b32_e32 v92, 16, v88
	v_and_b32_e32 v93, 0xffff0000, v88
	v_pk_fma_f32 v[98:99], v[96:97], v[96:97], v[98:99]
	v_pk_fma_f32 v[102:103], v[100:101], v[100:101], v[102:103]
	v_lshlrev_b32_e32 v105, 16, v81
	v_lshlrev_b32_e32 v104, 16, v80
	v_and_b32_e32 v81, 0xffff0000, v81
	v_and_b32_e32 v80, 0xffff0000, v80
	v_lshlrev_b32_e32 v109, 16, v83
	v_lshlrev_b32_e32 v108, 16, v82
	v_and_b32_e32 v83, 0xffff0000, v83
	v_and_b32_e32 v82, 0xffff0000, v82
	v_pk_mul_f32 v[106:107], v[80:81], v[80:81]
	v_pk_mul_f32 v[110:111], v[82:83], v[82:83]
	v_mul_f32_e32 v116, v92, v92
	v_mul_f32_e32 v117, v93, v93
	v_pk_add_f32 v[98:99], v[98:99], v[98:99] op_sel:[0,1] op_sel_hi:[1,0]
	v_pk_add_f32 v[102:103], v[102:103], v[102:103] op_sel:[0,1] op_sel_hi:[1,0]
	v_lshlrev_b32_e32 v88, 16, v89
	v_and_b32_e32 v89, 0xffff0000, v89
	v_pk_fma_f32 v[106:107], v[104:105], v[104:105], v[106:107]
	v_pk_fma_f32 v[110:111], v[108:109], v[108:109], v[110:111]
	v_mov_b32_e32 v99, v116
	v_mov_b32_e32 v103, v117
	v_mul_f32_e32 v118, v88, v88
	v_mul_f32_e32 v119, v89, v89
	v_pk_add_f32 v[98:99], v[98:99], v[102:103]
	v_pk_add_f32 v[102:103], v[106:107], v[106:107] op_sel:[0,1] op_sel_hi:[1,0]
	v_pk_add_f32 v[106:107], v[110:111], v[110:111] op_sel:[0,1] op_sel_hi:[1,0]
	v_mov_b32_e32 v103, v118
	v_mov_b32_e32 v107, v119
	v_lshlrev_b32_e32 v112, 16, v84
	v_and_b32_e32 v113, 0xffff0000, v84
	v_lshlrev_b32_e32 v84, 16, v85
	v_and_b32_e32 v85, 0xffff0000, v85
	v_pk_add_f32 v[102:103], v[102:103], v[106:107]
	v_lshlrev_b32_e32 v94, 16, v90
	v_and_b32_e32 v95, 0xffff0000, v90
	v_pk_add_f32 v[98:99], v[98:99], v[102:103]
	v_mul_f32_e32 v102, v113, v113
	v_mul_f32_e32 v106, v85, v85
	v_mul_f32_e32 v120, v94, v94
	v_mul_f32_e32 v121, v95, v95
	v_pk_fma_f32 v[102:103], v[112:113], v[112:113], v[102:103] op_sel_hi:[1,1,0]
	v_pk_fma_f32 v[106:107], v[84:85], v[84:85], v[106:107] op_sel_hi:[1,1,0]
	v_lshlrev_b32_e32 v114, 16, v86
	v_and_b32_e32 v115, 0xffff0000, v86
	v_lshlrev_b32_e32 v86, 16, v87
	v_and_b32_e32 v87, 0xffff0000, v87
	v_mov_b32_e32 v103, v120
	v_mov_b32_e32 v107, v121
	v_lshlrev_b32_e32 v90, 16, v91
	v_and_b32_e32 v91, 0xffff0000, v91
	v_pk_add_f32 v[102:103], v[102:103], v[106:107]
	v_mul_f32_e32 v106, v115, v115
	v_mul_f32_e32 v110, v87, v87
	v_mul_f32_e32 v122, v90, v90
	v_mul_f32_e32 v123, v91, v91
	v_pk_fma_f32 v[106:107], v[114:115], v[114:115], v[106:107] op_sel_hi:[1,1,0]
	v_pk_fma_f32 v[110:111], v[86:87], v[86:87], v[110:111] op_sel_hi:[1,1,0]
	v_mov_b32_e32 v107, v122
	v_mov_b32_e32 v111, v123
	v_pk_add_f32 v[106:107], v[106:107], v[110:111]
	s_nop 0
	v_pk_add_f32 v[102:103], v[102:103], v[106:107]
	s_nop 0
	v_pk_add_f32 v[98:99], v[98:99], v[102:103]
	s_nop 0
	v_add_f32_e32 v98, v98, v99
	v_mbcnt_lo_u32_b32 v99, -1, 0
	v_mbcnt_hi_u32_b32 v99, -1, v99
	s_nop 0
	v_lshlrev_b32_e32 v99, 2, v99
	v_xor_b32_e32 v99, 4, v99
	ds_bpermute_b32 v99, v99, v98
	s_waitcnt lgkmcnt(0)
; __device__ __forceinline__ v4u pk8(f32x4 a, f32x4 b) { v4u w; w.x = pk2(a[0], a[1]); w.y = pk2(a[2], a[3]); w.z = pk2(b[0], b[1]); w.w = pk2(b[2], b[3]); return w; }
; __device__ __forceinline__ float ssq8(const f32x4& a, const f32x4& b) { return ((a[0] * a[0] + a[1] * a[1]) + (a[2] * a[2] + a[3] * a[3])) + ((b[0] * b[0] + b[1] * b[1]) + (b[2] * b[2] + b[3] * b[3])); }
; __device__ __forceinline__ float shfl_xor_f(float v, int o) {
;     int l; asm volatile("v_mbcnt_lo_u32_b32 %0, -1, 0\n\tv_mbcnt_hi_u32_b32 %0, -1, %0" : "=v"(l));
;     return __builtin_bit_cast(float, __builtin_amdgcn_ds_bpermute((l ^ o) << 2, __builtin_bit_cast(int, v)));
; }
; __device__ __forceinline__ float wave_sum(float v) {
; #pragma unroll
;     for (int o = 1; o < 64; o <<= 1) v += shfl_xor_f(v, o);
; template <int XF32> __device__ __forceinline__ void norm_mod_phase(const void* x, const float* modl, int ch_shift, int ch_scale, bf16* H, int gw, int NGW, int lane) {
;     ...
;         for (int rr = 0; rr < 8; ++rr) {
;             const unsigned char* xr = (const unsigned char*)x + (size_t)(r0 + rr) * rowb; f32x4 v[4][2]; float s = 0.f;
; #pragma unroll
;             for (int j = 0; j < 4; ++j) ld_row8<XF32>(xr, lane, j, v[j][0], v[j][1]);
; #pragma unroll
;             for (int j = 0; j < 4; ++j) s += ssq8(v[j][0], v[j][1]);
;             const float rstd = 1.f / sqrtf(wave_sum(s) * (1.f / DM) + EPS);
;             v4u* o = (v4u*)(H + (size_t)(r0 + rr) * DM);
; #pragma unroll
;             for (int j = 0; j < 4; ++j) o[lane + 64 * j] = pk8(v[j][0] * rstd * sc[j][0] + sh[j][0], v[j][1] * rstd * sc[j][1] + sh[j][1]);
	v_add_f32_e32 v98, v98, v99
	v_mbcnt_lo_u32_b32 v99, -1, 0
	v_mbcnt_hi_u32_b32 v99, -1, v99
	s_nop 0
	v_lshlrev_b32_e32 v99, 2, v99
	v_xor_b32_e32 v99, 8, v99
	ds_bpermute_b32 v99, v99, v98
	s_waitcnt lgkmcnt(0)
	v_add_f32_e32 v98, v98, v99
	v_mbcnt_lo_u32_b32 v99, -1, 0
	v_mbcnt_hi_u32_b32 v99, -1, v99
	s_nop 0
	v_lshlrev_b32_e32 v99, 2, v99
	v_xor_b32_e32 v99, 16, v99
	ds_bpermute_b32 v99, v99, v98
	s_waitcnt lgkmcnt(0)
	v_add_f32_e32 v98, v98, v99
	v_mbcnt_lo_u32_b32 v99, -1, 0
	v_mbcnt_hi_u32_b32 v99, -1, v99
	s_nop 0
	v_lshlrev_b32_e32 v99, 2, v99
	v_xor_b32_e32 v99, 32, v99
	ds_bpermute_b32 v99, v99, v98
	s_waitcnt lgkmcnt(0)
	v_add_f32_e32 v98, v98, v99
	v_mbcnt_lo_u32_b32 v99, -1, 0
	v_mbcnt_hi_u32_b32 v99, -1, v99
	s_nop 0
	v_lshlrev_b32_e32 v99, 2, v99
	v_xor_b32_e32 v99, 64, v99
	ds_bpermute_b32 v99, v99, v98
	s_waitcnt lgkmcnt(0)
	v_add_f32_e32 v98, v98, v99
	v_mbcnt_lo_u32_b32 v99, -1, 0
	v_mbcnt_hi_u32_b32 v99, -1, v99
	s_nop 0
	v_lshlrev_b32_e32 v99, 2, v99
	v_xor_b32_e32 v99, 0x80, v99
	ds_bpermute_b32 v99, v99, v98
	s_waitcnt lgkmcnt(0)
	v_add_f32_e32 v98, v98, v99
	v_fmamk_f32 v98, v98, 0x3a000000, v224
	v_cmp_gt_f32_e32 vcc, s41, v98
	v_mul_f32_e32 v99, 0x4f800000, v98
	s_nop 0
	v_cndmask_b32_e32 v98, v98, v99, vcc
	v_sqrt_f32_e32 v99, v98
	s_nop 0
	v_add_u32_e32 v102, -1, v99
	v_fma_f32 v103, -v102, v99, v98
	v_cmp_ge_f32_e64 s[0:1], 0, v103
	v_add_u32_e32 v103, 1, v99
	s_nop 0
	v_cndmask_b32_e64 v102, v99, v102, s[0:1]
	v_fma_f32 v99, -v103, v99, v98
	v_cmp_lt_f32_e64 s[0:1], 0, v99
	s_nop 1
	v_cndmask_b32_e64 v99, v102, v103, s[0:1]
	v_mul_f32_e32 v102, 0x37800000, v99
	v_cndmask_b32_e32 v99, v99, v102, vcc
	v_cmp_class_f32_e32 vcc, v98, v225
	s_nop 1
	v_cndmask_b32_e32 v98, v99, v98, vcc
	v_div_scale_f32 v99, s[0:1], v98, v98, 1.0
	v_rcp_f32_e32 v102, v99
	s_nop 0
	v_fma_f32 v103, -v99, v102, 1.0
	v_fmac_f32_e32 v102, v103, v102
	v_div_scale_f32 v103, vcc, 1.0, v98, 1.0
	v_mul_f32_e32 v106, v103, v102
	v_fma_f32 v107, -v99, v106, v103
	v_fmac_f32_e32 v106, v107, v102
	v_fma_f32 v99, -v99, v106, v103
	v_div_fmas_f32 v99, v99, v102, v106
	v_div_fixup_f32 v98, v99, v98, 1.0
	v_mov_b32_e32 v102, v96
	v_mov_b32_e32 v103, v76
	v_mov_b32_e32 v76, v97
	v_pk_mul_f32 v[102:103], v[98:99], v[102:103] op_sel_hi:[0,1]
	v_pk_mul_f32 v[76:77], v[98:99], v[76:77] op_sel_hi:[0,1]
	v_pk_fma_f32 v[96:97], v[48:49], v[76:77], v[6:7]
	v_pk_fma_f32 v[76:77], v[50:51], v[102:103], v[4:5]
	v_mov_b32_e32 v102, v100
	v_mov_b32_e32 v103, v78
	v_mov_b32_e32 v78, v101
	v_pk_mul_f32 v[102:103], v[98:99], v[102:103] op_sel_hi:[0,1]
	v_pk_mul_f32 v[78:79], v[98:99], v[78:79] op_sel_hi:[0,1]
	v_pk_fma_f32 v[100:101], v[44:45], v[78:79], v[2:3]
	v_pk_fma_f32 v[78:79], v[46:47], v[102:103], v[0:1]
	v_cvt_pk_bf16_f32 v76, v76, v77
	v_cvt_pk_bf16_f32 v77, v96, v97
	v_cvt_pk_bf16_f32 v78, v78, v79
	v_cvt_pk_bf16_f32 v79, v100, v101
	v_lshl_add_u64 v[96:97], v[34:35], 0, s[60:61]
	global_store_dwordx4 v[96:97], v[76:79], off
	s_lshl_b64 s[60:61], s[4:5], 12
	s_add_i32 s4, s4, s10
	v_mov_b32_e32 v77, v80
	v_mov_b32_e32 v80, v105
	v_mov_b32_e32 v76, v104
	v_pk_mul_f32 v[78:79], v[98:99], v[80:81] op_sel_hi:[0,1]
	v_mov_b32_e32 v80, v108
	v_mov_b32_e32 v81, v82
	v_mov_b32_e32 v82, v109
	v_pk_mul_f32 v[76:77], v[98:99], v[76:77] op_sel_hi:[0,1]
	v_pk_mul_f32 v[80:81], v[98:99], v[80:81] op_sel_hi:[0,1]
	v_pk_mul_f32 v[82:83], v[98:99], v[82:83] op_sel_hi:[0,1]
	v_pk_fma_f32 v[78:79], v[56:57], v[78:79], v[14:15]
	v_pk_fma_f32 v[76:77], v[58:59], v[76:77], v[12:13]
	v_pk_fma_f32 v[82:83], v[52:53], v[82:83], v[10:11]
	v_pk_fma_f32 v[80:81], v[54:55], v[80:81], v[8:9]
	v_cvt_pk_bf16_f32 v76, v76, v77
	v_cvt_pk_bf16_f32 v77, v78, v79
	v_cvt_pk_bf16_f32 v78, v80, v81
	v_cvt_pk_bf16_f32 v79, v82, v83
	global_store_dwordx4 v[96:97], v[76:79], off offset:1024
	v_pk_mul_f32 v[80:81], v[98:99], v[114:115] op_sel_hi:[0,1]
	v_pk_mul_f32 v[82:83], v[98:99], v[86:87] op_sel_hi:[0,1]
	v_pk_mul_f32 v[76:77], v[98:99], v[112:113] op_sel_hi:[0,1]
	v_pk_mul_f32 v[78:79], v[98:99], v[84:85] op_sel_hi:[0,1]
	v_pk_fma_f32 v[78:79], v[64:65], v[78:79], v[22:23]
	v_pk_fma_f32 v[76:77], v[66:67], v[76:77], v[20:21]
	v_pk_fma_f32 v[82:83], v[60:61], v[82:83], v[18:19]
	v_pk_fma_f32 v[80:81], v[62:63], v[80:81], v[16:17]
	v_cvt_pk_bf16_f32 v76, v76, v77
	v_cvt_pk_bf16_f32 v77, v78, v79
	v_cvt_pk_bf16_f32 v78, v80, v81
	v_cvt_pk_bf16_f32 v79, v82, v83
	global_store_dwordx4 v[96:97], v[76:79], off offset:2048
	v_pk_mul_f32 v[80:81], v[94:95], v[98:99] op_sel_hi:[1,0]
	v_pk_mul_f32 v[82:83], v[90:91], v[98:99] op_sel_hi:[1,0]
	v_pk_mul_f32 v[76:77], v[92:93], v[98:99] op_sel_hi:[1,0]
	v_pk_mul_f32 v[78:79], v[88:89], v[98:99] op_sel_hi:[1,0]
	v_pk_fma_f32 v[76:77], v[74:75], v[76:77], v[28:29]
	v_pk_fma_f32 v[78:79], v[72:73], v[78:79], v[30:31]
	v_pk_fma_f32 v[82:83], v[68:69], v[82:83], v[26:27]
	v_pk_fma_f32 v[80:81], v[70:71], v[80:81], v[24:25]
	v_cvt_pk_bf16_f32 v76, v76, v77
	v_cvt_pk_bf16_f32 v77, v78, v79
	v_cvt_pk_bf16_f32 v78, v80, v81
	v_cvt_pk_bf16_f32 v79, v82, v83
	global_store_dwordx4 v[96:97], v[76:79], off offset:3072
	v_lshl_add_u64 v[88:89], v[32:33], 0, s[60:61]
	global_load_dwordx4 v[76:79], v[88:89], off
	global_load_dwordx4 v[80:83], v[88:89], off offset:1024
	global_load_dwordx4 v[84:87], v[88:89], off offset:2048
	s_nop 0
	global_load_dwordx4 v[88:91], v[88:89], off offset:3072
	s_cmpk_lt_i32 s56, 0x800
	s_waitcnt vmcnt(3)
	v_lshlrev_b32_e32 v97, 16, v77
	v_lshlrev_b32_e32 v96, 16, v76
	v_and_b32_e32 v77, 0xffff0000, v77
	v_and_b32_e32 v76, 0xffff0000, v76
	v_lshlrev_b32_e32 v101, 16, v79
	v_lshlrev_b32_e32 v100, 16, v78
	v_and_b32_e32 v79, 0xffff0000, v79
	v_and_b32_e32 v78, 0xffff0000, v78
	v_pk_mul_f32 v[98:99], v[76:77], v[76:77]
	v_pk_mul_f32 v[102:103], v[78:79], v[78:79]
	s_waitcnt vmcnt(0)
; __device__ __forceinline__ float ssq8(const f32x4& a, const f32x4& b) { return ((a[0] * a[0] + a[1] * a[1]) + (a[2] * a[2] + a[3] * a[3])) + ((b[0] * b[0] + b[1] * b[1]) + (b[2] * b[2] + b[3] * b[3])); }
; __device__ __forceinline__ float shfl_xor_f(float v, int o) {
;     int l; asm volatile("v_mbcnt_lo_u32_b32 %0, -1, 0\n\tv_mbcnt_hi_u32_b32 %0, -1, %0" : "=v"(l));
;     return __builtin_bit_cast(float, __builtin_amdgcn_ds_bpermute((l ^ o) << 2, __builtin_bit_cast(int, v)));
; }
; __device__ __forceinline__ float wave_sum(float v) {
; #pragma unroll
;     for (int o = 1; o < 64; o <<= 1) v += shfl_xor_f(v, o);
; template <int XF32> __device__ __forceinline__ void norm_mod_phase(const void* x, const float* modl, int ch_shift, int ch_scale, bf16* H, int gw, int NGW, int lane) {
;     ...
;         for (int rr = 0; rr < 8; ++rr) {
;             const unsigned char* xr = (const unsigned char*)x + (size_t)(r0 + rr) * rowb; f32x4 v[4][2]; float s = 0.f;
; #pragma unroll
;             for (int j = 0; j < 4; ++j) ld_row8<XF32>(xr, lane, j, v[j][0], v[j][1]);
; #pragma unroll
;             for (int j = 0; j < 4; ++j) s += ssq8(v[j][0], v[j][1]);
	v_lshlrev_b32_e32 v92, 16, v88
	v_and_b32_e32 v93, 0xffff0000, v88
	v_pk_fma_f32 v[98:99], v[96:97], v[96:97], v[98:99]
	v_pk_fma_f32 v[102:103], v[100:101], v[100:101], v[102:103]
	v_lshlrev_b32_e32 v105, 16, v81
	v_lshlrev_b32_e32 v104, 16, v80
	v_and_b32_e32 v81, 0xffff0000, v81
	v_and_b32_e32 v80, 0xffff0000, v80
	v_lshlrev_b32_e32 v109, 16, v83
	v_lshlrev_b32_e32 v108, 16, v82
	v_and_b32_e32 v83, 0xffff0000, v83
	v_and_b32_e32 v82, 0xffff0000, v82
	v_pk_mul_f32 v[106:107], v[80:81], v[80:81]
	v_pk_mul_f32 v[110:111], v[82:83], v[82:83]
	v_mul_f32_e32 v116, v92, v92
	v_mul_f32_e32 v117, v93, v93
	v_pk_add_f32 v[98:99], v[98:99], v[98:99] op_sel:[0,1] op_sel_hi:[1,0]
	v_pk_add_f32 v[102:103], v[102:103], v[102:103] op_sel:[0,1] op_sel_hi:[1,0]
	v_lshlrev_b32_e32 v88, 16, v89
	v_and_b32_e32 v89, 0xffff0000, v89
	v_pk_fma_f32 v[106:107], v[104:105], v[104:105], v[106:107]
	v_pk_fma_f32 v[110:111], v[108:109], v[108:109], v[110:111]
	v_mov_b32_e32 v99, v116
	v_mov_b32_e32 v103, v117
	v_mul_f32_e32 v118, v88, v88
	v_mul_f32_e32 v119, v89, v89
	v_pk_add_f32 v[98:99], v[98:99], v[102:103]
	v_pk_add_f32 v[102:103], v[106:107], v[106:107] op_sel:[0,1] op_sel_hi:[1,0]
	v_pk_add_f32 v[106:107], v[110:111], v[110:111] op_sel:[0,1] op_sel_hi:[1,0]
	v_mov_b32_e32 v103, v118
	v_mov_b32_e32 v107, v119
	v_lshlrev_b32_e32 v112, 16, v84
	v_and_b32_e32 v113, 0xffff0000, v84
	v_lshlrev_b32_e32 v84, 16, v85
	v_and_b32_e32 v85, 0xffff0000, v85
	v_pk_add_f32 v[102:103], v[102:103], v[106:107]
	v_lshlrev_b32_e32 v94, 16, v90
	v_and_b32_e32 v95, 0xffff0000, v90
	v_pk_add_f32 v[98:99], v[98:99], v[102:103]
	v_mul_f32_e32 v102, v113, v113
	v_mul_f32_e32 v106, v85, v85
	v_mul_f32_e32 v120, v94, v94
	v_mul_f32_e32 v121, v95, v95
	v_pk_fma_f32 v[102:103], v[112:113], v[112:113], v[102:103] op_sel_hi:[1,1,0]
	v_pk_fma_f32 v[106:107], v[84:85], v[84:85], v[106:107] op_sel_hi:[1,1,0]
	v_lshlrev_b32_e32 v114, 16, v86
	v_and_b32_e32 v115, 0xffff0000, v86
	v_lshlrev_b32_e32 v86, 16, v87
	v_and_b32_e32 v87, 0xffff0000, v87
	v_mov_b32_e32 v103, v120
	v_mov_b32_e32 v107, v121
	v_lshlrev_b32_e32 v90, 16, v91
	v_and_b32_e32 v91, 0xffff0000, v91
	v_pk_add_f32 v[102:103], v[102:103], v[106:107]
	v_mul_f32_e32 v106, v115, v115
	v_mul_f32_e32 v110, v87, v87
	v_mul_f32_e32 v122, v90, v90
	v_mul_f32_e32 v123, v91, v91
	v_pk_fma_f32 v[106:107], v[114:115], v[114:115], v[106:107] op_sel_hi:[1,1,0]
	v_pk_fma_f32 v[110:111], v[86:87], v[86:87], v[110:111] op_sel_hi:[1,1,0]
	v_mov_b32_e32 v107, v122
	v_mov_b32_e32 v111, v123
	v_pk_add_f32 v[106:107], v[106:107], v[110:111]
	s_nop 0
	v_pk_add_f32 v[102:103], v[102:103], v[106:107]
	s_nop 0
	v_pk_add_f32 v[98:99], v[98:99], v[102:103]
	s_nop 0
	v_add_f32_e32 v98, v98, v99
	v_mbcnt_lo_u32_b32 v99, -1, 0
	v_mbcnt_hi_u32_b32 v99, -1, v99
	s_nop 0
	v_lshlrev_b32_e32 v99, 2, v99
	v_xor_b32_e32 v99, 4, v99
	ds_bpermute_b32 v99, v99, v98
	s_waitcnt lgkmcnt(0)
	v_add_f32_e32 v98, v98, v99
	v_mbcnt_lo_u32_b32 v99, -1, 0
	v_mbcnt_hi_u32_b32 v99, -1, v99
	s_nop 0
	v_lshlrev_b32_e32 v99, 2, v99
	v_xor_b32_e32 v99, 8, v99
	ds_bpermute_b32 v99, v99, v98
	s_waitcnt lgkmcnt(0)
	v_add_f32_e32 v98, v98, v99
	v_mbcnt_lo_u32_b32 v99, -1, 0
	v_mbcnt_hi_u32_b32 v99, -1, v99
	s_nop 0
	v_lshlrev_b32_e32 v99, 2, v99
	v_xor_b32_e32 v99, 16, v99
	ds_bpermute_b32 v99, v99, v98
	s_waitcnt lgkmcnt(0)
	v_add_f32_e32 v98, v98, v99
	v_mbcnt_lo_u32_b32 v99, -1, 0
	v_mbcnt_hi_u32_b32 v99, -1, v99
	s_nop 0
	v_lshlrev_b32_e32 v99, 2, v99
	v_xor_b32_e32 v99, 32, v99
	ds_bpermute_b32 v99, v99, v98
	s_waitcnt lgkmcnt(0)
	v_add_f32_e32 v98, v98, v99
	v_mbcnt_lo_u32_b32 v99, -1, 0
	v_mbcnt_hi_u32_b32 v99, -1, v99
	s_nop 0
	v_lshlrev_b32_e32 v99, 2, v99
	v_xor_b32_e32 v99, 64, v99
	ds_bpermute_b32 v99, v99, v98
	s_waitcnt lgkmcnt(0)
	v_add_f32_e32 v98, v98, v99
	v_mbcnt_lo_u32_b32 v99, -1, 0
	v_mbcnt_hi_u32_b32 v99, -1, v99
	s_nop 0
	v_lshlrev_b32_e32 v99, 2, v99
	v_xor_b32_e32 v99, 0x80, v99
	ds_bpermute_b32 v99, v99, v98
	s_waitcnt lgkmcnt(0)
; __device__ __forceinline__ v4u pk8(f32x4 a, f32x4 b) { v4u w; w.x = pk2(a[0], a[1]); w.y = pk2(a[2], a[3]); w.z = pk2(b[0], b[1]); w.w = pk2(b[2], b[3]); return w; }
; template <int XF32> __device__ __forceinline__ void norm_mod_phase(const void* x, const float* modl, int ch_shift, int ch_scale, bf16* H, int gw, int NGW, int lane) {
;     ...
;     for (int blk = gw; blk < M / 8; blk += NGW) {
;     ...
;             const float rstd = 1.f / sqrtf(wave_sum(s) * (1.f / DM) + EPS);
;             v4u* o = (v4u*)(H + (size_t)(r0 + rr) * DM);
; #pragma unroll
;             for (int j = 0; j < 4; ++j) o[lane + 64 * j] = pk8(v[j][0] * rstd * sc[j][0] + sh[j][0], v[j][1] * rstd * sc[j][1] + sh[j][1]);
;         }
	v_add_f32_e32 v98, v98, v99
	v_fmamk_f32 v98, v98, 0x3a000000, v224
	v_cmp_gt_f32_e32 vcc, s41, v98
	v_mul_f32_e32 v99, 0x4f800000, v98
	s_nop 0
	v_cndmask_b32_e32 v98, v98, v99, vcc
	v_sqrt_f32_e32 v99, v98
	s_nop 0
	v_add_u32_e32 v102, -1, v99
	v_fma_f32 v103, -v102, v99, v98
	v_cmp_ge_f32_e64 s[0:1], 0, v103
	v_add_u32_e32 v103, 1, v99
	s_nop 0
	v_cndmask_b32_e64 v102, v99, v102, s[0:1]
	v_fma_f32 v99, -v103, v99, v98
	v_cmp_lt_f32_e64 s[0:1], 0, v99
	s_nop 1
	v_cndmask_b32_e64 v99, v102, v103, s[0:1]
	v_mul_f32_e32 v102, 0x37800000, v99
	v_cndmask_b32_e32 v99, v99, v102, vcc
	v_cmp_class_f32_e32 vcc, v98, v225
	s_nop 1
	v_cndmask_b32_e32 v98, v99, v98, vcc
	v_div_scale_f32 v99, s[0:1], v98, v98, 1.0
	v_rcp_f32_e32 v102, v99
	s_nop 0
	v_fma_f32 v103, -v99, v102, 1.0
	v_fmac_f32_e32 v102, v103, v102
	v_div_scale_f32 v103, vcc, 1.0, v98, 1.0
	v_mul_f32_e32 v106, v103, v102
	v_fma_f32 v107, -v99, v106, v103
	v_fmac_f32_e32 v106, v107, v102
	v_fma_f32 v99, -v99, v106, v103
	v_div_fmas_f32 v99, v99, v102, v106
	v_div_fixup_f32 v98, v99, v98, 1.0
	v_mov_b32_e32 v103, v76
	v_mov_b32_e32 v76, v97
	v_mov_b32_e32 v102, v96
	v_pk_mul_f32 v[76:77], v[98:99], v[76:77] op_sel_hi:[0,1]
	v_pk_mul_f32 v[102:103], v[98:99], v[102:103] op_sel_hi:[0,1]
	v_pk_fma_f32 v[6:7], v[48:49], v[76:77], v[6:7]
	v_mov_b32_e32 v48, v100
	v_mov_b32_e32 v49, v78
	v_mov_b32_e32 v78, v101
	v_pk_fma_f32 v[4:5], v[50:51], v[102:103], v[4:5]
	v_pk_mul_f32 v[48:49], v[98:99], v[48:49] op_sel_hi:[0,1]
	v_pk_mul_f32 v[50:51], v[98:99], v[78:79] op_sel_hi:[0,1]
	v_pk_fma_f32 v[44:45], v[44:45], v[50:51], v[2:3]
	v_pk_fma_f32 v[2:3], v[46:47], v[48:49], v[0:1]
	v_cvt_pk_bf16_f32 v0, v4, v5
	v_cvt_pk_bf16_f32 v1, v6, v7
	v_cvt_pk_bf16_f32 v2, v2, v3
	v_cvt_pk_bf16_f32 v3, v44, v45
	v_lshl_add_u64 v[4:5], v[34:35], 0, s[60:61]
	global_store_dwordx4 v[4:5], v[0:3], off
	v_mov_b32_e32 v6, v108
	v_mov_b32_e32 v7, v82
	v_mov_b32_e32 v0, v104
	v_mov_b32_e32 v1, v80
	v_pk_mul_f32 v[0:1], v[98:99], v[0:1] op_sel_hi:[0,1]
	v_mov_b32_e32 v80, v105
	v_mov_b32_e32 v82, v109
	v_pk_mul_f32 v[2:3], v[98:99], v[80:81] op_sel_hi:[0,1]
	v_pk_fma_f32 v[0:1], v[58:59], v[0:1], v[12:13]
	v_pk_mul_f32 v[6:7], v[98:99], v[6:7] op_sel_hi:[0,1]
	v_pk_mul_f32 v[12:13], v[98:99], v[82:83] op_sel_hi:[0,1]
	v_pk_fma_f32 v[2:3], v[56:57], v[2:3], v[14:15]
	v_pk_fma_f32 v[10:11], v[52:53], v[12:13], v[10:11]
	v_pk_fma_f32 v[6:7], v[54:55], v[6:7], v[8:9]
	v_cvt_pk_bf16_f32 v0, v0, v1
	v_cvt_pk_bf16_f32 v1, v2, v3
	v_cvt_pk_bf16_f32 v2, v6, v7
	v_cvt_pk_bf16_f32 v3, v10, v11
	global_store_dwordx4 v[4:5], v[0:3], off offset:1024
	v_pk_mul_f32 v[6:7], v[98:99], v[114:115] op_sel_hi:[0,1]
	v_pk_mul_f32 v[8:9], v[98:99], v[86:87] op_sel_hi:[0,1]
	v_pk_mul_f32 v[0:1], v[98:99], v[112:113] op_sel_hi:[0,1]
	v_pk_mul_f32 v[2:3], v[98:99], v[84:85] op_sel_hi:[0,1]
	v_pk_fma_f32 v[2:3], v[64:65], v[2:3], v[22:23]
	v_pk_fma_f32 v[0:1], v[66:67], v[0:1], v[20:21]
	v_pk_fma_f32 v[8:9], v[60:61], v[8:9], v[18:19]
	v_pk_fma_f32 v[6:7], v[62:63], v[6:7], v[16:17]
	v_cvt_pk_bf16_f32 v0, v0, v1
	v_cvt_pk_bf16_f32 v1, v2, v3
	v_cvt_pk_bf16_f32 v2, v6, v7
	v_cvt_pk_bf16_f32 v3, v8, v9
	global_store_dwordx4 v[4:5], v[0:3], off offset:2048
	v_pk_mul_f32 v[6:7], v[94:95], v[98:99] op_sel_hi:[1,0]
	v_pk_mul_f32 v[8:9], v[90:91], v[98:99] op_sel_hi:[1,0]
	v_pk_mul_f32 v[0:1], v[92:93], v[98:99] op_sel_hi:[1,0]
	v_pk_mul_f32 v[2:3], v[88:89], v[98:99] op_sel_hi:[1,0]
	v_pk_fma_f32 v[0:1], v[74:75], v[0:1], v[28:29]
	v_pk_fma_f32 v[2:3], v[72:73], v[2:3], v[30:31]
	v_pk_fma_f32 v[8:9], v[68:69], v[8:9], v[26:27]
	v_pk_fma_f32 v[6:7], v[70:71], v[6:7], v[24:25]
	v_cvt_pk_bf16_f32 v0, v0, v1
	v_cvt_pk_bf16_f32 v1, v2, v3
	v_cvt_pk_bf16_f32 v2, v6, v7
	v_cvt_pk_bf16_f32 v3, v8, v9
	global_store_dwordx4 v[4:5], v[0:3], off offset:3072
	s_cbranch_scc1 .LBB0_919
